# GEMM K-loops: A operand triple-buffered through 32 KiB of static LDS (160 KiB total), B double; per step issue B(t+1) then A(t+2), end-of-step wait vmcnt(4)
# speedup vs baseline: 1.0304x; 1.0120x over previous
.LBB0_113:
	v_add_u32_e32 v172, v153, v170
	v_add_u32_e32 v173, v153, v171
	v_add_u32_e32 v174, v169, v170
	v_add_u32_e32 v175, v169, v171
	s_mov_b64 s[100:101], 0x80
	v_lshl_add_u64 v[240:241], v[128:129], 0, s[100:101]
	s_mov_b64 s[100:101], 0x20080
	v_lshl_add_u64 v[242:243], v[128:129], 0, s[100:101]
	s_mov_b64 s[100:101], 0x40080
	v_lshl_add_u64 v[244:245], v[128:129], 0, s[100:101]
	s_mov_b64 s[100:101], 0x60080
	v_lshl_add_u64 v[246:247], v[128:129], 0, s[100:101]
	s_mov_b64 s[100:101], 0x80
	v_lshl_add_u64 v[138:139], v[130:131], 0, s[100:101]
	s_mov_b64 s[100:101], 0x20080
	v_lshl_add_u64 v[140:141], v[130:131], 0, s[100:101]
	s_mov_b64 s[100:101], 0x40080
	v_lshl_add_u64 v[250:251], v[130:131], 0, s[100:101]
	s_mov_b64 s[100:101], 0x60080
	v_lshl_add_u64 v[252:253], v[130:131], 0, s[100:101]
	v_readfirstlane_b32 s100, v145
	v_readfirstlane_b32 s101, v146
	v_add_u32_e32 v254, 0x20000, v172
	v_add_u32_e32 v255, 0x20000, v173
	s_nop 3
	ds_read_b128 v[176:179], v172 offset:0
	ds_read_b128 v[180:183], v172 offset:2048
	ds_read_b128 v[184:187], v172 offset:4096
	ds_read_b128 v[188:191], v172 offset:6144
	ds_read_b128 v[208:211], v174 offset:0
	ds_read_b128 v[212:215], v174 offset:2048
	ds_read_b128 v[216:219], v174 offset:4096
	ds_read_b128 v[220:223], v174 offset:6144
	s_add_u32 m0, s100, 0x8000
	s_nop 0
	global_load_lds_dwordx4 v[240:241], off
	v_lshl_add_u64 v[240:241], v[240:241], 0, s[34:35]
	s_add_u32 m0, s100, 0xa000
	s_nop 0
	global_load_lds_dwordx4 v[242:243], off
	v_lshl_add_u64 v[242:243], v[242:243], 0, s[34:35]
	s_add_u32 m0, s100, 0xc000
	s_nop 0
	global_load_lds_dwordx4 v[244:245], off
	v_lshl_add_u64 v[244:245], v[244:245], 0, s[34:35]
	s_add_u32 m0, s100, 0xe000
	s_nop 0
	global_load_lds_dwordx4 v[246:247], off
	v_lshl_add_u64 v[246:247], v[246:247], 0, s[34:35]
	s_add_u32 m0, s101, 0x8000
	s_nop 0
	global_load_lds_dwordx4 v[138:139], off
	v_lshl_add_u64 v[138:139], v[138:139], 0, s[34:35]
	s_add_u32 m0, s101, 0xa000
	s_nop 0
	global_load_lds_dwordx4 v[140:141], off
	v_lshl_add_u64 v[140:141], v[140:141], 0, s[34:35]
	s_add_u32 m0, s101, 0xc000
	s_nop 0
	global_load_lds_dwordx4 v[250:251], off
	v_lshl_add_u64 v[250:251], v[250:251], 0, s[34:35]
	s_add_u32 m0, s101, 0xe000
	s_nop 0
	global_load_lds_dwordx4 v[252:253], off
	v_lshl_add_u64 v[252:253], v[252:253], 0, s[34:35]
	s_waitcnt lgkmcnt(0)
	v_mfma_f32_16x16x32_bf16 v[120:123], v[208:211], v[176:179], v[120:123]
	ds_read_b128 v[224:227], v174 offset:8192
	v_mfma_f32_16x16x32_bf16 v[112:115], v[212:215], v[176:179], v[112:115]
	ds_read_b128 v[228:231], v174 offset:10240
	v_mfma_f32_16x16x32_bf16 v[124:127], v[216:219], v[176:179], v[124:127]
	ds_read_b128 v[232:235], v174 offset:12288
	v_mfma_f32_16x16x32_bf16 v[116:119], v[220:223], v[176:179], v[116:119]
	ds_read_b128 v[236:239], v174 offset:14336
	v_mfma_f32_16x16x32_bf16 v[88:91], v[208:211], v[180:183], v[88:91]
	s_add_u32 m0, s100, 0x20000
	v_mfma_f32_16x16x32_bf16 v[80:83], v[212:215], v[180:183], v[80:83]
	global_load_lds_dwordx4 v[240:241], off
	v_lshl_add_u64 v[240:241], v[240:241], 0, s[34:35]
	v_mfma_f32_16x16x32_bf16 v[92:95], v[216:219], v[180:183], v[92:95]
	s_add_u32 m0, s100, 0x22000
	v_mfma_f32_16x16x32_bf16 v[84:87], v[220:223], v[180:183], v[84:87]
	global_load_lds_dwordx4 v[242:243], off
	v_lshl_add_u64 v[242:243], v[242:243], 0, s[34:35]
	v_mfma_f32_16x16x32_bf16 v[56:59], v[208:211], v[184:187], v[56:59]
	s_add_u32 m0, s100, 0x24000
	v_mfma_f32_16x16x32_bf16 v[48:51], v[212:215], v[184:187], v[48:51]
	global_load_lds_dwordx4 v[244:245], off
	v_lshl_add_u64 v[244:245], v[244:245], 0, s[34:35]
	v_mfma_f32_16x16x32_bf16 v[60:63], v[216:219], v[184:187], v[60:63]
	s_add_u32 m0, s100, 0x26000
	v_mfma_f32_16x16x32_bf16 v[52:55], v[220:223], v[184:187], v[52:55]
	global_load_lds_dwordx4 v[246:247], off
	v_lshl_add_u64 v[246:247], v[246:247], 0, s[34:35]
	v_mfma_f32_16x16x32_bf16 v[24:27], v[208:211], v[188:191], v[24:27]
	v_mfma_f32_16x16x32_bf16 v[16:19], v[212:215], v[188:191], v[16:19]
	v_mfma_f32_16x16x32_bf16 v[28:31], v[216:219], v[188:191], v[28:31]
	v_mfma_f32_16x16x32_bf16 v[20:23], v[220:223], v[188:191], v[20:23]
	s_waitcnt lgkmcnt(0)
	v_mfma_f32_16x16x32_bf16 v[104:107], v[224:227], v[176:179], v[104:107]
	ds_read_b128 v[192:195], v173 offset:0
	v_mfma_f32_16x16x32_bf16 v[96:99], v[228:231], v[176:179], v[96:99]
	ds_read_b128 v[196:199], v173 offset:2048
	v_mfma_f32_16x16x32_bf16 v[108:111], v[232:235], v[176:179], v[108:111]
	ds_read_b128 v[200:203], v173 offset:4096
	v_mfma_f32_16x16x32_bf16 v[100:103], v[236:239], v[176:179], v[100:103]
	ds_read_b128 v[204:207], v173 offset:6144
	v_mfma_f32_16x16x32_bf16 v[72:75], v[224:227], v[180:183], v[72:75]
	ds_read_b128 v[208:211], v175 offset:0
	v_mfma_f32_16x16x32_bf16 v[64:67], v[228:231], v[180:183], v[64:67]
	ds_read_b128 v[212:215], v175 offset:2048
	v_mfma_f32_16x16x32_bf16 v[76:79], v[232:235], v[180:183], v[76:79]
	ds_read_b128 v[216:219], v175 offset:4096
	v_mfma_f32_16x16x32_bf16 v[68:71], v[236:239], v[180:183], v[68:71]
	ds_read_b128 v[220:223], v175 offset:6144
	v_mfma_f32_16x16x32_bf16 v[40:43], v[224:227], v[184:187], v[40:43]
	v_mfma_f32_16x16x32_bf16 v[32:35], v[228:231], v[184:187], v[32:35]
	v_mfma_f32_16x16x32_bf16 v[44:47], v[232:235], v[184:187], v[44:47]
	v_mfma_f32_16x16x32_bf16 v[36:39], v[236:239], v[184:187], v[36:39]
	v_mfma_f32_16x16x32_bf16 v[8:11], v[224:227], v[188:191], v[8:11]
	v_mfma_f32_16x16x32_bf16 v[0:3], v[228:231], v[188:191], v[0:3]
	v_mfma_f32_16x16x32_bf16 v[12:15], v[232:235], v[188:191], v[12:15]
	v_mfma_f32_16x16x32_bf16 v[4:7], v[236:239], v[188:191], v[4:7]
	s_waitcnt lgkmcnt(0)
	v_mfma_f32_16x16x32_bf16 v[120:123], v[208:211], v[192:195], v[120:123]
	ds_read_b128 v[224:227], v175 offset:8192
	v_mfma_f32_16x16x32_bf16 v[112:115], v[212:215], v[192:195], v[112:115]
	ds_read_b128 v[228:231], v175 offset:10240
	v_mfma_f32_16x16x32_bf16 v[124:127], v[216:219], v[192:195], v[124:127]
	ds_read_b128 v[232:235], v175 offset:12288
	v_mfma_f32_16x16x32_bf16 v[116:119], v[220:223], v[192:195], v[116:119]
	ds_read_b128 v[236:239], v175 offset:14336
	v_mfma_f32_16x16x32_bf16 v[88:91], v[208:211], v[196:199], v[88:91]
	v_mfma_f32_16x16x32_bf16 v[80:83], v[212:215], v[196:199], v[80:83]
	v_mfma_f32_16x16x32_bf16 v[92:95], v[216:219], v[196:199], v[92:95]
	v_mfma_f32_16x16x32_bf16 v[84:87], v[220:223], v[196:199], v[84:87]
	v_mfma_f32_16x16x32_bf16 v[56:59], v[208:211], v[200:203], v[56:59]
	v_mfma_f32_16x16x32_bf16 v[48:51], v[212:215], v[200:203], v[48:51]
	v_mfma_f32_16x16x32_bf16 v[60:63], v[216:219], v[200:203], v[60:63]
	v_mfma_f32_16x16x32_bf16 v[52:55], v[220:223], v[200:203], v[52:55]
	v_mfma_f32_16x16x32_bf16 v[24:27], v[208:211], v[204:207], v[24:27]
	v_mfma_f32_16x16x32_bf16 v[16:19], v[212:215], v[204:207], v[16:19]
	v_mfma_f32_16x16x32_bf16 v[28:31], v[216:219], v[204:207], v[28:31]
	v_mfma_f32_16x16x32_bf16 v[20:23], v[220:223], v[204:207], v[20:23]
	s_waitcnt lgkmcnt(0)
	s_waitcnt vmcnt(4)
	s_barrier
	s_mov_b32 s7, 2
.Lgemm_p2_loop:
	v_mfma_f32_16x16x32_bf16 v[104:107], v[224:227], v[192:195], v[104:107]
	ds_read_b128 v[176:179], v172 offset:32768
	v_mfma_f32_16x16x32_bf16 v[96:99], v[228:231], v[192:195], v[96:99]
	ds_read_b128 v[180:183], v172 offset:34816
	v_mfma_f32_16x16x32_bf16 v[108:111], v[232:235], v[192:195], v[108:111]
	ds_read_b128 v[184:187], v172 offset:36864
	v_mfma_f32_16x16x32_bf16 v[100:103], v[236:239], v[192:195], v[100:103]
	ds_read_b128 v[188:191], v172 offset:38912
	v_mfma_f32_16x16x32_bf16 v[72:75], v[224:227], v[196:199], v[72:75]
	ds_read_b128 v[208:211], v174 offset:32768
	v_mfma_f32_16x16x32_bf16 v[64:67], v[228:231], v[196:199], v[64:67]
	ds_read_b128 v[212:215], v174 offset:34816
	v_mfma_f32_16x16x32_bf16 v[76:79], v[232:235], v[196:199], v[76:79]
	ds_read_b128 v[216:219], v174 offset:36864
	v_mfma_f32_16x16x32_bf16 v[68:71], v[236:239], v[196:199], v[68:71]
	ds_read_b128 v[220:223], v174 offset:38912
	v_mfma_f32_16x16x32_bf16 v[40:43], v[224:227], v[200:203], v[40:43]
	s_mov_b32 m0, s101
	v_mfma_f32_16x16x32_bf16 v[32:35], v[228:231], v[200:203], v[32:35]
	global_load_lds_dwordx4 v[138:139], off
	v_lshl_add_u64 v[138:139], v[138:139], 0, s[34:35]
	v_mfma_f32_16x16x32_bf16 v[44:47], v[232:235], v[200:203], v[44:47]
	s_add_u32 m0, s101, 0x2000
	v_mfma_f32_16x16x32_bf16 v[36:39], v[236:239], v[200:203], v[36:39]
	global_load_lds_dwordx4 v[140:141], off
	v_lshl_add_u64 v[140:141], v[140:141], 0, s[34:35]
	v_mfma_f32_16x16x32_bf16 v[8:11], v[224:227], v[204:207], v[8:11]
	s_add_u32 m0, s101, 0x4000
	v_mfma_f32_16x16x32_bf16 v[0:3], v[228:231], v[204:207], v[0:3]
	global_load_lds_dwordx4 v[250:251], off
	v_lshl_add_u64 v[250:251], v[250:251], 0, s[34:35]
	v_mfma_f32_16x16x32_bf16 v[12:15], v[232:235], v[204:207], v[12:15]
	s_add_u32 m0, s101, 0x6000
	v_mfma_f32_16x16x32_bf16 v[4:7], v[236:239], v[204:207], v[4:7]
	global_load_lds_dwordx4 v[252:253], off
	v_lshl_add_u64 v[252:253], v[252:253], 0, s[34:35]
	s_waitcnt lgkmcnt(0)
	v_mfma_f32_16x16x32_bf16 v[120:123], v[208:211], v[176:179], v[120:123]
	ds_read_b128 v[224:227], v174 offset:40960
	v_mfma_f32_16x16x32_bf16 v[112:115], v[212:215], v[176:179], v[112:115]
	ds_read_b128 v[228:231], v174 offset:43008
	v_mfma_f32_16x16x32_bf16 v[124:127], v[216:219], v[176:179], v[124:127]
	ds_read_b128 v[232:235], v174 offset:45056
	v_mfma_f32_16x16x32_bf16 v[116:119], v[220:223], v[176:179], v[116:119]
	ds_read_b128 v[236:239], v174 offset:47104
	v_mfma_f32_16x16x32_bf16 v[88:91], v[208:211], v[180:183], v[88:91]
	s_mov_b32 m0, s100
	v_mfma_f32_16x16x32_bf16 v[80:83], v[212:215], v[180:183], v[80:83]
	global_load_lds_dwordx4 v[240:241], off
	v_lshl_add_u64 v[240:241], v[240:241], 0, s[34:35]
	v_mfma_f32_16x16x32_bf16 v[92:95], v[216:219], v[180:183], v[92:95]
	s_add_u32 m0, s100, 0x2000
	v_mfma_f32_16x16x32_bf16 v[84:87], v[220:223], v[180:183], v[84:87]
	global_load_lds_dwordx4 v[242:243], off
	v_lshl_add_u64 v[242:243], v[242:243], 0, s[34:35]
	v_mfma_f32_16x16x32_bf16 v[56:59], v[208:211], v[184:187], v[56:59]
	s_add_u32 m0, s100, 0x4000
	v_mfma_f32_16x16x32_bf16 v[48:51], v[212:215], v[184:187], v[48:51]
	global_load_lds_dwordx4 v[244:245], off
	v_lshl_add_u64 v[244:245], v[244:245], 0, s[34:35]
	v_mfma_f32_16x16x32_bf16 v[60:63], v[216:219], v[184:187], v[60:63]
	s_add_u32 m0, s100, 0x6000
	v_mfma_f32_16x16x32_bf16 v[52:55], v[220:223], v[184:187], v[52:55]
	global_load_lds_dwordx4 v[246:247], off
	v_lshl_add_u64 v[246:247], v[246:247], 0, s[34:35]
	v_mfma_f32_16x16x32_bf16 v[24:27], v[208:211], v[188:191], v[24:27]
	v_mfma_f32_16x16x32_bf16 v[16:19], v[212:215], v[188:191], v[16:19]
	v_mfma_f32_16x16x32_bf16 v[28:31], v[216:219], v[188:191], v[28:31]
	v_mfma_f32_16x16x32_bf16 v[20:23], v[220:223], v[188:191], v[20:23]
	s_waitcnt lgkmcnt(0)
	v_mfma_f32_16x16x32_bf16 v[104:107], v[224:227], v[176:179], v[104:107]
	ds_read_b128 v[192:195], v173 offset:32768
	v_mfma_f32_16x16x32_bf16 v[96:99], v[228:231], v[176:179], v[96:99]
	ds_read_b128 v[196:199], v173 offset:34816
	v_mfma_f32_16x16x32_bf16 v[108:111], v[232:235], v[176:179], v[108:111]
	ds_read_b128 v[200:203], v173 offset:36864
	v_mfma_f32_16x16x32_bf16 v[100:103], v[236:239], v[176:179], v[100:103]
	ds_read_b128 v[204:207], v173 offset:38912
	v_mfma_f32_16x16x32_bf16 v[72:75], v[224:227], v[180:183], v[72:75]
	ds_read_b128 v[208:211], v175 offset:32768
	v_mfma_f32_16x16x32_bf16 v[64:67], v[228:231], v[180:183], v[64:67]
	ds_read_b128 v[212:215], v175 offset:34816
	v_mfma_f32_16x16x32_bf16 v[76:79], v[232:235], v[180:183], v[76:79]
	ds_read_b128 v[216:219], v175 offset:36864
	v_mfma_f32_16x16x32_bf16 v[68:71], v[236:239], v[180:183], v[68:71]
	ds_read_b128 v[220:223], v175 offset:38912
	v_mfma_f32_16x16x32_bf16 v[40:43], v[224:227], v[184:187], v[40:43]
	v_mfma_f32_16x16x32_bf16 v[32:35], v[228:231], v[184:187], v[32:35]
	v_mfma_f32_16x16x32_bf16 v[44:47], v[232:235], v[184:187], v[44:47]
	v_mfma_f32_16x16x32_bf16 v[36:39], v[236:239], v[184:187], v[36:39]
	v_mfma_f32_16x16x32_bf16 v[8:11], v[224:227], v[188:191], v[8:11]
	v_mfma_f32_16x16x32_bf16 v[0:3], v[228:231], v[188:191], v[0:3]
	v_mfma_f32_16x16x32_bf16 v[12:15], v[232:235], v[188:191], v[12:15]
	v_mfma_f32_16x16x32_bf16 v[4:7], v[236:239], v[188:191], v[4:7]
	s_waitcnt lgkmcnt(0)
	v_mfma_f32_16x16x32_bf16 v[120:123], v[208:211], v[192:195], v[120:123]
	ds_read_b128 v[224:227], v175 offset:40960
	v_mfma_f32_16x16x32_bf16 v[112:115], v[212:215], v[192:195], v[112:115]
	ds_read_b128 v[228:231], v175 offset:43008
	v_mfma_f32_16x16x32_bf16 v[124:127], v[216:219], v[192:195], v[124:127]
	ds_read_b128 v[232:235], v175 offset:45056
	v_mfma_f32_16x16x32_bf16 v[116:119], v[220:223], v[192:195], v[116:119]
	ds_read_b128 v[236:239], v175 offset:47104
	v_mfma_f32_16x16x32_bf16 v[88:91], v[208:211], v[196:199], v[88:91]
	v_mfma_f32_16x16x32_bf16 v[80:83], v[212:215], v[196:199], v[80:83]
	v_mfma_f32_16x16x32_bf16 v[92:95], v[216:219], v[196:199], v[92:95]
	v_mfma_f32_16x16x32_bf16 v[84:87], v[220:223], v[196:199], v[84:87]
	v_mfma_f32_16x16x32_bf16 v[56:59], v[208:211], v[200:203], v[56:59]
	v_mfma_f32_16x16x32_bf16 v[48:51], v[212:215], v[200:203], v[48:51]
	v_mfma_f32_16x16x32_bf16 v[60:63], v[216:219], v[200:203], v[60:63]
	v_mfma_f32_16x16x32_bf16 v[52:55], v[220:223], v[200:203], v[52:55]
	v_mfma_f32_16x16x32_bf16 v[24:27], v[208:211], v[204:207], v[24:27]
	v_mfma_f32_16x16x32_bf16 v[16:19], v[212:215], v[204:207], v[16:19]
	v_mfma_f32_16x16x32_bf16 v[28:31], v[216:219], v[204:207], v[28:31]
	v_mfma_f32_16x16x32_bf16 v[20:23], v[220:223], v[204:207], v[20:23]
	s_waitcnt lgkmcnt(0)
	s_waitcnt vmcnt(4)
	s_barrier
	v_mfma_f32_16x16x32_bf16 v[104:107], v[224:227], v[192:195], v[104:107]
	ds_read_b128 v[176:179], v254 offset:0
	v_mfma_f32_16x16x32_bf16 v[96:99], v[228:231], v[192:195], v[96:99]
	ds_read_b128 v[180:183], v254 offset:2048
	v_mfma_f32_16x16x32_bf16 v[108:111], v[232:235], v[192:195], v[108:111]
	ds_read_b128 v[184:187], v254 offset:4096
	v_mfma_f32_16x16x32_bf16 v[100:103], v[236:239], v[192:195], v[100:103]
	ds_read_b128 v[188:191], v254 offset:6144
	v_mfma_f32_16x16x32_bf16 v[72:75], v[224:227], v[196:199], v[72:75]
	ds_read_b128 v[208:211], v174 offset:0
	v_mfma_f32_16x16x32_bf16 v[64:67], v[228:231], v[196:199], v[64:67]
	ds_read_b128 v[212:215], v174 offset:2048
	v_mfma_f32_16x16x32_bf16 v[76:79], v[232:235], v[196:199], v[76:79]
	ds_read_b128 v[216:219], v174 offset:4096
	v_mfma_f32_16x16x32_bf16 v[68:71], v[236:239], v[196:199], v[68:71]
	ds_read_b128 v[220:223], v174 offset:6144
	v_mfma_f32_16x16x32_bf16 v[40:43], v[224:227], v[200:203], v[40:43]
	s_add_u32 m0, s101, 0x8000
	v_mfma_f32_16x16x32_bf16 v[32:35], v[228:231], v[200:203], v[32:35]
	global_load_lds_dwordx4 v[138:139], off
	v_lshl_add_u64 v[138:139], v[138:139], 0, s[34:35]
	v_mfma_f32_16x16x32_bf16 v[44:47], v[232:235], v[200:203], v[44:47]
	s_add_u32 m0, s101, 0xa000
	v_mfma_f32_16x16x32_bf16 v[36:39], v[236:239], v[200:203], v[36:39]
	global_load_lds_dwordx4 v[140:141], off
	v_lshl_add_u64 v[140:141], v[140:141], 0, s[34:35]
	v_mfma_f32_16x16x32_bf16 v[8:11], v[224:227], v[204:207], v[8:11]
	s_add_u32 m0, s101, 0xc000
	v_mfma_f32_16x16x32_bf16 v[0:3], v[228:231], v[204:207], v[0:3]
	global_load_lds_dwordx4 v[250:251], off
	v_lshl_add_u64 v[250:251], v[250:251], 0, s[34:35]
	v_mfma_f32_16x16x32_bf16 v[12:15], v[232:235], v[204:207], v[12:15]
	s_add_u32 m0, s101, 0xe000
	v_mfma_f32_16x16x32_bf16 v[4:7], v[236:239], v[204:207], v[4:7]
	global_load_lds_dwordx4 v[252:253], off
	v_lshl_add_u64 v[252:253], v[252:253], 0, s[34:35]
	s_waitcnt lgkmcnt(0)
	v_mfma_f32_16x16x32_bf16 v[120:123], v[208:211], v[176:179], v[120:123]
	ds_read_b128 v[224:227], v174 offset:8192
	v_mfma_f32_16x16x32_bf16 v[112:115], v[212:215], v[176:179], v[112:115]
	ds_read_b128 v[228:231], v174 offset:10240
	v_mfma_f32_16x16x32_bf16 v[124:127], v[216:219], v[176:179], v[124:127]
	ds_read_b128 v[232:235], v174 offset:12288
	v_mfma_f32_16x16x32_bf16 v[116:119], v[220:223], v[176:179], v[116:119]
	ds_read_b128 v[236:239], v174 offset:14336
	v_mfma_f32_16x16x32_bf16 v[88:91], v[208:211], v[180:183], v[88:91]
	s_add_u32 m0, s100, 0x8000
	v_mfma_f32_16x16x32_bf16 v[80:83], v[212:215], v[180:183], v[80:83]
	global_load_lds_dwordx4 v[240:241], off
	v_lshl_add_u64 v[240:241], v[240:241], 0, s[34:35]
	v_mfma_f32_16x16x32_bf16 v[92:95], v[216:219], v[180:183], v[92:95]
	s_add_u32 m0, s100, 0xa000
	v_mfma_f32_16x16x32_bf16 v[84:87], v[220:223], v[180:183], v[84:87]
	global_load_lds_dwordx4 v[242:243], off
	v_lshl_add_u64 v[242:243], v[242:243], 0, s[34:35]
	v_mfma_f32_16x16x32_bf16 v[56:59], v[208:211], v[184:187], v[56:59]
	s_add_u32 m0, s100, 0xc000
	v_mfma_f32_16x16x32_bf16 v[48:51], v[212:215], v[184:187], v[48:51]
	global_load_lds_dwordx4 v[244:245], off
	v_lshl_add_u64 v[244:245], v[244:245], 0, s[34:35]
	v_mfma_f32_16x16x32_bf16 v[60:63], v[216:219], v[184:187], v[60:63]
	s_add_u32 m0, s100, 0xe000
	v_mfma_f32_16x16x32_bf16 v[52:55], v[220:223], v[184:187], v[52:55]
	global_load_lds_dwordx4 v[246:247], off
	v_lshl_add_u64 v[246:247], v[246:247], 0, s[34:35]
	v_mfma_f32_16x16x32_bf16 v[24:27], v[208:211], v[188:191], v[24:27]
	v_mfma_f32_16x16x32_bf16 v[16:19], v[212:215], v[188:191], v[16:19]
	v_mfma_f32_16x16x32_bf16 v[28:31], v[216:219], v[188:191], v[28:31]
	v_mfma_f32_16x16x32_bf16 v[20:23], v[220:223], v[188:191], v[20:23]
	s_waitcnt lgkmcnt(0)
	v_mfma_f32_16x16x32_bf16 v[104:107], v[224:227], v[176:179], v[104:107]
	ds_read_b128 v[192:195], v255 offset:0
	v_mfma_f32_16x16x32_bf16 v[96:99], v[228:231], v[176:179], v[96:99]
	ds_read_b128 v[196:199], v255 offset:2048
	v_mfma_f32_16x16x32_bf16 v[108:111], v[232:235], v[176:179], v[108:111]
	ds_read_b128 v[200:203], v255 offset:4096
	v_mfma_f32_16x16x32_bf16 v[100:103], v[236:239], v[176:179], v[100:103]
	ds_read_b128 v[204:207], v255 offset:6144
	v_mfma_f32_16x16x32_bf16 v[72:75], v[224:227], v[180:183], v[72:75]
	ds_read_b128 v[208:211], v175 offset:0
	v_mfma_f32_16x16x32_bf16 v[64:67], v[228:231], v[180:183], v[64:67]
	ds_read_b128 v[212:215], v175 offset:2048
	v_mfma_f32_16x16x32_bf16 v[76:79], v[232:235], v[180:183], v[76:79]
	ds_read_b128 v[216:219], v175 offset:4096
	v_mfma_f32_16x16x32_bf16 v[68:71], v[236:239], v[180:183], v[68:71]
	ds_read_b128 v[220:223], v175 offset:6144
	v_mfma_f32_16x16x32_bf16 v[40:43], v[224:227], v[184:187], v[40:43]
	v_mfma_f32_16x16x32_bf16 v[32:35], v[228:231], v[184:187], v[32:35]
	v_mfma_f32_16x16x32_bf16 v[44:47], v[232:235], v[184:187], v[44:47]
	v_mfma_f32_16x16x32_bf16 v[36:39], v[236:239], v[184:187], v[36:39]
	v_mfma_f32_16x16x32_bf16 v[8:11], v[224:227], v[188:191], v[8:11]
	v_mfma_f32_16x16x32_bf16 v[0:3], v[228:231], v[188:191], v[0:3]
	v_mfma_f32_16x16x32_bf16 v[12:15], v[232:235], v[188:191], v[12:15]
	v_mfma_f32_16x16x32_bf16 v[4:7], v[236:239], v[188:191], v[4:7]
	s_waitcnt lgkmcnt(0)
	v_mfma_f32_16x16x32_bf16 v[120:123], v[208:211], v[192:195], v[120:123]
	ds_read_b128 v[224:227], v175 offset:8192
	v_mfma_f32_16x16x32_bf16 v[112:115], v[212:215], v[192:195], v[112:115]
	ds_read_b128 v[228:231], v175 offset:10240
	v_mfma_f32_16x16x32_bf16 v[124:127], v[216:219], v[192:195], v[124:127]
	ds_read_b128 v[232:235], v175 offset:12288
	v_mfma_f32_16x16x32_bf16 v[116:119], v[220:223], v[192:195], v[116:119]
	ds_read_b128 v[236:239], v175 offset:14336
	v_mfma_f32_16x16x32_bf16 v[88:91], v[208:211], v[196:199], v[88:91]
	v_mfma_f32_16x16x32_bf16 v[80:83], v[212:215], v[196:199], v[80:83]
	v_mfma_f32_16x16x32_bf16 v[92:95], v[216:219], v[196:199], v[92:95]
	v_mfma_f32_16x16x32_bf16 v[84:87], v[220:223], v[196:199], v[84:87]
	v_mfma_f32_16x16x32_bf16 v[56:59], v[208:211], v[200:203], v[56:59]
	v_mfma_f32_16x16x32_bf16 v[48:51], v[212:215], v[200:203], v[48:51]
	v_mfma_f32_16x16x32_bf16 v[60:63], v[216:219], v[200:203], v[60:63]
	v_mfma_f32_16x16x32_bf16 v[52:55], v[220:223], v[200:203], v[52:55]
	v_mfma_f32_16x16x32_bf16 v[24:27], v[208:211], v[204:207], v[24:27]
	v_mfma_f32_16x16x32_bf16 v[16:19], v[212:215], v[204:207], v[16:19]
	v_mfma_f32_16x16x32_bf16 v[28:31], v[216:219], v[204:207], v[28:31]
	v_mfma_f32_16x16x32_bf16 v[20:23], v[220:223], v[204:207], v[20:23]
	s_waitcnt lgkmcnt(0)
	s_waitcnt vmcnt(4)
	s_barrier
	v_mfma_f32_16x16x32_bf16 v[104:107], v[224:227], v[192:195], v[104:107]
	ds_read_b128 v[176:179], v172 offset:0
	v_mfma_f32_16x16x32_bf16 v[96:99], v[228:231], v[192:195], v[96:99]
	ds_read_b128 v[180:183], v172 offset:2048
	v_mfma_f32_16x16x32_bf16 v[108:111], v[232:235], v[192:195], v[108:111]
	ds_read_b128 v[184:187], v172 offset:4096
	v_mfma_f32_16x16x32_bf16 v[100:103], v[236:239], v[192:195], v[100:103]
	ds_read_b128 v[188:191], v172 offset:6144
	v_mfma_f32_16x16x32_bf16 v[72:75], v[224:227], v[196:199], v[72:75]
	ds_read_b128 v[208:211], v174 offset:32768
	v_mfma_f32_16x16x32_bf16 v[64:67], v[228:231], v[196:199], v[64:67]
	ds_read_b128 v[212:215], v174 offset:34816
	v_mfma_f32_16x16x32_bf16 v[76:79], v[232:235], v[196:199], v[76:79]
	ds_read_b128 v[216:219], v174 offset:36864
	v_mfma_f32_16x16x32_bf16 v[68:71], v[236:239], v[196:199], v[68:71]
	ds_read_b128 v[220:223], v174 offset:38912
	v_mfma_f32_16x16x32_bf16 v[40:43], v[224:227], v[200:203], v[40:43]
	s_mov_b32 m0, s101
	v_mfma_f32_16x16x32_bf16 v[32:35], v[228:231], v[200:203], v[32:35]
	global_load_lds_dwordx4 v[138:139], off
	v_lshl_add_u64 v[138:139], v[138:139], 0, s[34:35]
	v_mfma_f32_16x16x32_bf16 v[44:47], v[232:235], v[200:203], v[44:47]
	s_add_u32 m0, s101, 0x2000
	v_mfma_f32_16x16x32_bf16 v[36:39], v[236:239], v[200:203], v[36:39]
	global_load_lds_dwordx4 v[140:141], off
	v_lshl_add_u64 v[140:141], v[140:141], 0, s[34:35]
	v_mfma_f32_16x16x32_bf16 v[8:11], v[224:227], v[204:207], v[8:11]
	s_add_u32 m0, s101, 0x4000
	v_mfma_f32_16x16x32_bf16 v[0:3], v[228:231], v[204:207], v[0:3]
	global_load_lds_dwordx4 v[250:251], off
	v_lshl_add_u64 v[250:251], v[250:251], 0, s[34:35]
	v_mfma_f32_16x16x32_bf16 v[12:15], v[232:235], v[204:207], v[12:15]
	s_add_u32 m0, s101, 0x6000
	v_mfma_f32_16x16x32_bf16 v[4:7], v[236:239], v[204:207], v[4:7]
	global_load_lds_dwordx4 v[252:253], off
	v_lshl_add_u64 v[252:253], v[252:253], 0, s[34:35]
	s_waitcnt lgkmcnt(0)
	v_mfma_f32_16x16x32_bf16 v[120:123], v[208:211], v[176:179], v[120:123]
	ds_read_b128 v[224:227], v174 offset:40960
	v_mfma_f32_16x16x32_bf16 v[112:115], v[212:215], v[176:179], v[112:115]
	ds_read_b128 v[228:231], v174 offset:43008
	v_mfma_f32_16x16x32_bf16 v[124:127], v[216:219], v[176:179], v[124:127]
	ds_read_b128 v[232:235], v174 offset:45056
	v_mfma_f32_16x16x32_bf16 v[116:119], v[220:223], v[176:179], v[116:119]
	ds_read_b128 v[236:239], v174 offset:47104
	v_mfma_f32_16x16x32_bf16 v[88:91], v[208:211], v[180:183], v[88:91]
	s_add_u32 m0, s100, 0x20000
	v_mfma_f32_16x16x32_bf16 v[80:83], v[212:215], v[180:183], v[80:83]
	global_load_lds_dwordx4 v[240:241], off
	v_lshl_add_u64 v[240:241], v[240:241], 0, s[34:35]
	v_mfma_f32_16x16x32_bf16 v[92:95], v[216:219], v[180:183], v[92:95]
	s_add_u32 m0, s100, 0x22000
	v_mfma_f32_16x16x32_bf16 v[84:87], v[220:223], v[180:183], v[84:87]
	global_load_lds_dwordx4 v[242:243], off
	v_lshl_add_u64 v[242:243], v[242:243], 0, s[34:35]
	v_mfma_f32_16x16x32_bf16 v[56:59], v[208:211], v[184:187], v[56:59]
	s_add_u32 m0, s100, 0x24000
	v_mfma_f32_16x16x32_bf16 v[48:51], v[212:215], v[184:187], v[48:51]
	global_load_lds_dwordx4 v[244:245], off
	v_lshl_add_u64 v[244:245], v[244:245], 0, s[34:35]
	v_mfma_f32_16x16x32_bf16 v[60:63], v[216:219], v[184:187], v[60:63]
	s_add_u32 m0, s100, 0x26000
	v_mfma_f32_16x16x32_bf16 v[52:55], v[220:223], v[184:187], v[52:55]
	global_load_lds_dwordx4 v[246:247], off
	v_lshl_add_u64 v[246:247], v[246:247], 0, s[34:35]
	v_mfma_f32_16x16x32_bf16 v[24:27], v[208:211], v[188:191], v[24:27]
	v_mfma_f32_16x16x32_bf16 v[16:19], v[212:215], v[188:191], v[16:19]
	v_mfma_f32_16x16x32_bf16 v[28:31], v[216:219], v[188:191], v[28:31]
	v_mfma_f32_16x16x32_bf16 v[20:23], v[220:223], v[188:191], v[20:23]
	s_waitcnt lgkmcnt(0)
	v_mfma_f32_16x16x32_bf16 v[104:107], v[224:227], v[176:179], v[104:107]
	ds_read_b128 v[192:195], v173 offset:0
	v_mfma_f32_16x16x32_bf16 v[96:99], v[228:231], v[176:179], v[96:99]
	ds_read_b128 v[196:199], v173 offset:2048
	v_mfma_f32_16x16x32_bf16 v[108:111], v[232:235], v[176:179], v[108:111]
	ds_read_b128 v[200:203], v173 offset:4096
	v_mfma_f32_16x16x32_bf16 v[100:103], v[236:239], v[176:179], v[100:103]
	ds_read_b128 v[204:207], v173 offset:6144
	v_mfma_f32_16x16x32_bf16 v[72:75], v[224:227], v[180:183], v[72:75]
	ds_read_b128 v[208:211], v175 offset:32768
	v_mfma_f32_16x16x32_bf16 v[64:67], v[228:231], v[180:183], v[64:67]
	ds_read_b128 v[212:215], v175 offset:34816
	v_mfma_f32_16x16x32_bf16 v[76:79], v[232:235], v[180:183], v[76:79]
	ds_read_b128 v[216:219], v175 offset:36864
	v_mfma_f32_16x16x32_bf16 v[68:71], v[236:239], v[180:183], v[68:71]
	ds_read_b128 v[220:223], v175 offset:38912
	v_mfma_f32_16x16x32_bf16 v[40:43], v[224:227], v[184:187], v[40:43]
	v_mfma_f32_16x16x32_bf16 v[32:35], v[228:231], v[184:187], v[32:35]
	v_mfma_f32_16x16x32_bf16 v[44:47], v[232:235], v[184:187], v[44:47]
	v_mfma_f32_16x16x32_bf16 v[36:39], v[236:239], v[184:187], v[36:39]
	v_mfma_f32_16x16x32_bf16 v[8:11], v[224:227], v[188:191], v[8:11]
	v_mfma_f32_16x16x32_bf16 v[0:3], v[228:231], v[188:191], v[0:3]
	v_mfma_f32_16x16x32_bf16 v[12:15], v[232:235], v[188:191], v[12:15]
	v_mfma_f32_16x16x32_bf16 v[4:7], v[236:239], v[188:191], v[4:7]
	s_waitcnt lgkmcnt(0)
	v_mfma_f32_16x16x32_bf16 v[120:123], v[208:211], v[192:195], v[120:123]
	ds_read_b128 v[224:227], v175 offset:40960
	v_mfma_f32_16x16x32_bf16 v[112:115], v[212:215], v[192:195], v[112:115]
	ds_read_b128 v[228:231], v175 offset:43008
	v_mfma_f32_16x16x32_bf16 v[124:127], v[216:219], v[192:195], v[124:127]
	ds_read_b128 v[232:235], v175 offset:45056
	v_mfma_f32_16x16x32_bf16 v[116:119], v[220:223], v[192:195], v[116:119]
	ds_read_b128 v[236:239], v175 offset:47104
	v_mfma_f32_16x16x32_bf16 v[88:91], v[208:211], v[196:199], v[88:91]
	v_mfma_f32_16x16x32_bf16 v[80:83], v[212:215], v[196:199], v[80:83]
	v_mfma_f32_16x16x32_bf16 v[92:95], v[216:219], v[196:199], v[92:95]
	v_mfma_f32_16x16x32_bf16 v[84:87], v[220:223], v[196:199], v[84:87]
	v_mfma_f32_16x16x32_bf16 v[56:59], v[208:211], v[200:203], v[56:59]
	v_mfma_f32_16x16x32_bf16 v[48:51], v[212:215], v[200:203], v[48:51]
	v_mfma_f32_16x16x32_bf16 v[60:63], v[216:219], v[200:203], v[60:63]
	v_mfma_f32_16x16x32_bf16 v[52:55], v[220:223], v[200:203], v[52:55]
	v_mfma_f32_16x16x32_bf16 v[24:27], v[208:211], v[204:207], v[24:27]
	v_mfma_f32_16x16x32_bf16 v[16:19], v[212:215], v[204:207], v[16:19]
	v_mfma_f32_16x16x32_bf16 v[28:31], v[216:219], v[204:207], v[28:31]
	v_mfma_f32_16x16x32_bf16 v[20:23], v[220:223], v[204:207], v[20:23]
	s_waitcnt lgkmcnt(0)
	s_waitcnt vmcnt(4)
	s_barrier
	v_mfma_f32_16x16x32_bf16 v[104:107], v[224:227], v[192:195], v[104:107]
	ds_read_b128 v[176:179], v172 offset:32768
	v_mfma_f32_16x16x32_bf16 v[96:99], v[228:231], v[192:195], v[96:99]
	ds_read_b128 v[180:183], v172 offset:34816
	v_mfma_f32_16x16x32_bf16 v[108:111], v[232:235], v[192:195], v[108:111]
	ds_read_b128 v[184:187], v172 offset:36864
	v_mfma_f32_16x16x32_bf16 v[100:103], v[236:239], v[192:195], v[100:103]
	ds_read_b128 v[188:191], v172 offset:38912
	v_mfma_f32_16x16x32_bf16 v[72:75], v[224:227], v[196:199], v[72:75]
	ds_read_b128 v[208:211], v174 offset:0
	v_mfma_f32_16x16x32_bf16 v[64:67], v[228:231], v[196:199], v[64:67]
	ds_read_b128 v[212:215], v174 offset:2048
	v_mfma_f32_16x16x32_bf16 v[76:79], v[232:235], v[196:199], v[76:79]
	ds_read_b128 v[216:219], v174 offset:4096
	v_mfma_f32_16x16x32_bf16 v[68:71], v[236:239], v[196:199], v[68:71]
	ds_read_b128 v[220:223], v174 offset:6144
	v_mfma_f32_16x16x32_bf16 v[40:43], v[224:227], v[200:203], v[40:43]
	s_add_u32 m0, s101, 0x8000
	v_mfma_f32_16x16x32_bf16 v[32:35], v[228:231], v[200:203], v[32:35]
	global_load_lds_dwordx4 v[138:139], off
	v_lshl_add_u64 v[138:139], v[138:139], 0, s[34:35]
	v_mfma_f32_16x16x32_bf16 v[44:47], v[232:235], v[200:203], v[44:47]
	s_add_u32 m0, s101, 0xa000
	v_mfma_f32_16x16x32_bf16 v[36:39], v[236:239], v[200:203], v[36:39]
	global_load_lds_dwordx4 v[140:141], off
	v_lshl_add_u64 v[140:141], v[140:141], 0, s[34:35]
	v_mfma_f32_16x16x32_bf16 v[8:11], v[224:227], v[204:207], v[8:11]
	s_add_u32 m0, s101, 0xc000
	v_mfma_f32_16x16x32_bf16 v[0:3], v[228:231], v[204:207], v[0:3]
	global_load_lds_dwordx4 v[250:251], off
	v_lshl_add_u64 v[250:251], v[250:251], 0, s[34:35]
	v_mfma_f32_16x16x32_bf16 v[12:15], v[232:235], v[204:207], v[12:15]
	s_add_u32 m0, s101, 0xe000
	v_mfma_f32_16x16x32_bf16 v[4:7], v[236:239], v[204:207], v[4:7]
	global_load_lds_dwordx4 v[252:253], off
	v_lshl_add_u64 v[252:253], v[252:253], 0, s[34:35]
	s_waitcnt lgkmcnt(0)
	v_mfma_f32_16x16x32_bf16 v[120:123], v[208:211], v[176:179], v[120:123]
	ds_read_b128 v[224:227], v174 offset:8192
	v_mfma_f32_16x16x32_bf16 v[112:115], v[212:215], v[176:179], v[112:115]
	ds_read_b128 v[228:231], v174 offset:10240
	v_mfma_f32_16x16x32_bf16 v[124:127], v[216:219], v[176:179], v[124:127]
	ds_read_b128 v[232:235], v174 offset:12288
	v_mfma_f32_16x16x32_bf16 v[116:119], v[220:223], v[176:179], v[116:119]
	ds_read_b128 v[236:239], v174 offset:14336
	v_mfma_f32_16x16x32_bf16 v[88:91], v[208:211], v[180:183], v[88:91]
	s_mov_b32 m0, s100
	v_mfma_f32_16x16x32_bf16 v[80:83], v[212:215], v[180:183], v[80:83]
	global_load_lds_dwordx4 v[240:241], off
	v_lshl_add_u64 v[240:241], v[240:241], 0, s[34:35]
	v_mfma_f32_16x16x32_bf16 v[92:95], v[216:219], v[180:183], v[92:95]
	s_add_u32 m0, s100, 0x2000
	v_mfma_f32_16x16x32_bf16 v[84:87], v[220:223], v[180:183], v[84:87]
	global_load_lds_dwordx4 v[242:243], off
	v_lshl_add_u64 v[242:243], v[242:243], 0, s[34:35]
	v_mfma_f32_16x16x32_bf16 v[56:59], v[208:211], v[184:187], v[56:59]
	s_add_u32 m0, s100, 0x4000
	v_mfma_f32_16x16x32_bf16 v[48:51], v[212:215], v[184:187], v[48:51]
	global_load_lds_dwordx4 v[244:245], off
	v_lshl_add_u64 v[244:245], v[244:245], 0, s[34:35]
	v_mfma_f32_16x16x32_bf16 v[60:63], v[216:219], v[184:187], v[60:63]
	s_add_u32 m0, s100, 0x6000
	v_mfma_f32_16x16x32_bf16 v[52:55], v[220:223], v[184:187], v[52:55]
	global_load_lds_dwordx4 v[246:247], off
	v_lshl_add_u64 v[246:247], v[246:247], 0, s[34:35]
	v_mfma_f32_16x16x32_bf16 v[24:27], v[208:211], v[188:191], v[24:27]
	v_mfma_f32_16x16x32_bf16 v[16:19], v[212:215], v[188:191], v[16:19]
	v_mfma_f32_16x16x32_bf16 v[28:31], v[216:219], v[188:191], v[28:31]
	v_mfma_f32_16x16x32_bf16 v[20:23], v[220:223], v[188:191], v[20:23]
	s_waitcnt lgkmcnt(0)
	v_mfma_f32_16x16x32_bf16 v[104:107], v[224:227], v[176:179], v[104:107]
	ds_read_b128 v[192:195], v173 offset:32768
	v_mfma_f32_16x16x32_bf16 v[96:99], v[228:231], v[176:179], v[96:99]
	ds_read_b128 v[196:199], v173 offset:34816
	v_mfma_f32_16x16x32_bf16 v[108:111], v[232:235], v[176:179], v[108:111]
	ds_read_b128 v[200:203], v173 offset:36864
	v_mfma_f32_16x16x32_bf16 v[100:103], v[236:239], v[176:179], v[100:103]
	ds_read_b128 v[204:207], v173 offset:38912
	v_mfma_f32_16x16x32_bf16 v[72:75], v[224:227], v[180:183], v[72:75]
	ds_read_b128 v[208:211], v175 offset:0
	v_mfma_f32_16x16x32_bf16 v[64:67], v[228:231], v[180:183], v[64:67]
	ds_read_b128 v[212:215], v175 offset:2048
	v_mfma_f32_16x16x32_bf16 v[76:79], v[232:235], v[180:183], v[76:79]
	ds_read_b128 v[216:219], v175 offset:4096
	v_mfma_f32_16x16x32_bf16 v[68:71], v[236:239], v[180:183], v[68:71]
	ds_read_b128 v[220:223], v175 offset:6144
	v_mfma_f32_16x16x32_bf16 v[40:43], v[224:227], v[184:187], v[40:43]
	v_mfma_f32_16x16x32_bf16 v[32:35], v[228:231], v[184:187], v[32:35]
	v_mfma_f32_16x16x32_bf16 v[44:47], v[232:235], v[184:187], v[44:47]
	v_mfma_f32_16x16x32_bf16 v[36:39], v[236:239], v[184:187], v[36:39]
	v_mfma_f32_16x16x32_bf16 v[8:11], v[224:227], v[188:191], v[8:11]
	v_mfma_f32_16x16x32_bf16 v[0:3], v[228:231], v[188:191], v[0:3]
	v_mfma_f32_16x16x32_bf16 v[12:15], v[232:235], v[188:191], v[12:15]
	v_mfma_f32_16x16x32_bf16 v[4:7], v[236:239], v[188:191], v[4:7]
	s_waitcnt lgkmcnt(0)
	v_mfma_f32_16x16x32_bf16 v[120:123], v[208:211], v[192:195], v[120:123]
	ds_read_b128 v[224:227], v175 offset:8192
	v_mfma_f32_16x16x32_bf16 v[112:115], v[212:215], v[192:195], v[112:115]
	ds_read_b128 v[228:231], v175 offset:10240
	v_mfma_f32_16x16x32_bf16 v[124:127], v[216:219], v[192:195], v[124:127]
	ds_read_b128 v[232:235], v175 offset:12288
	v_mfma_f32_16x16x32_bf16 v[116:119], v[220:223], v[192:195], v[116:119]
	ds_read_b128 v[236:239], v175 offset:14336
	v_mfma_f32_16x16x32_bf16 v[88:91], v[208:211], v[196:199], v[88:91]
	v_mfma_f32_16x16x32_bf16 v[80:83], v[212:215], v[196:199], v[80:83]
	v_mfma_f32_16x16x32_bf16 v[92:95], v[216:219], v[196:199], v[92:95]
	v_mfma_f32_16x16x32_bf16 v[84:87], v[220:223], v[196:199], v[84:87]
	v_mfma_f32_16x16x32_bf16 v[56:59], v[208:211], v[200:203], v[56:59]
	v_mfma_f32_16x16x32_bf16 v[48:51], v[212:215], v[200:203], v[48:51]
	v_mfma_f32_16x16x32_bf16 v[60:63], v[216:219], v[200:203], v[60:63]
	v_mfma_f32_16x16x32_bf16 v[52:55], v[220:223], v[200:203], v[52:55]
	v_mfma_f32_16x16x32_bf16 v[24:27], v[208:211], v[204:207], v[24:27]
	v_mfma_f32_16x16x32_bf16 v[16:19], v[212:215], v[204:207], v[16:19]
	v_mfma_f32_16x16x32_bf16 v[28:31], v[216:219], v[204:207], v[28:31]
	v_mfma_f32_16x16x32_bf16 v[20:23], v[220:223], v[204:207], v[20:23]
	s_waitcnt lgkmcnt(0)
	s_waitcnt vmcnt(4)
	s_barrier
	v_mfma_f32_16x16x32_bf16 v[104:107], v[224:227], v[192:195], v[104:107]
	ds_read_b128 v[176:179], v254 offset:0
	v_mfma_f32_16x16x32_bf16 v[96:99], v[228:231], v[192:195], v[96:99]
	ds_read_b128 v[180:183], v254 offset:2048
	v_mfma_f32_16x16x32_bf16 v[108:111], v[232:235], v[192:195], v[108:111]
	ds_read_b128 v[184:187], v254 offset:4096
	v_mfma_f32_16x16x32_bf16 v[100:103], v[236:239], v[192:195], v[100:103]
	ds_read_b128 v[188:191], v254 offset:6144
	v_mfma_f32_16x16x32_bf16 v[72:75], v[224:227], v[196:199], v[72:75]
	ds_read_b128 v[208:211], v174 offset:32768
	v_mfma_f32_16x16x32_bf16 v[64:67], v[228:231], v[196:199], v[64:67]
	ds_read_b128 v[212:215], v174 offset:34816
	v_mfma_f32_16x16x32_bf16 v[76:79], v[232:235], v[196:199], v[76:79]
	ds_read_b128 v[216:219], v174 offset:36864
	v_mfma_f32_16x16x32_bf16 v[68:71], v[236:239], v[196:199], v[68:71]
	ds_read_b128 v[220:223], v174 offset:38912
	v_mfma_f32_16x16x32_bf16 v[40:43], v[224:227], v[200:203], v[40:43]
	s_mov_b32 m0, s101
	v_mfma_f32_16x16x32_bf16 v[32:35], v[228:231], v[200:203], v[32:35]
	global_load_lds_dwordx4 v[138:139], off
	v_lshl_add_u64 v[138:139], v[138:139], 0, s[34:35]
	v_mfma_f32_16x16x32_bf16 v[44:47], v[232:235], v[200:203], v[44:47]
	s_add_u32 m0, s101, 0x2000
	v_mfma_f32_16x16x32_bf16 v[36:39], v[236:239], v[200:203], v[36:39]
	global_load_lds_dwordx4 v[140:141], off
	v_lshl_add_u64 v[140:141], v[140:141], 0, s[34:35]
	v_mfma_f32_16x16x32_bf16 v[8:11], v[224:227], v[204:207], v[8:11]
	s_add_u32 m0, s101, 0x4000
	v_mfma_f32_16x16x32_bf16 v[0:3], v[228:231], v[204:207], v[0:3]
	global_load_lds_dwordx4 v[250:251], off
	v_lshl_add_u64 v[250:251], v[250:251], 0, s[34:35]
	v_mfma_f32_16x16x32_bf16 v[12:15], v[232:235], v[204:207], v[12:15]
	s_add_u32 m0, s101, 0x6000
	v_mfma_f32_16x16x32_bf16 v[4:7], v[236:239], v[204:207], v[4:7]
	global_load_lds_dwordx4 v[252:253], off
	v_lshl_add_u64 v[252:253], v[252:253], 0, s[34:35]
	s_waitcnt lgkmcnt(0)
	v_mfma_f32_16x16x32_bf16 v[120:123], v[208:211], v[176:179], v[120:123]
	ds_read_b128 v[224:227], v174 offset:40960
	v_mfma_f32_16x16x32_bf16 v[112:115], v[212:215], v[176:179], v[112:115]
	ds_read_b128 v[228:231], v174 offset:43008
	v_mfma_f32_16x16x32_bf16 v[124:127], v[216:219], v[176:179], v[124:127]
	ds_read_b128 v[232:235], v174 offset:45056
	v_mfma_f32_16x16x32_bf16 v[116:119], v[220:223], v[176:179], v[116:119]
	ds_read_b128 v[236:239], v174 offset:47104
	v_mfma_f32_16x16x32_bf16 v[88:91], v[208:211], v[180:183], v[88:91]
	s_add_u32 m0, s100, 0x8000
	v_mfma_f32_16x16x32_bf16 v[80:83], v[212:215], v[180:183], v[80:83]
	global_load_lds_dwordx4 v[240:241], off
	v_lshl_add_u64 v[240:241], v[240:241], 0, s[34:35]
	v_mfma_f32_16x16x32_bf16 v[92:95], v[216:219], v[180:183], v[92:95]
	s_add_u32 m0, s100, 0xa000
	v_mfma_f32_16x16x32_bf16 v[84:87], v[220:223], v[180:183], v[84:87]
	global_load_lds_dwordx4 v[242:243], off
	v_lshl_add_u64 v[242:243], v[242:243], 0, s[34:35]
	v_mfma_f32_16x16x32_bf16 v[56:59], v[208:211], v[184:187], v[56:59]
	s_add_u32 m0, s100, 0xc000
	v_mfma_f32_16x16x32_bf16 v[48:51], v[212:215], v[184:187], v[48:51]
	global_load_lds_dwordx4 v[244:245], off
	v_lshl_add_u64 v[244:245], v[244:245], 0, s[34:35]
	v_mfma_f32_16x16x32_bf16 v[60:63], v[216:219], v[184:187], v[60:63]
	s_add_u32 m0, s100, 0xe000
	v_mfma_f32_16x16x32_bf16 v[52:55], v[220:223], v[184:187], v[52:55]
	global_load_lds_dwordx4 v[246:247], off
	v_lshl_add_u64 v[246:247], v[246:247], 0, s[34:35]
	v_mfma_f32_16x16x32_bf16 v[24:27], v[208:211], v[188:191], v[24:27]
	v_mfma_f32_16x16x32_bf16 v[16:19], v[212:215], v[188:191], v[16:19]
	v_mfma_f32_16x16x32_bf16 v[28:31], v[216:219], v[188:191], v[28:31]
	v_mfma_f32_16x16x32_bf16 v[20:23], v[220:223], v[188:191], v[20:23]
	s_waitcnt lgkmcnt(0)
	v_mfma_f32_16x16x32_bf16 v[104:107], v[224:227], v[176:179], v[104:107]
	ds_read_b128 v[192:195], v255 offset:0
	v_mfma_f32_16x16x32_bf16 v[96:99], v[228:231], v[176:179], v[96:99]
	ds_read_b128 v[196:199], v255 offset:2048
	v_mfma_f32_16x16x32_bf16 v[108:111], v[232:235], v[176:179], v[108:111]
	ds_read_b128 v[200:203], v255 offset:4096
	v_mfma_f32_16x16x32_bf16 v[100:103], v[236:239], v[176:179], v[100:103]
	ds_read_b128 v[204:207], v255 offset:6144
	v_mfma_f32_16x16x32_bf16 v[72:75], v[224:227], v[180:183], v[72:75]
	ds_read_b128 v[208:211], v175 offset:32768
	v_mfma_f32_16x16x32_bf16 v[64:67], v[228:231], v[180:183], v[64:67]
	ds_read_b128 v[212:215], v175 offset:34816
	v_mfma_f32_16x16x32_bf16 v[76:79], v[232:235], v[180:183], v[76:79]
	ds_read_b128 v[216:219], v175 offset:36864
	v_mfma_f32_16x16x32_bf16 v[68:71], v[236:239], v[180:183], v[68:71]
	ds_read_b128 v[220:223], v175 offset:38912
	v_mfma_f32_16x16x32_bf16 v[40:43], v[224:227], v[184:187], v[40:43]
	v_mfma_f32_16x16x32_bf16 v[32:35], v[228:231], v[184:187], v[32:35]
	v_mfma_f32_16x16x32_bf16 v[44:47], v[232:235], v[184:187], v[44:47]
	v_mfma_f32_16x16x32_bf16 v[36:39], v[236:239], v[184:187], v[36:39]
	v_mfma_f32_16x16x32_bf16 v[8:11], v[224:227], v[188:191], v[8:11]
	v_mfma_f32_16x16x32_bf16 v[0:3], v[228:231], v[188:191], v[0:3]
	v_mfma_f32_16x16x32_bf16 v[12:15], v[232:235], v[188:191], v[12:15]
	v_mfma_f32_16x16x32_bf16 v[4:7], v[236:239], v[188:191], v[4:7]
	s_waitcnt lgkmcnt(0)
	v_mfma_f32_16x16x32_bf16 v[120:123], v[208:211], v[192:195], v[120:123]
	ds_read_b128 v[224:227], v175 offset:40960
	v_mfma_f32_16x16x32_bf16 v[112:115], v[212:215], v[192:195], v[112:115]
	ds_read_b128 v[228:231], v175 offset:43008
	v_mfma_f32_16x16x32_bf16 v[124:127], v[216:219], v[192:195], v[124:127]
	ds_read_b128 v[232:235], v175 offset:45056
	v_mfma_f32_16x16x32_bf16 v[116:119], v[220:223], v[192:195], v[116:119]
	ds_read_b128 v[236:239], v175 offset:47104
	v_mfma_f32_16x16x32_bf16 v[88:91], v[208:211], v[196:199], v[88:91]
	v_mfma_f32_16x16x32_bf16 v[80:83], v[212:215], v[196:199], v[80:83]
	v_mfma_f32_16x16x32_bf16 v[92:95], v[216:219], v[196:199], v[92:95]
	v_mfma_f32_16x16x32_bf16 v[84:87], v[220:223], v[196:199], v[84:87]
	v_mfma_f32_16x16x32_bf16 v[56:59], v[208:211], v[200:203], v[56:59]
	v_mfma_f32_16x16x32_bf16 v[48:51], v[212:215], v[200:203], v[48:51]
	v_mfma_f32_16x16x32_bf16 v[60:63], v[216:219], v[200:203], v[60:63]
	v_mfma_f32_16x16x32_bf16 v[52:55], v[220:223], v[200:203], v[52:55]
	v_mfma_f32_16x16x32_bf16 v[24:27], v[208:211], v[204:207], v[24:27]
	v_mfma_f32_16x16x32_bf16 v[16:19], v[212:215], v[204:207], v[16:19]
	v_mfma_f32_16x16x32_bf16 v[28:31], v[216:219], v[204:207], v[28:31]
	v_mfma_f32_16x16x32_bf16 v[20:23], v[220:223], v[204:207], v[20:23]
	s_waitcnt lgkmcnt(0)
	s_waitcnt vmcnt(4)
	s_barrier
	v_mfma_f32_16x16x32_bf16 v[104:107], v[224:227], v[192:195], v[104:107]
	ds_read_b128 v[176:179], v172 offset:0
	v_mfma_f32_16x16x32_bf16 v[96:99], v[228:231], v[192:195], v[96:99]
	ds_read_b128 v[180:183], v172 offset:2048
	v_mfma_f32_16x16x32_bf16 v[108:111], v[232:235], v[192:195], v[108:111]
	ds_read_b128 v[184:187], v172 offset:4096
	v_mfma_f32_16x16x32_bf16 v[100:103], v[236:239], v[192:195], v[100:103]
	ds_read_b128 v[188:191], v172 offset:6144
	v_mfma_f32_16x16x32_bf16 v[72:75], v[224:227], v[196:199], v[72:75]
	ds_read_b128 v[208:211], v174 offset:0
	v_mfma_f32_16x16x32_bf16 v[64:67], v[228:231], v[196:199], v[64:67]
	ds_read_b128 v[212:215], v174 offset:2048
	v_mfma_f32_16x16x32_bf16 v[76:79], v[232:235], v[196:199], v[76:79]
	ds_read_b128 v[216:219], v174 offset:4096
	v_mfma_f32_16x16x32_bf16 v[68:71], v[236:239], v[196:199], v[68:71]
	ds_read_b128 v[220:223], v174 offset:6144
	v_mfma_f32_16x16x32_bf16 v[40:43], v[224:227], v[200:203], v[40:43]
	s_add_u32 m0, s101, 0x8000
	v_mfma_f32_16x16x32_bf16 v[32:35], v[228:231], v[200:203], v[32:35]
	global_load_lds_dwordx4 v[138:139], off
	v_lshl_add_u64 v[138:139], v[138:139], 0, s[34:35]
	v_mfma_f32_16x16x32_bf16 v[44:47], v[232:235], v[200:203], v[44:47]
	s_add_u32 m0, s101, 0xa000
	v_mfma_f32_16x16x32_bf16 v[36:39], v[236:239], v[200:203], v[36:39]
	global_load_lds_dwordx4 v[140:141], off
	v_lshl_add_u64 v[140:141], v[140:141], 0, s[34:35]
	v_mfma_f32_16x16x32_bf16 v[8:11], v[224:227], v[204:207], v[8:11]
	s_add_u32 m0, s101, 0xc000
	v_mfma_f32_16x16x32_bf16 v[0:3], v[228:231], v[204:207], v[0:3]
	global_load_lds_dwordx4 v[250:251], off
	v_lshl_add_u64 v[250:251], v[250:251], 0, s[34:35]
	v_mfma_f32_16x16x32_bf16 v[12:15], v[232:235], v[204:207], v[12:15]
	s_add_u32 m0, s101, 0xe000
	v_mfma_f32_16x16x32_bf16 v[4:7], v[236:239], v[204:207], v[4:7]
	global_load_lds_dwordx4 v[252:253], off
	v_lshl_add_u64 v[252:253], v[252:253], 0, s[34:35]
	s_waitcnt lgkmcnt(0)
	v_mfma_f32_16x16x32_bf16 v[120:123], v[208:211], v[176:179], v[120:123]
	ds_read_b128 v[224:227], v174 offset:8192
	v_mfma_f32_16x16x32_bf16 v[112:115], v[212:215], v[176:179], v[112:115]
	ds_read_b128 v[228:231], v174 offset:10240
	v_mfma_f32_16x16x32_bf16 v[124:127], v[216:219], v[176:179], v[124:127]
	ds_read_b128 v[232:235], v174 offset:12288
	v_mfma_f32_16x16x32_bf16 v[116:119], v[220:223], v[176:179], v[116:119]
	ds_read_b128 v[236:239], v174 offset:14336
	v_mfma_f32_16x16x32_bf16 v[88:91], v[208:211], v[180:183], v[88:91]
	s_add_u32 m0, s100, 0x20000
	v_mfma_f32_16x16x32_bf16 v[80:83], v[212:215], v[180:183], v[80:83]
	global_load_lds_dwordx4 v[240:241], off
	v_lshl_add_u64 v[240:241], v[240:241], 0, s[34:35]
	v_mfma_f32_16x16x32_bf16 v[92:95], v[216:219], v[180:183], v[92:95]
	s_add_u32 m0, s100, 0x22000
	v_mfma_f32_16x16x32_bf16 v[84:87], v[220:223], v[180:183], v[84:87]
	global_load_lds_dwordx4 v[242:243], off
	v_lshl_add_u64 v[242:243], v[242:243], 0, s[34:35]
	v_mfma_f32_16x16x32_bf16 v[56:59], v[208:211], v[184:187], v[56:59]
	s_add_u32 m0, s100, 0x24000
	v_mfma_f32_16x16x32_bf16 v[48:51], v[212:215], v[184:187], v[48:51]
	global_load_lds_dwordx4 v[244:245], off
	v_lshl_add_u64 v[244:245], v[244:245], 0, s[34:35]
	v_mfma_f32_16x16x32_bf16 v[60:63], v[216:219], v[184:187], v[60:63]
	s_add_u32 m0, s100, 0x26000
	v_mfma_f32_16x16x32_bf16 v[52:55], v[220:223], v[184:187], v[52:55]
	global_load_lds_dwordx4 v[246:247], off
	v_lshl_add_u64 v[246:247], v[246:247], 0, s[34:35]
	v_mfma_f32_16x16x32_bf16 v[24:27], v[208:211], v[188:191], v[24:27]
	v_mfma_f32_16x16x32_bf16 v[16:19], v[212:215], v[188:191], v[16:19]
	v_mfma_f32_16x16x32_bf16 v[28:31], v[216:219], v[188:191], v[28:31]
	v_mfma_f32_16x16x32_bf16 v[20:23], v[220:223], v[188:191], v[20:23]
	s_waitcnt lgkmcnt(0)
	v_mfma_f32_16x16x32_bf16 v[104:107], v[224:227], v[176:179], v[104:107]
	ds_read_b128 v[192:195], v173 offset:0
	v_mfma_f32_16x16x32_bf16 v[96:99], v[228:231], v[176:179], v[96:99]
	ds_read_b128 v[196:199], v173 offset:2048
	v_mfma_f32_16x16x32_bf16 v[108:111], v[232:235], v[176:179], v[108:111]
	ds_read_b128 v[200:203], v173 offset:4096
	v_mfma_f32_16x16x32_bf16 v[100:103], v[236:239], v[176:179], v[100:103]
	ds_read_b128 v[204:207], v173 offset:6144
	v_mfma_f32_16x16x32_bf16 v[72:75], v[224:227], v[180:183], v[72:75]
	ds_read_b128 v[208:211], v175 offset:0
	v_mfma_f32_16x16x32_bf16 v[64:67], v[228:231], v[180:183], v[64:67]
	ds_read_b128 v[212:215], v175 offset:2048
	v_mfma_f32_16x16x32_bf16 v[76:79], v[232:235], v[180:183], v[76:79]
	ds_read_b128 v[216:219], v175 offset:4096
	v_mfma_f32_16x16x32_bf16 v[68:71], v[236:239], v[180:183], v[68:71]
	ds_read_b128 v[220:223], v175 offset:6144
	v_mfma_f32_16x16x32_bf16 v[40:43], v[224:227], v[184:187], v[40:43]
	v_mfma_f32_16x16x32_bf16 v[32:35], v[228:231], v[184:187], v[32:35]
	v_mfma_f32_16x16x32_bf16 v[44:47], v[232:235], v[184:187], v[44:47]
	v_mfma_f32_16x16x32_bf16 v[36:39], v[236:239], v[184:187], v[36:39]
	v_mfma_f32_16x16x32_bf16 v[8:11], v[224:227], v[188:191], v[8:11]
	v_mfma_f32_16x16x32_bf16 v[0:3], v[228:231], v[188:191], v[0:3]
	v_mfma_f32_16x16x32_bf16 v[12:15], v[232:235], v[188:191], v[12:15]
	v_mfma_f32_16x16x32_bf16 v[4:7], v[236:239], v[188:191], v[4:7]
	s_waitcnt lgkmcnt(0)
	v_mfma_f32_16x16x32_bf16 v[120:123], v[208:211], v[192:195], v[120:123]
	ds_read_b128 v[224:227], v175 offset:8192
	v_mfma_f32_16x16x32_bf16 v[112:115], v[212:215], v[192:195], v[112:115]
	ds_read_b128 v[228:231], v175 offset:10240
	v_mfma_f32_16x16x32_bf16 v[124:127], v[216:219], v[192:195], v[124:127]
	ds_read_b128 v[232:235], v175 offset:12288
	v_mfma_f32_16x16x32_bf16 v[116:119], v[220:223], v[192:195], v[116:119]
	ds_read_b128 v[236:239], v175 offset:14336
	v_mfma_f32_16x16x32_bf16 v[88:91], v[208:211], v[196:199], v[88:91]
	v_mfma_f32_16x16x32_bf16 v[80:83], v[212:215], v[196:199], v[80:83]
	v_mfma_f32_16x16x32_bf16 v[92:95], v[216:219], v[196:199], v[92:95]
	v_mfma_f32_16x16x32_bf16 v[84:87], v[220:223], v[196:199], v[84:87]
	v_mfma_f32_16x16x32_bf16 v[56:59], v[208:211], v[200:203], v[56:59]
	v_mfma_f32_16x16x32_bf16 v[48:51], v[212:215], v[200:203], v[48:51]
	v_mfma_f32_16x16x32_bf16 v[60:63], v[216:219], v[200:203], v[60:63]
	v_mfma_f32_16x16x32_bf16 v[52:55], v[220:223], v[200:203], v[52:55]
	v_mfma_f32_16x16x32_bf16 v[24:27], v[208:211], v[204:207], v[24:27]
	v_mfma_f32_16x16x32_bf16 v[16:19], v[212:215], v[204:207], v[16:19]
	v_mfma_f32_16x16x32_bf16 v[28:31], v[216:219], v[204:207], v[28:31]
	v_mfma_f32_16x16x32_bf16 v[20:23], v[220:223], v[204:207], v[20:23]
	s_waitcnt lgkmcnt(0)
	s_waitcnt vmcnt(4)
	s_barrier
	s_add_i32 s7, s7, -1
	s_cmp_lg_u32 s7, 0
	s_cbranch_scc1 .Lgemm_p2_loop
	v_mfma_f32_16x16x32_bf16 v[104:107], v[224:227], v[192:195], v[104:107]
	ds_read_b128 v[176:179], v172 offset:32768
	v_mfma_f32_16x16x32_bf16 v[96:99], v[228:231], v[192:195], v[96:99]
	ds_read_b128 v[180:183], v172 offset:34816
	v_mfma_f32_16x16x32_bf16 v[108:111], v[232:235], v[192:195], v[108:111]
	ds_read_b128 v[184:187], v172 offset:36864
	v_mfma_f32_16x16x32_bf16 v[100:103], v[236:239], v[192:195], v[100:103]
	ds_read_b128 v[188:191], v172 offset:38912
	v_mfma_f32_16x16x32_bf16 v[72:75], v[224:227], v[196:199], v[72:75]
	ds_read_b128 v[208:211], v174 offset:32768
	v_mfma_f32_16x16x32_bf16 v[64:67], v[228:231], v[196:199], v[64:67]
	ds_read_b128 v[212:215], v174 offset:34816
	v_mfma_f32_16x16x32_bf16 v[76:79], v[232:235], v[196:199], v[76:79]
	ds_read_b128 v[216:219], v174 offset:36864
	v_mfma_f32_16x16x32_bf16 v[68:71], v[236:239], v[196:199], v[68:71]
	ds_read_b128 v[220:223], v174 offset:38912
	v_mfma_f32_16x16x32_bf16 v[40:43], v[224:227], v[200:203], v[40:43]
	s_mov_b32 m0, s101
	v_mfma_f32_16x16x32_bf16 v[32:35], v[228:231], v[200:203], v[32:35]
	global_load_lds_dwordx4 v[138:139], off
	v_lshl_add_u64 v[138:139], v[138:139], 0, s[34:35]
	v_mfma_f32_16x16x32_bf16 v[44:47], v[232:235], v[200:203], v[44:47]
	s_add_u32 m0, s101, 0x2000
	v_mfma_f32_16x16x32_bf16 v[36:39], v[236:239], v[200:203], v[36:39]
	global_load_lds_dwordx4 v[140:141], off
	v_lshl_add_u64 v[140:141], v[140:141], 0, s[34:35]
	v_mfma_f32_16x16x32_bf16 v[8:11], v[224:227], v[204:207], v[8:11]
	s_add_u32 m0, s101, 0x4000
	v_mfma_f32_16x16x32_bf16 v[0:3], v[228:231], v[204:207], v[0:3]
	global_load_lds_dwordx4 v[250:251], off
	v_lshl_add_u64 v[250:251], v[250:251], 0, s[34:35]
	v_mfma_f32_16x16x32_bf16 v[12:15], v[232:235], v[204:207], v[12:15]
	s_add_u32 m0, s101, 0x6000
	v_mfma_f32_16x16x32_bf16 v[4:7], v[236:239], v[204:207], v[4:7]
	global_load_lds_dwordx4 v[252:253], off
	v_lshl_add_u64 v[252:253], v[252:253], 0, s[34:35]
	s_waitcnt lgkmcnt(0)
	v_mfma_f32_16x16x32_bf16 v[120:123], v[208:211], v[176:179], v[120:123]
	ds_read_b128 v[224:227], v174 offset:40960
	v_mfma_f32_16x16x32_bf16 v[112:115], v[212:215], v[176:179], v[112:115]
	ds_read_b128 v[228:231], v174 offset:43008
	v_mfma_f32_16x16x32_bf16 v[124:127], v[216:219], v[176:179], v[124:127]
	ds_read_b128 v[232:235], v174 offset:45056
	v_mfma_f32_16x16x32_bf16 v[116:119], v[220:223], v[176:179], v[116:119]
	ds_read_b128 v[236:239], v174 offset:47104
	v_mfma_f32_16x16x32_bf16 v[88:91], v[208:211], v[180:183], v[88:91]
	s_mov_b32 m0, s100
	v_mfma_f32_16x16x32_bf16 v[80:83], v[212:215], v[180:183], v[80:83]
	global_load_lds_dwordx4 v[240:241], off
	v_lshl_add_u64 v[240:241], v[240:241], 0, s[34:35]
	v_mfma_f32_16x16x32_bf16 v[92:95], v[216:219], v[180:183], v[92:95]
	s_add_u32 m0, s100, 0x2000
	v_mfma_f32_16x16x32_bf16 v[84:87], v[220:223], v[180:183], v[84:87]
	global_load_lds_dwordx4 v[242:243], off
	v_lshl_add_u64 v[242:243], v[242:243], 0, s[34:35]
	v_mfma_f32_16x16x32_bf16 v[56:59], v[208:211], v[184:187], v[56:59]
	s_add_u32 m0, s100, 0x4000
	v_mfma_f32_16x16x32_bf16 v[48:51], v[212:215], v[184:187], v[48:51]
	global_load_lds_dwordx4 v[244:245], off
	v_lshl_add_u64 v[244:245], v[244:245], 0, s[34:35]
	v_mfma_f32_16x16x32_bf16 v[60:63], v[216:219], v[184:187], v[60:63]
	s_add_u32 m0, s100, 0x6000
	v_mfma_f32_16x16x32_bf16 v[52:55], v[220:223], v[184:187], v[52:55]
	global_load_lds_dwordx4 v[246:247], off
	v_lshl_add_u64 v[246:247], v[246:247], 0, s[34:35]
	v_mfma_f32_16x16x32_bf16 v[24:27], v[208:211], v[188:191], v[24:27]
	v_mfma_f32_16x16x32_bf16 v[16:19], v[212:215], v[188:191], v[16:19]
	v_mfma_f32_16x16x32_bf16 v[28:31], v[216:219], v[188:191], v[28:31]
	v_mfma_f32_16x16x32_bf16 v[20:23], v[220:223], v[188:191], v[20:23]
	s_waitcnt lgkmcnt(0)
	v_mfma_f32_16x16x32_bf16 v[104:107], v[224:227], v[176:179], v[104:107]
	ds_read_b128 v[192:195], v173 offset:32768
	v_mfma_f32_16x16x32_bf16 v[96:99], v[228:231], v[176:179], v[96:99]
	ds_read_b128 v[196:199], v173 offset:34816
	v_mfma_f32_16x16x32_bf16 v[108:111], v[232:235], v[176:179], v[108:111]
	ds_read_b128 v[200:203], v173 offset:36864
	v_mfma_f32_16x16x32_bf16 v[100:103], v[236:239], v[176:179], v[100:103]
	ds_read_b128 v[204:207], v173 offset:38912
	v_mfma_f32_16x16x32_bf16 v[72:75], v[224:227], v[180:183], v[72:75]
	ds_read_b128 v[208:211], v175 offset:32768
	v_mfma_f32_16x16x32_bf16 v[64:67], v[228:231], v[180:183], v[64:67]
	ds_read_b128 v[212:215], v175 offset:34816
	v_mfma_f32_16x16x32_bf16 v[76:79], v[232:235], v[180:183], v[76:79]
	ds_read_b128 v[216:219], v175 offset:36864
	v_mfma_f32_16x16x32_bf16 v[68:71], v[236:239], v[180:183], v[68:71]
	ds_read_b128 v[220:223], v175 offset:38912
	v_mfma_f32_16x16x32_bf16 v[40:43], v[224:227], v[184:187], v[40:43]
	v_mfma_f32_16x16x32_bf16 v[32:35], v[228:231], v[184:187], v[32:35]
	v_mfma_f32_16x16x32_bf16 v[44:47], v[232:235], v[184:187], v[44:47]
	v_mfma_f32_16x16x32_bf16 v[36:39], v[236:239], v[184:187], v[36:39]
	v_mfma_f32_16x16x32_bf16 v[8:11], v[224:227], v[188:191], v[8:11]
	v_mfma_f32_16x16x32_bf16 v[0:3], v[228:231], v[188:191], v[0:3]
	v_mfma_f32_16x16x32_bf16 v[12:15], v[232:235], v[188:191], v[12:15]
	v_mfma_f32_16x16x32_bf16 v[4:7], v[236:239], v[188:191], v[4:7]
	s_waitcnt lgkmcnt(0)
	v_mfma_f32_16x16x32_bf16 v[120:123], v[208:211], v[192:195], v[120:123]
	ds_read_b128 v[224:227], v175 offset:40960
	v_mfma_f32_16x16x32_bf16 v[112:115], v[212:215], v[192:195], v[112:115]
	ds_read_b128 v[228:231], v175 offset:43008
	v_mfma_f32_16x16x32_bf16 v[124:127], v[216:219], v[192:195], v[124:127]
	ds_read_b128 v[232:235], v175 offset:45056
	v_mfma_f32_16x16x32_bf16 v[116:119], v[220:223], v[192:195], v[116:119]
	ds_read_b128 v[236:239], v175 offset:47104
	v_mfma_f32_16x16x32_bf16 v[88:91], v[208:211], v[196:199], v[88:91]
	v_mfma_f32_16x16x32_bf16 v[80:83], v[212:215], v[196:199], v[80:83]
	v_mfma_f32_16x16x32_bf16 v[92:95], v[216:219], v[196:199], v[92:95]
	v_mfma_f32_16x16x32_bf16 v[84:87], v[220:223], v[196:199], v[84:87]
	v_mfma_f32_16x16x32_bf16 v[56:59], v[208:211], v[200:203], v[56:59]
	v_mfma_f32_16x16x32_bf16 v[48:51], v[212:215], v[200:203], v[48:51]
	v_mfma_f32_16x16x32_bf16 v[60:63], v[216:219], v[200:203], v[60:63]
	v_mfma_f32_16x16x32_bf16 v[52:55], v[220:223], v[200:203], v[52:55]
	v_mfma_f32_16x16x32_bf16 v[24:27], v[208:211], v[204:207], v[24:27]
	v_mfma_f32_16x16x32_bf16 v[16:19], v[212:215], v[204:207], v[16:19]
	v_mfma_f32_16x16x32_bf16 v[28:31], v[216:219], v[204:207], v[28:31]
	v_mfma_f32_16x16x32_bf16 v[20:23], v[220:223], v[204:207], v[20:23]
	s_waitcnt lgkmcnt(0)
	s_waitcnt vmcnt(4)
	s_barrier
	v_mfma_f32_16x16x32_bf16 v[104:107], v[224:227], v[192:195], v[104:107]
	ds_read_b128 v[176:179], v254 offset:0
	v_mfma_f32_16x16x32_bf16 v[96:99], v[228:231], v[192:195], v[96:99]
	ds_read_b128 v[180:183], v254 offset:2048
	v_mfma_f32_16x16x32_bf16 v[108:111], v[232:235], v[192:195], v[108:111]
	ds_read_b128 v[184:187], v254 offset:4096
	v_mfma_f32_16x16x32_bf16 v[100:103], v[236:239], v[192:195], v[100:103]
	ds_read_b128 v[188:191], v254 offset:6144
	v_mfma_f32_16x16x32_bf16 v[72:75], v[224:227], v[196:199], v[72:75]
	ds_read_b128 v[208:211], v174 offset:0
	v_mfma_f32_16x16x32_bf16 v[64:67], v[228:231], v[196:199], v[64:67]
	ds_read_b128 v[212:215], v174 offset:2048
	v_mfma_f32_16x16x32_bf16 v[76:79], v[232:235], v[196:199], v[76:79]
	ds_read_b128 v[216:219], v174 offset:4096
	v_mfma_f32_16x16x32_bf16 v[68:71], v[236:239], v[196:199], v[68:71]
	ds_read_b128 v[220:223], v174 offset:6144
	v_mfma_f32_16x16x32_bf16 v[40:43], v[224:227], v[200:203], v[40:43]
	s_add_u32 m0, s101, 0x8000
	v_mfma_f32_16x16x32_bf16 v[32:35], v[228:231], v[200:203], v[32:35]
	global_load_lds_dwordx4 v[138:139], off
	v_lshl_add_u64 v[138:139], v[138:139], 0, s[34:35]
	v_mfma_f32_16x16x32_bf16 v[44:47], v[232:235], v[200:203], v[44:47]
	s_add_u32 m0, s101, 0xa000
	v_mfma_f32_16x16x32_bf16 v[36:39], v[236:239], v[200:203], v[36:39]
	global_load_lds_dwordx4 v[140:141], off
	v_lshl_add_u64 v[140:141], v[140:141], 0, s[34:35]
	v_mfma_f32_16x16x32_bf16 v[8:11], v[224:227], v[204:207], v[8:11]
	s_add_u32 m0, s101, 0xc000
	v_mfma_f32_16x16x32_bf16 v[0:3], v[228:231], v[204:207], v[0:3]
	global_load_lds_dwordx4 v[250:251], off
	v_lshl_add_u64 v[250:251], v[250:251], 0, s[34:35]
	v_mfma_f32_16x16x32_bf16 v[12:15], v[232:235], v[204:207], v[12:15]
	s_add_u32 m0, s101, 0xe000
	v_mfma_f32_16x16x32_bf16 v[4:7], v[236:239], v[204:207], v[4:7]
	global_load_lds_dwordx4 v[252:253], off
	v_lshl_add_u64 v[252:253], v[252:253], 0, s[34:35]
	s_waitcnt lgkmcnt(0)
	v_mfma_f32_16x16x32_bf16 v[120:123], v[208:211], v[176:179], v[120:123]
	ds_read_b128 v[224:227], v174 offset:8192
	v_mfma_f32_16x16x32_bf16 v[112:115], v[212:215], v[176:179], v[112:115]
	ds_read_b128 v[228:231], v174 offset:10240
	v_mfma_f32_16x16x32_bf16 v[124:127], v[216:219], v[176:179], v[124:127]
	ds_read_b128 v[232:235], v174 offset:12288
	v_mfma_f32_16x16x32_bf16 v[116:119], v[220:223], v[176:179], v[116:119]
	ds_read_b128 v[236:239], v174 offset:14336
	v_mfma_f32_16x16x32_bf16 v[88:91], v[208:211], v[180:183], v[88:91]
	v_mfma_f32_16x16x32_bf16 v[80:83], v[212:215], v[180:183], v[80:83]
	v_mfma_f32_16x16x32_bf16 v[92:95], v[216:219], v[180:183], v[92:95]
	v_mfma_f32_16x16x32_bf16 v[84:87], v[220:223], v[180:183], v[84:87]
	v_mfma_f32_16x16x32_bf16 v[56:59], v[208:211], v[184:187], v[56:59]
	v_mfma_f32_16x16x32_bf16 v[48:51], v[212:215], v[184:187], v[48:51]
	v_mfma_f32_16x16x32_bf16 v[60:63], v[216:219], v[184:187], v[60:63]
	v_mfma_f32_16x16x32_bf16 v[52:55], v[220:223], v[184:187], v[52:55]
	v_mfma_f32_16x16x32_bf16 v[24:27], v[208:211], v[188:191], v[24:27]
	v_mfma_f32_16x16x32_bf16 v[16:19], v[212:215], v[188:191], v[16:19]
	v_mfma_f32_16x16x32_bf16 v[28:31], v[216:219], v[188:191], v[28:31]
	v_mfma_f32_16x16x32_bf16 v[20:23], v[220:223], v[188:191], v[20:23]
	s_waitcnt lgkmcnt(0)
	v_mfma_f32_16x16x32_bf16 v[104:107], v[224:227], v[176:179], v[104:107]
	ds_read_b128 v[192:195], v255 offset:0
	v_mfma_f32_16x16x32_bf16 v[96:99], v[228:231], v[176:179], v[96:99]
	ds_read_b128 v[196:199], v255 offset:2048
	v_mfma_f32_16x16x32_bf16 v[108:111], v[232:235], v[176:179], v[108:111]
	ds_read_b128 v[200:203], v255 offset:4096
	v_mfma_f32_16x16x32_bf16 v[100:103], v[236:239], v[176:179], v[100:103]
	ds_read_b128 v[204:207], v255 offset:6144
	v_mfma_f32_16x16x32_bf16 v[72:75], v[224:227], v[180:183], v[72:75]
	ds_read_b128 v[208:211], v175 offset:0
	v_mfma_f32_16x16x32_bf16 v[64:67], v[228:231], v[180:183], v[64:67]
	ds_read_b128 v[212:215], v175 offset:2048
	v_mfma_f32_16x16x32_bf16 v[76:79], v[232:235], v[180:183], v[76:79]
	ds_read_b128 v[216:219], v175 offset:4096
	v_mfma_f32_16x16x32_bf16 v[68:71], v[236:239], v[180:183], v[68:71]
	ds_read_b128 v[220:223], v175 offset:6144
	v_mfma_f32_16x16x32_bf16 v[40:43], v[224:227], v[184:187], v[40:43]
	v_mfma_f32_16x16x32_bf16 v[32:35], v[228:231], v[184:187], v[32:35]
	v_mfma_f32_16x16x32_bf16 v[44:47], v[232:235], v[184:187], v[44:47]
	v_mfma_f32_16x16x32_bf16 v[36:39], v[236:239], v[184:187], v[36:39]
	v_mfma_f32_16x16x32_bf16 v[8:11], v[224:227], v[188:191], v[8:11]
	v_mfma_f32_16x16x32_bf16 v[0:3], v[228:231], v[188:191], v[0:3]
	v_mfma_f32_16x16x32_bf16 v[12:15], v[232:235], v[188:191], v[12:15]
	v_mfma_f32_16x16x32_bf16 v[4:7], v[236:239], v[188:191], v[4:7]
	s_waitcnt lgkmcnt(0)
	v_mfma_f32_16x16x32_bf16 v[120:123], v[208:211], v[192:195], v[120:123]
	ds_read_b128 v[224:227], v175 offset:8192
	v_mfma_f32_16x16x32_bf16 v[112:115], v[212:215], v[192:195], v[112:115]
	ds_read_b128 v[228:231], v175 offset:10240
	v_mfma_f32_16x16x32_bf16 v[124:127], v[216:219], v[192:195], v[124:127]
	ds_read_b128 v[232:235], v175 offset:12288
	v_mfma_f32_16x16x32_bf16 v[116:119], v[220:223], v[192:195], v[116:119]
	ds_read_b128 v[236:239], v175 offset:14336
	v_mfma_f32_16x16x32_bf16 v[88:91], v[208:211], v[196:199], v[88:91]
	v_mfma_f32_16x16x32_bf16 v[80:83], v[212:215], v[196:199], v[80:83]
	v_mfma_f32_16x16x32_bf16 v[92:95], v[216:219], v[196:199], v[92:95]
	v_mfma_f32_16x16x32_bf16 v[84:87], v[220:223], v[196:199], v[84:87]
	v_mfma_f32_16x16x32_bf16 v[56:59], v[208:211], v[200:203], v[56:59]
	v_mfma_f32_16x16x32_bf16 v[48:51], v[212:215], v[200:203], v[48:51]
	v_mfma_f32_16x16x32_bf16 v[60:63], v[216:219], v[200:203], v[60:63]
	v_mfma_f32_16x16x32_bf16 v[52:55], v[220:223], v[200:203], v[52:55]
	v_mfma_f32_16x16x32_bf16 v[24:27], v[208:211], v[204:207], v[24:27]
	v_mfma_f32_16x16x32_bf16 v[16:19], v[212:215], v[204:207], v[16:19]
	v_mfma_f32_16x16x32_bf16 v[28:31], v[216:219], v[204:207], v[28:31]
	v_mfma_f32_16x16x32_bf16 v[20:23], v[220:223], v[204:207], v[20:23]
	s_waitcnt lgkmcnt(0)
	s_waitcnt vmcnt(0)
	s_barrier
	v_mfma_f32_16x16x32_bf16 v[104:107], v[224:227], v[192:195], v[104:107]
	ds_read_b128 v[176:179], v172 offset:0
	v_mfma_f32_16x16x32_bf16 v[96:99], v[228:231], v[192:195], v[96:99]
	ds_read_b128 v[180:183], v172 offset:2048
	v_mfma_f32_16x16x32_bf16 v[108:111], v[232:235], v[192:195], v[108:111]
	ds_read_b128 v[184:187], v172 offset:4096
	v_mfma_f32_16x16x32_bf16 v[100:103], v[236:239], v[192:195], v[100:103]
	ds_read_b128 v[188:191], v172 offset:6144
	v_mfma_f32_16x16x32_bf16 v[72:75], v[224:227], v[196:199], v[72:75]
	ds_read_b128 v[208:211], v174 offset:32768
	v_mfma_f32_16x16x32_bf16 v[64:67], v[228:231], v[196:199], v[64:67]
	ds_read_b128 v[212:215], v174 offset:34816
	v_mfma_f32_16x16x32_bf16 v[76:79], v[232:235], v[196:199], v[76:79]
	ds_read_b128 v[216:219], v174 offset:36864
	v_mfma_f32_16x16x32_bf16 v[68:71], v[236:239], v[196:199], v[68:71]
	ds_read_b128 v[220:223], v174 offset:38912
	v_mfma_f32_16x16x32_bf16 v[40:43], v[224:227], v[200:203], v[40:43]
	v_mfma_f32_16x16x32_bf16 v[32:35], v[228:231], v[200:203], v[32:35]
	v_mfma_f32_16x16x32_bf16 v[44:47], v[232:235], v[200:203], v[44:47]
	v_mfma_f32_16x16x32_bf16 v[36:39], v[236:239], v[200:203], v[36:39]
	v_mfma_f32_16x16x32_bf16 v[8:11], v[224:227], v[204:207], v[8:11]
	v_mfma_f32_16x16x32_bf16 v[0:3], v[228:231], v[204:207], v[0:3]
	v_mfma_f32_16x16x32_bf16 v[12:15], v[232:235], v[204:207], v[12:15]
	v_mfma_f32_16x16x32_bf16 v[4:7], v[236:239], v[204:207], v[4:7]
	s_waitcnt lgkmcnt(0)
	v_mfma_f32_16x16x32_bf16 v[120:123], v[208:211], v[176:179], v[120:123]
	ds_read_b128 v[224:227], v174 offset:40960
	v_mfma_f32_16x16x32_bf16 v[112:115], v[212:215], v[176:179], v[112:115]
	ds_read_b128 v[228:231], v174 offset:43008
	v_mfma_f32_16x16x32_bf16 v[124:127], v[216:219], v[176:179], v[124:127]
	ds_read_b128 v[232:235], v174 offset:45056
	v_mfma_f32_16x16x32_bf16 v[116:119], v[220:223], v[176:179], v[116:119]
	ds_read_b128 v[236:239], v174 offset:47104
	v_mfma_f32_16x16x32_bf16 v[88:91], v[208:211], v[180:183], v[88:91]
	v_mfma_f32_16x16x32_bf16 v[80:83], v[212:215], v[180:183], v[80:83]
	v_mfma_f32_16x16x32_bf16 v[92:95], v[216:219], v[180:183], v[92:95]
	v_mfma_f32_16x16x32_bf16 v[84:87], v[220:223], v[180:183], v[84:87]
	v_mfma_f32_16x16x32_bf16 v[56:59], v[208:211], v[184:187], v[56:59]
	v_mfma_f32_16x16x32_bf16 v[48:51], v[212:215], v[184:187], v[48:51]
	v_mfma_f32_16x16x32_bf16 v[60:63], v[216:219], v[184:187], v[60:63]
	v_mfma_f32_16x16x32_bf16 v[52:55], v[220:223], v[184:187], v[52:55]
	v_mfma_f32_16x16x32_bf16 v[24:27], v[208:211], v[188:191], v[24:27]
	v_mfma_f32_16x16x32_bf16 v[16:19], v[212:215], v[188:191], v[16:19]
	v_mfma_f32_16x16x32_bf16 v[28:31], v[216:219], v[188:191], v[28:31]
	v_mfma_f32_16x16x32_bf16 v[20:23], v[220:223], v[188:191], v[20:23]
	s_waitcnt lgkmcnt(0)
	v_mfma_f32_16x16x32_bf16 v[104:107], v[224:227], v[176:179], v[104:107]
	ds_read_b128 v[192:195], v173 offset:0
	v_mfma_f32_16x16x32_bf16 v[96:99], v[228:231], v[176:179], v[96:99]
	ds_read_b128 v[196:199], v173 offset:2048
	v_mfma_f32_16x16x32_bf16 v[108:111], v[232:235], v[176:179], v[108:111]
	ds_read_b128 v[200:203], v173 offset:4096
	v_mfma_f32_16x16x32_bf16 v[100:103], v[236:239], v[176:179], v[100:103]
	ds_read_b128 v[204:207], v173 offset:6144
	v_mfma_f32_16x16x32_bf16 v[72:75], v[224:227], v[180:183], v[72:75]
	ds_read_b128 v[208:211], v175 offset:32768
	v_mfma_f32_16x16x32_bf16 v[64:67], v[228:231], v[180:183], v[64:67]
	ds_read_b128 v[212:215], v175 offset:34816
	v_mfma_f32_16x16x32_bf16 v[76:79], v[232:235], v[180:183], v[76:79]
	ds_read_b128 v[216:219], v175 offset:36864
	v_mfma_f32_16x16x32_bf16 v[68:71], v[236:239], v[180:183], v[68:71]
	ds_read_b128 v[220:223], v175 offset:38912
	v_mfma_f32_16x16x32_bf16 v[40:43], v[224:227], v[184:187], v[40:43]
	v_mfma_f32_16x16x32_bf16 v[32:35], v[228:231], v[184:187], v[32:35]
	v_mfma_f32_16x16x32_bf16 v[44:47], v[232:235], v[184:187], v[44:47]
	v_mfma_f32_16x16x32_bf16 v[36:39], v[236:239], v[184:187], v[36:39]
	v_mfma_f32_16x16x32_bf16 v[8:11], v[224:227], v[188:191], v[8:11]
	v_mfma_f32_16x16x32_bf16 v[0:3], v[228:231], v[188:191], v[0:3]
	v_mfma_f32_16x16x32_bf16 v[12:15], v[232:235], v[188:191], v[12:15]
	v_mfma_f32_16x16x32_bf16 v[4:7], v[236:239], v[188:191], v[4:7]
	s_waitcnt lgkmcnt(0)
	v_mfma_f32_16x16x32_bf16 v[120:123], v[208:211], v[192:195], v[120:123]
	ds_read_b128 v[224:227], v175 offset:40960
	v_mfma_f32_16x16x32_bf16 v[112:115], v[212:215], v[192:195], v[112:115]
	ds_read_b128 v[228:231], v175 offset:43008
	v_mfma_f32_16x16x32_bf16 v[124:127], v[216:219], v[192:195], v[124:127]
	ds_read_b128 v[232:235], v175 offset:45056
	v_mfma_f32_16x16x32_bf16 v[116:119], v[220:223], v[192:195], v[116:119]
	ds_read_b128 v[236:239], v175 offset:47104
	v_mfma_f32_16x16x32_bf16 v[88:91], v[208:211], v[196:199], v[88:91]
	v_mfma_f32_16x16x32_bf16 v[80:83], v[212:215], v[196:199], v[80:83]
	v_mfma_f32_16x16x32_bf16 v[92:95], v[216:219], v[196:199], v[92:95]
	v_mfma_f32_16x16x32_bf16 v[84:87], v[220:223], v[196:199], v[84:87]
	v_mfma_f32_16x16x32_bf16 v[56:59], v[208:211], v[200:203], v[56:59]
	v_mfma_f32_16x16x32_bf16 v[48:51], v[212:215], v[200:203], v[48:51]
	v_mfma_f32_16x16x32_bf16 v[60:63], v[216:219], v[200:203], v[60:63]
	v_mfma_f32_16x16x32_bf16 v[52:55], v[220:223], v[200:203], v[52:55]
	v_mfma_f32_16x16x32_bf16 v[24:27], v[208:211], v[204:207], v[24:27]
	v_mfma_f32_16x16x32_bf16 v[16:19], v[212:215], v[204:207], v[16:19]
	v_mfma_f32_16x16x32_bf16 v[28:31], v[216:219], v[204:207], v[28:31]
	v_mfma_f32_16x16x32_bf16 v[20:23], v[220:223], v[204:207], v[20:23]
	s_waitcnt lgkmcnt(0)
	s_barrier
	v_mfma_f32_16x16x32_bf16 v[104:107], v[224:227], v[192:195], v[104:107]
	v_mfma_f32_16x16x32_bf16 v[96:99], v[228:231], v[192:195], v[96:99]
	v_mfma_f32_16x16x32_bf16 v[108:111], v[232:235], v[192:195], v[108:111]
	v_mfma_f32_16x16x32_bf16 v[100:103], v[236:239], v[192:195], v[100:103]
	v_mfma_f32_16x16x32_bf16 v[72:75], v[224:227], v[196:199], v[72:75]
	v_mfma_f32_16x16x32_bf16 v[64:67], v[228:231], v[196:199], v[64:67]
	v_mfma_f32_16x16x32_bf16 v[76:79], v[232:235], v[196:199], v[76:79]
	v_mfma_f32_16x16x32_bf16 v[68:71], v[236:239], v[196:199], v[68:71]
	v_mfma_f32_16x16x32_bf16 v[40:43], v[224:227], v[200:203], v[40:43]
	v_mfma_f32_16x16x32_bf16 v[32:35], v[228:231], v[200:203], v[32:35]
	v_mfma_f32_16x16x32_bf16 v[44:47], v[232:235], v[200:203], v[44:47]
	v_mfma_f32_16x16x32_bf16 v[36:39], v[236:239], v[200:203], v[36:39]
	v_mfma_f32_16x16x32_bf16 v[8:11], v[224:227], v[204:207], v[8:11]
	v_mfma_f32_16x16x32_bf16 v[0:3], v[228:231], v[204:207], v[0:3]
	v_mfma_f32_16x16x32_bf16 v[12:15], v[232:235], v[204:207], v[12:15]
	v_mfma_f32_16x16x32_bf16 v[4:7], v[236:239], v[204:207], v[4:7]
	s_nop 7
	s_nop 3
	s_branch .LBB0_115

.LBB0_1106:
	v_add_u32_e32 v172, v153, v170
	v_add_u32_e32 v173, v153, v171
	v_add_u32_e32 v174, v169, v170
	v_add_u32_e32 v175, v169, v171
	s_mov_b64 s[100:101], 0x80
	v_lshl_add_u64 v[240:241], v[128:129], 0, s[100:101]
	s_mov_b64 s[100:101], 0x6c080
	v_lshl_add_u64 v[242:243], v[128:129], 0, s[100:101]
	s_mov_b64 s[100:101], 0xd8080
	v_lshl_add_u64 v[244:245], v[128:129], 0, s[100:101]
	s_mov_b64 s[100:101], 0x144080
	v_lshl_add_u64 v[246:247], v[128:129], 0, s[100:101]
	s_mov_b64 s[100:101], 0x80
	v_lshl_add_u64 v[138:139], v[130:131], 0, s[100:101]
	s_mov_b64 s[100:101], 0x20080
	v_lshl_add_u64 v[140:141], v[130:131], 0, s[100:101]
	s_mov_b64 s[100:101], 0x40080
	v_lshl_add_u64 v[250:251], v[130:131], 0, s[100:101]
	s_mov_b64 s[100:101], 0x60080
	v_lshl_add_u64 v[252:253], v[130:131], 0, s[100:101]
	v_readfirstlane_b32 s100, v144
	v_readfirstlane_b32 s101, v145
	v_add_u32_e32 v254, 0x20000, v172
	v_add_u32_e32 v255, 0x20000, v173
	s_nop 3
	ds_read_b128 v[176:179], v172 offset:0
	ds_read_b128 v[180:183], v172 offset:2048
	ds_read_b128 v[184:187], v172 offset:4096
	ds_read_b128 v[188:191], v172 offset:6144
	ds_read_b128 v[208:211], v174 offset:0
	ds_read_b128 v[212:215], v174 offset:2048
	ds_read_b128 v[216:219], v174 offset:4096
	ds_read_b128 v[220:223], v174 offset:6144
	s_add_u32 m0, s100, 0x8000
	s_nop 0
	global_load_lds_dwordx4 v[240:241], off
	v_lshl_add_u64 v[240:241], v[240:241], 0, s[34:35]
	s_add_u32 m0, s100, 0xa000
	s_nop 0
	global_load_lds_dwordx4 v[242:243], off
	v_lshl_add_u64 v[242:243], v[242:243], 0, s[34:35]
	s_add_u32 m0, s100, 0xc000
	s_nop 0
	global_load_lds_dwordx4 v[244:245], off
	v_lshl_add_u64 v[244:245], v[244:245], 0, s[34:35]
	s_add_u32 m0, s100, 0xe000
	s_nop 0
	global_load_lds_dwordx4 v[246:247], off
	v_lshl_add_u64 v[246:247], v[246:247], 0, s[34:35]
	s_add_u32 m0, s101, 0x8000
	s_nop 0
	global_load_lds_dwordx4 v[138:139], off
	v_lshl_add_u64 v[138:139], v[138:139], 0, s[34:35]
	s_add_u32 m0, s101, 0xa000
	s_nop 0
	global_load_lds_dwordx4 v[140:141], off
	v_lshl_add_u64 v[140:141], v[140:141], 0, s[34:35]
	s_add_u32 m0, s101, 0xc000
	s_nop 0
	global_load_lds_dwordx4 v[250:251], off
	v_lshl_add_u64 v[250:251], v[250:251], 0, s[34:35]
	s_add_u32 m0, s101, 0xe000
	s_nop 0
	global_load_lds_dwordx4 v[252:253], off
	v_lshl_add_u64 v[252:253], v[252:253], 0, s[34:35]
	s_waitcnt lgkmcnt(0)
	v_mfma_f32_16x16x32_bf16 v[124:127], v[208:211], v[176:179], v[124:127]
	ds_read_b128 v[224:227], v174 offset:8192
	v_mfma_f32_16x16x32_bf16 v[120:123], v[212:215], v[176:179], v[120:123]
	ds_read_b128 v[228:231], v174 offset:10240
	v_mfma_f32_16x16x32_bf16 v[116:119], v[216:219], v[176:179], v[116:119]
	ds_read_b128 v[232:235], v174 offset:12288
	v_mfma_f32_16x16x32_bf16 v[112:115], v[220:223], v[176:179], v[112:115]
	ds_read_b128 v[236:239], v174 offset:14336
	v_mfma_f32_16x16x32_bf16 v[92:95], v[208:211], v[180:183], v[92:95]
	s_add_u32 m0, s100, 0x20000
	v_mfma_f32_16x16x32_bf16 v[88:91], v[212:215], v[180:183], v[88:91]
	global_load_lds_dwordx4 v[240:241], off
	v_lshl_add_u64 v[240:241], v[240:241], 0, s[34:35]
	v_mfma_f32_16x16x32_bf16 v[84:87], v[216:219], v[180:183], v[84:87]
	s_add_u32 m0, s100, 0x22000
	v_mfma_f32_16x16x32_bf16 v[80:83], v[220:223], v[180:183], v[80:83]
	global_load_lds_dwordx4 v[242:243], off
	v_lshl_add_u64 v[242:243], v[242:243], 0, s[34:35]
	v_mfma_f32_16x16x32_bf16 v[60:63], v[208:211], v[184:187], v[60:63]
	s_add_u32 m0, s100, 0x24000
	v_mfma_f32_16x16x32_bf16 v[56:59], v[212:215], v[184:187], v[56:59]
	global_load_lds_dwordx4 v[244:245], off
	v_lshl_add_u64 v[244:245], v[244:245], 0, s[34:35]
	v_mfma_f32_16x16x32_bf16 v[52:55], v[216:219], v[184:187], v[52:55]
	s_add_u32 m0, s100, 0x26000
	v_mfma_f32_16x16x32_bf16 v[48:51], v[220:223], v[184:187], v[48:51]
	global_load_lds_dwordx4 v[246:247], off
	v_lshl_add_u64 v[246:247], v[246:247], 0, s[34:35]
	v_mfma_f32_16x16x32_bf16 v[28:31], v[208:211], v[188:191], v[28:31]
	v_mfma_f32_16x16x32_bf16 v[24:27], v[212:215], v[188:191], v[24:27]
	v_mfma_f32_16x16x32_bf16 v[20:23], v[216:219], v[188:191], v[20:23]
	v_mfma_f32_16x16x32_bf16 v[16:19], v[220:223], v[188:191], v[16:19]
	s_waitcnt lgkmcnt(0)
	v_mfma_f32_16x16x32_bf16 v[108:111], v[224:227], v[176:179], v[108:111]
	ds_read_b128 v[192:195], v173 offset:0
	v_mfma_f32_16x16x32_bf16 v[104:107], v[228:231], v[176:179], v[104:107]
	ds_read_b128 v[196:199], v173 offset:2048
	v_mfma_f32_16x16x32_bf16 v[100:103], v[232:235], v[176:179], v[100:103]
	ds_read_b128 v[200:203], v173 offset:4096
	v_mfma_f32_16x16x32_bf16 v[96:99], v[236:239], v[176:179], v[96:99]
	ds_read_b128 v[204:207], v173 offset:6144
	v_mfma_f32_16x16x32_bf16 v[76:79], v[224:227], v[180:183], v[76:79]
	ds_read_b128 v[208:211], v175 offset:0
	v_mfma_f32_16x16x32_bf16 v[72:75], v[228:231], v[180:183], v[72:75]
	ds_read_b128 v[212:215], v175 offset:2048
	v_mfma_f32_16x16x32_bf16 v[68:71], v[232:235], v[180:183], v[68:71]
	ds_read_b128 v[216:219], v175 offset:4096
	v_mfma_f32_16x16x32_bf16 v[64:67], v[236:239], v[180:183], v[64:67]
	ds_read_b128 v[220:223], v175 offset:6144
	v_mfma_f32_16x16x32_bf16 v[44:47], v[224:227], v[184:187], v[44:47]
	v_mfma_f32_16x16x32_bf16 v[40:43], v[228:231], v[184:187], v[40:43]
	v_mfma_f32_16x16x32_bf16 v[36:39], v[232:235], v[184:187], v[36:39]
	v_mfma_f32_16x16x32_bf16 v[32:35], v[236:239], v[184:187], v[32:35]
	v_mfma_f32_16x16x32_bf16 v[12:15], v[224:227], v[188:191], v[12:15]
	v_mfma_f32_16x16x32_bf16 v[8:11], v[228:231], v[188:191], v[8:11]
	v_mfma_f32_16x16x32_bf16 v[4:7], v[232:235], v[188:191], v[4:7]
	v_mfma_f32_16x16x32_bf16 v[0:3], v[236:239], v[188:191], v[0:3]
	s_waitcnt lgkmcnt(0)
	v_mfma_f32_16x16x32_bf16 v[124:127], v[208:211], v[192:195], v[124:127]
	ds_read_b128 v[224:227], v175 offset:8192
	v_mfma_f32_16x16x32_bf16 v[120:123], v[212:215], v[192:195], v[120:123]
	ds_read_b128 v[228:231], v175 offset:10240
	v_mfma_f32_16x16x32_bf16 v[116:119], v[216:219], v[192:195], v[116:119]
	ds_read_b128 v[232:235], v175 offset:12288
	v_mfma_f32_16x16x32_bf16 v[112:115], v[220:223], v[192:195], v[112:115]
	ds_read_b128 v[236:239], v175 offset:14336
	v_mfma_f32_16x16x32_bf16 v[92:95], v[208:211], v[196:199], v[92:95]
	v_mfma_f32_16x16x32_bf16 v[88:91], v[212:215], v[196:199], v[88:91]
	v_mfma_f32_16x16x32_bf16 v[84:87], v[216:219], v[196:199], v[84:87]
	v_mfma_f32_16x16x32_bf16 v[80:83], v[220:223], v[196:199], v[80:83]
	v_mfma_f32_16x16x32_bf16 v[60:63], v[208:211], v[200:203], v[60:63]
	v_mfma_f32_16x16x32_bf16 v[56:59], v[212:215], v[200:203], v[56:59]
	v_mfma_f32_16x16x32_bf16 v[52:55], v[216:219], v[200:203], v[52:55]
	v_mfma_f32_16x16x32_bf16 v[48:51], v[220:223], v[200:203], v[48:51]
	v_mfma_f32_16x16x32_bf16 v[28:31], v[208:211], v[204:207], v[28:31]
	v_mfma_f32_16x16x32_bf16 v[24:27], v[212:215], v[204:207], v[24:27]
	v_mfma_f32_16x16x32_bf16 v[20:23], v[216:219], v[204:207], v[20:23]
	v_mfma_f32_16x16x32_bf16 v[16:19], v[220:223], v[204:207], v[16:19]
	s_waitcnt lgkmcnt(0)
	s_waitcnt vmcnt(4)
	s_barrier
	s_mov_b32 s46, 2
.Lgemm_p7_loop:
	v_mfma_f32_16x16x32_bf16 v[108:111], v[224:227], v[192:195], v[108:111]
	ds_read_b128 v[176:179], v172 offset:32768
	v_mfma_f32_16x16x32_bf16 v[104:107], v[228:231], v[192:195], v[104:107]
	ds_read_b128 v[180:183], v172 offset:34816
	v_mfma_f32_16x16x32_bf16 v[100:103], v[232:235], v[192:195], v[100:103]
	ds_read_b128 v[184:187], v172 offset:36864
	v_mfma_f32_16x16x32_bf16 v[96:99], v[236:239], v[192:195], v[96:99]
	ds_read_b128 v[188:191], v172 offset:38912
	v_mfma_f32_16x16x32_bf16 v[76:79], v[224:227], v[196:199], v[76:79]
	ds_read_b128 v[208:211], v174 offset:32768
	v_mfma_f32_16x16x32_bf16 v[72:75], v[228:231], v[196:199], v[72:75]
	ds_read_b128 v[212:215], v174 offset:34816
	v_mfma_f32_16x16x32_bf16 v[68:71], v[232:235], v[196:199], v[68:71]
	ds_read_b128 v[216:219], v174 offset:36864
	v_mfma_f32_16x16x32_bf16 v[64:67], v[236:239], v[196:199], v[64:67]
	ds_read_b128 v[220:223], v174 offset:38912
	v_mfma_f32_16x16x32_bf16 v[44:47], v[224:227], v[200:203], v[44:47]
	s_mov_b32 m0, s101
	v_mfma_f32_16x16x32_bf16 v[40:43], v[228:231], v[200:203], v[40:43]
	global_load_lds_dwordx4 v[138:139], off
	v_lshl_add_u64 v[138:139], v[138:139], 0, s[34:35]
	v_mfma_f32_16x16x32_bf16 v[36:39], v[232:235], v[200:203], v[36:39]
	s_add_u32 m0, s101, 0x2000
	v_mfma_f32_16x16x32_bf16 v[32:35], v[236:239], v[200:203], v[32:35]
	global_load_lds_dwordx4 v[140:141], off
	v_lshl_add_u64 v[140:141], v[140:141], 0, s[34:35]
	v_mfma_f32_16x16x32_bf16 v[12:15], v[224:227], v[204:207], v[12:15]
	s_add_u32 m0, s101, 0x4000
	v_mfma_f32_16x16x32_bf16 v[8:11], v[228:231], v[204:207], v[8:11]
	global_load_lds_dwordx4 v[250:251], off
	v_lshl_add_u64 v[250:251], v[250:251], 0, s[34:35]
	v_mfma_f32_16x16x32_bf16 v[4:7], v[232:235], v[204:207], v[4:7]
	s_add_u32 m0, s101, 0x6000
	v_mfma_f32_16x16x32_bf16 v[0:3], v[236:239], v[204:207], v[0:3]
	global_load_lds_dwordx4 v[252:253], off
	v_lshl_add_u64 v[252:253], v[252:253], 0, s[34:35]
	s_waitcnt lgkmcnt(0)
	v_mfma_f32_16x16x32_bf16 v[124:127], v[208:211], v[176:179], v[124:127]
	ds_read_b128 v[224:227], v174 offset:40960
	v_mfma_f32_16x16x32_bf16 v[120:123], v[212:215], v[176:179], v[120:123]
	ds_read_b128 v[228:231], v174 offset:43008
	v_mfma_f32_16x16x32_bf16 v[116:119], v[216:219], v[176:179], v[116:119]
	ds_read_b128 v[232:235], v174 offset:45056
	v_mfma_f32_16x16x32_bf16 v[112:115], v[220:223], v[176:179], v[112:115]
	ds_read_b128 v[236:239], v174 offset:47104
	v_mfma_f32_16x16x32_bf16 v[92:95], v[208:211], v[180:183], v[92:95]
	s_mov_b32 m0, s100
	v_mfma_f32_16x16x32_bf16 v[88:91], v[212:215], v[180:183], v[88:91]
	global_load_lds_dwordx4 v[240:241], off
	v_lshl_add_u64 v[240:241], v[240:241], 0, s[34:35]
	v_mfma_f32_16x16x32_bf16 v[84:87], v[216:219], v[180:183], v[84:87]
	s_add_u32 m0, s100, 0x2000
	v_mfma_f32_16x16x32_bf16 v[80:83], v[220:223], v[180:183], v[80:83]
	global_load_lds_dwordx4 v[242:243], off
	v_lshl_add_u64 v[242:243], v[242:243], 0, s[34:35]
	v_mfma_f32_16x16x32_bf16 v[60:63], v[208:211], v[184:187], v[60:63]
	s_add_u32 m0, s100, 0x4000
	v_mfma_f32_16x16x32_bf16 v[56:59], v[212:215], v[184:187], v[56:59]
	global_load_lds_dwordx4 v[244:245], off
	v_lshl_add_u64 v[244:245], v[244:245], 0, s[34:35]
	v_mfma_f32_16x16x32_bf16 v[52:55], v[216:219], v[184:187], v[52:55]
	s_add_u32 m0, s100, 0x6000
	v_mfma_f32_16x16x32_bf16 v[48:51], v[220:223], v[184:187], v[48:51]
	global_load_lds_dwordx4 v[246:247], off
	v_lshl_add_u64 v[246:247], v[246:247], 0, s[34:35]
	v_mfma_f32_16x16x32_bf16 v[28:31], v[208:211], v[188:191], v[28:31]
	v_mfma_f32_16x16x32_bf16 v[24:27], v[212:215], v[188:191], v[24:27]
	v_mfma_f32_16x16x32_bf16 v[20:23], v[216:219], v[188:191], v[20:23]
	v_mfma_f32_16x16x32_bf16 v[16:19], v[220:223], v[188:191], v[16:19]
	s_waitcnt lgkmcnt(0)
	v_mfma_f32_16x16x32_bf16 v[108:111], v[224:227], v[176:179], v[108:111]
	ds_read_b128 v[192:195], v173 offset:32768
	v_mfma_f32_16x16x32_bf16 v[104:107], v[228:231], v[176:179], v[104:107]
	ds_read_b128 v[196:199], v173 offset:34816
	v_mfma_f32_16x16x32_bf16 v[100:103], v[232:235], v[176:179], v[100:103]
	ds_read_b128 v[200:203], v173 offset:36864
	v_mfma_f32_16x16x32_bf16 v[96:99], v[236:239], v[176:179], v[96:99]
	ds_read_b128 v[204:207], v173 offset:38912
	v_mfma_f32_16x16x32_bf16 v[76:79], v[224:227], v[180:183], v[76:79]
	ds_read_b128 v[208:211], v175 offset:32768
	v_mfma_f32_16x16x32_bf16 v[72:75], v[228:231], v[180:183], v[72:75]
	ds_read_b128 v[212:215], v175 offset:34816
	v_mfma_f32_16x16x32_bf16 v[68:71], v[232:235], v[180:183], v[68:71]
	ds_read_b128 v[216:219], v175 offset:36864
	v_mfma_f32_16x16x32_bf16 v[64:67], v[236:239], v[180:183], v[64:67]
	ds_read_b128 v[220:223], v175 offset:38912
	v_mfma_f32_16x16x32_bf16 v[44:47], v[224:227], v[184:187], v[44:47]
	v_mfma_f32_16x16x32_bf16 v[40:43], v[228:231], v[184:187], v[40:43]
	v_mfma_f32_16x16x32_bf16 v[36:39], v[232:235], v[184:187], v[36:39]
	v_mfma_f32_16x16x32_bf16 v[32:35], v[236:239], v[184:187], v[32:35]
	v_mfma_f32_16x16x32_bf16 v[12:15], v[224:227], v[188:191], v[12:15]
	v_mfma_f32_16x16x32_bf16 v[8:11], v[228:231], v[188:191], v[8:11]
	v_mfma_f32_16x16x32_bf16 v[4:7], v[232:235], v[188:191], v[4:7]
	v_mfma_f32_16x16x32_bf16 v[0:3], v[236:239], v[188:191], v[0:3]
	s_waitcnt lgkmcnt(0)
	v_mfma_f32_16x16x32_bf16 v[124:127], v[208:211], v[192:195], v[124:127]
	ds_read_b128 v[224:227], v175 offset:40960
	v_mfma_f32_16x16x32_bf16 v[120:123], v[212:215], v[192:195], v[120:123]
	ds_read_b128 v[228:231], v175 offset:43008
	v_mfma_f32_16x16x32_bf16 v[116:119], v[216:219], v[192:195], v[116:119]
	ds_read_b128 v[232:235], v175 offset:45056
	v_mfma_f32_16x16x32_bf16 v[112:115], v[220:223], v[192:195], v[112:115]
	ds_read_b128 v[236:239], v175 offset:47104
	v_mfma_f32_16x16x32_bf16 v[92:95], v[208:211], v[196:199], v[92:95]
	v_mfma_f32_16x16x32_bf16 v[88:91], v[212:215], v[196:199], v[88:91]
	v_mfma_f32_16x16x32_bf16 v[84:87], v[216:219], v[196:199], v[84:87]
	v_mfma_f32_16x16x32_bf16 v[80:83], v[220:223], v[196:199], v[80:83]
	v_mfma_f32_16x16x32_bf16 v[60:63], v[208:211], v[200:203], v[60:63]
	v_mfma_f32_16x16x32_bf16 v[56:59], v[212:215], v[200:203], v[56:59]
	v_mfma_f32_16x16x32_bf16 v[52:55], v[216:219], v[200:203], v[52:55]
	v_mfma_f32_16x16x32_bf16 v[48:51], v[220:223], v[200:203], v[48:51]
	v_mfma_f32_16x16x32_bf16 v[28:31], v[208:211], v[204:207], v[28:31]
	v_mfma_f32_16x16x32_bf16 v[24:27], v[212:215], v[204:207], v[24:27]
	v_mfma_f32_16x16x32_bf16 v[20:23], v[216:219], v[204:207], v[20:23]
	v_mfma_f32_16x16x32_bf16 v[16:19], v[220:223], v[204:207], v[16:19]
	s_waitcnt lgkmcnt(0)
	s_waitcnt vmcnt(4)
	s_barrier
	v_mfma_f32_16x16x32_bf16 v[108:111], v[224:227], v[192:195], v[108:111]
	ds_read_b128 v[176:179], v254 offset:0
	v_mfma_f32_16x16x32_bf16 v[104:107], v[228:231], v[192:195], v[104:107]
	ds_read_b128 v[180:183], v254 offset:2048
	v_mfma_f32_16x16x32_bf16 v[100:103], v[232:235], v[192:195], v[100:103]
	ds_read_b128 v[184:187], v254 offset:4096
	v_mfma_f32_16x16x32_bf16 v[96:99], v[236:239], v[192:195], v[96:99]
	ds_read_b128 v[188:191], v254 offset:6144
	v_mfma_f32_16x16x32_bf16 v[76:79], v[224:227], v[196:199], v[76:79]
	ds_read_b128 v[208:211], v174 offset:0
	v_mfma_f32_16x16x32_bf16 v[72:75], v[228:231], v[196:199], v[72:75]
	ds_read_b128 v[212:215], v174 offset:2048
	v_mfma_f32_16x16x32_bf16 v[68:71], v[232:235], v[196:199], v[68:71]
	ds_read_b128 v[216:219], v174 offset:4096
	v_mfma_f32_16x16x32_bf16 v[64:67], v[236:239], v[196:199], v[64:67]
	ds_read_b128 v[220:223], v174 offset:6144
	v_mfma_f32_16x16x32_bf16 v[44:47], v[224:227], v[200:203], v[44:47]
	s_add_u32 m0, s101, 0x8000
	v_mfma_f32_16x16x32_bf16 v[40:43], v[228:231], v[200:203], v[40:43]
	global_load_lds_dwordx4 v[138:139], off
	v_lshl_add_u64 v[138:139], v[138:139], 0, s[34:35]
	v_mfma_f32_16x16x32_bf16 v[36:39], v[232:235], v[200:203], v[36:39]
	s_add_u32 m0, s101, 0xa000
	v_mfma_f32_16x16x32_bf16 v[32:35], v[236:239], v[200:203], v[32:35]
	global_load_lds_dwordx4 v[140:141], off
	v_lshl_add_u64 v[140:141], v[140:141], 0, s[34:35]
	v_mfma_f32_16x16x32_bf16 v[12:15], v[224:227], v[204:207], v[12:15]
	s_add_u32 m0, s101, 0xc000
	v_mfma_f32_16x16x32_bf16 v[8:11], v[228:231], v[204:207], v[8:11]
	global_load_lds_dwordx4 v[250:251], off
	v_lshl_add_u64 v[250:251], v[250:251], 0, s[34:35]
	v_mfma_f32_16x16x32_bf16 v[4:7], v[232:235], v[204:207], v[4:7]
	s_add_u32 m0, s101, 0xe000
	v_mfma_f32_16x16x32_bf16 v[0:3], v[236:239], v[204:207], v[0:3]
	global_load_lds_dwordx4 v[252:253], off
	v_lshl_add_u64 v[252:253], v[252:253], 0, s[34:35]
	s_waitcnt lgkmcnt(0)
	v_mfma_f32_16x16x32_bf16 v[124:127], v[208:211], v[176:179], v[124:127]
	ds_read_b128 v[224:227], v174 offset:8192
	v_mfma_f32_16x16x32_bf16 v[120:123], v[212:215], v[176:179], v[120:123]
	ds_read_b128 v[228:231], v174 offset:10240
	v_mfma_f32_16x16x32_bf16 v[116:119], v[216:219], v[176:179], v[116:119]
	ds_read_b128 v[232:235], v174 offset:12288
	v_mfma_f32_16x16x32_bf16 v[112:115], v[220:223], v[176:179], v[112:115]
	ds_read_b128 v[236:239], v174 offset:14336
	v_mfma_f32_16x16x32_bf16 v[92:95], v[208:211], v[180:183], v[92:95]
	s_add_u32 m0, s100, 0x8000
	v_mfma_f32_16x16x32_bf16 v[88:91], v[212:215], v[180:183], v[88:91]
	global_load_lds_dwordx4 v[240:241], off
	v_lshl_add_u64 v[240:241], v[240:241], 0, s[34:35]
	v_mfma_f32_16x16x32_bf16 v[84:87], v[216:219], v[180:183], v[84:87]
	s_add_u32 m0, s100, 0xa000
	v_mfma_f32_16x16x32_bf16 v[80:83], v[220:223], v[180:183], v[80:83]
	global_load_lds_dwordx4 v[242:243], off
	v_lshl_add_u64 v[242:243], v[242:243], 0, s[34:35]
	v_mfma_f32_16x16x32_bf16 v[60:63], v[208:211], v[184:187], v[60:63]
	s_add_u32 m0, s100, 0xc000
	v_mfma_f32_16x16x32_bf16 v[56:59], v[212:215], v[184:187], v[56:59]
	global_load_lds_dwordx4 v[244:245], off
	v_lshl_add_u64 v[244:245], v[244:245], 0, s[34:35]
	v_mfma_f32_16x16x32_bf16 v[52:55], v[216:219], v[184:187], v[52:55]
	s_add_u32 m0, s100, 0xe000
	v_mfma_f32_16x16x32_bf16 v[48:51], v[220:223], v[184:187], v[48:51]
	global_load_lds_dwordx4 v[246:247], off
	v_lshl_add_u64 v[246:247], v[246:247], 0, s[34:35]
	v_mfma_f32_16x16x32_bf16 v[28:31], v[208:211], v[188:191], v[28:31]
	v_mfma_f32_16x16x32_bf16 v[24:27], v[212:215], v[188:191], v[24:27]
	v_mfma_f32_16x16x32_bf16 v[20:23], v[216:219], v[188:191], v[20:23]
	v_mfma_f32_16x16x32_bf16 v[16:19], v[220:223], v[188:191], v[16:19]
	s_waitcnt lgkmcnt(0)
	v_mfma_f32_16x16x32_bf16 v[108:111], v[224:227], v[176:179], v[108:111]
	ds_read_b128 v[192:195], v255 offset:0
	v_mfma_f32_16x16x32_bf16 v[104:107], v[228:231], v[176:179], v[104:107]
	ds_read_b128 v[196:199], v255 offset:2048
	v_mfma_f32_16x16x32_bf16 v[100:103], v[232:235], v[176:179], v[100:103]
	ds_read_b128 v[200:203], v255 offset:4096
	v_mfma_f32_16x16x32_bf16 v[96:99], v[236:239], v[176:179], v[96:99]
	ds_read_b128 v[204:207], v255 offset:6144
	v_mfma_f32_16x16x32_bf16 v[76:79], v[224:227], v[180:183], v[76:79]
	ds_read_b128 v[208:211], v175 offset:0
	v_mfma_f32_16x16x32_bf16 v[72:75], v[228:231], v[180:183], v[72:75]
	ds_read_b128 v[212:215], v175 offset:2048
	v_mfma_f32_16x16x32_bf16 v[68:71], v[232:235], v[180:183], v[68:71]
	ds_read_b128 v[216:219], v175 offset:4096
	v_mfma_f32_16x16x32_bf16 v[64:67], v[236:239], v[180:183], v[64:67]
	ds_read_b128 v[220:223], v175 offset:6144
	v_mfma_f32_16x16x32_bf16 v[44:47], v[224:227], v[184:187], v[44:47]
	v_mfma_f32_16x16x32_bf16 v[40:43], v[228:231], v[184:187], v[40:43]
	v_mfma_f32_16x16x32_bf16 v[36:39], v[232:235], v[184:187], v[36:39]
	v_mfma_f32_16x16x32_bf16 v[32:35], v[236:239], v[184:187], v[32:35]
	v_mfma_f32_16x16x32_bf16 v[12:15], v[224:227], v[188:191], v[12:15]
	v_mfma_f32_16x16x32_bf16 v[8:11], v[228:231], v[188:191], v[8:11]
	v_mfma_f32_16x16x32_bf16 v[4:7], v[232:235], v[188:191], v[4:7]
	v_mfma_f32_16x16x32_bf16 v[0:3], v[236:239], v[188:191], v[0:3]
	s_waitcnt lgkmcnt(0)
	v_mfma_f32_16x16x32_bf16 v[124:127], v[208:211], v[192:195], v[124:127]
	ds_read_b128 v[224:227], v175 offset:8192
	v_mfma_f32_16x16x32_bf16 v[120:123], v[212:215], v[192:195], v[120:123]
	ds_read_b128 v[228:231], v175 offset:10240
	v_mfma_f32_16x16x32_bf16 v[116:119], v[216:219], v[192:195], v[116:119]
	ds_read_b128 v[232:235], v175 offset:12288
	v_mfma_f32_16x16x32_bf16 v[112:115], v[220:223], v[192:195], v[112:115]
	ds_read_b128 v[236:239], v175 offset:14336
	v_mfma_f32_16x16x32_bf16 v[92:95], v[208:211], v[196:199], v[92:95]
	v_mfma_f32_16x16x32_bf16 v[88:91], v[212:215], v[196:199], v[88:91]
	v_mfma_f32_16x16x32_bf16 v[84:87], v[216:219], v[196:199], v[84:87]
	v_mfma_f32_16x16x32_bf16 v[80:83], v[220:223], v[196:199], v[80:83]
	v_mfma_f32_16x16x32_bf16 v[60:63], v[208:211], v[200:203], v[60:63]
	v_mfma_f32_16x16x32_bf16 v[56:59], v[212:215], v[200:203], v[56:59]
	v_mfma_f32_16x16x32_bf16 v[52:55], v[216:219], v[200:203], v[52:55]
	v_mfma_f32_16x16x32_bf16 v[48:51], v[220:223], v[200:203], v[48:51]
	v_mfma_f32_16x16x32_bf16 v[28:31], v[208:211], v[204:207], v[28:31]
	v_mfma_f32_16x16x32_bf16 v[24:27], v[212:215], v[204:207], v[24:27]
	v_mfma_f32_16x16x32_bf16 v[20:23], v[216:219], v[204:207], v[20:23]
	v_mfma_f32_16x16x32_bf16 v[16:19], v[220:223], v[204:207], v[16:19]
	s_waitcnt lgkmcnt(0)
	s_waitcnt vmcnt(4)
	s_barrier
	v_mfma_f32_16x16x32_bf16 v[108:111], v[224:227], v[192:195], v[108:111]
	ds_read_b128 v[176:179], v172 offset:0
	v_mfma_f32_16x16x32_bf16 v[104:107], v[228:231], v[192:195], v[104:107]
	ds_read_b128 v[180:183], v172 offset:2048
	v_mfma_f32_16x16x32_bf16 v[100:103], v[232:235], v[192:195], v[100:103]
	ds_read_b128 v[184:187], v172 offset:4096
	v_mfma_f32_16x16x32_bf16 v[96:99], v[236:239], v[192:195], v[96:99]
	ds_read_b128 v[188:191], v172 offset:6144
	v_mfma_f32_16x16x32_bf16 v[76:79], v[224:227], v[196:199], v[76:79]
	ds_read_b128 v[208:211], v174 offset:32768
	v_mfma_f32_16x16x32_bf16 v[72:75], v[228:231], v[196:199], v[72:75]
	ds_read_b128 v[212:215], v174 offset:34816
	v_mfma_f32_16x16x32_bf16 v[68:71], v[232:235], v[196:199], v[68:71]
	ds_read_b128 v[216:219], v174 offset:36864
	v_mfma_f32_16x16x32_bf16 v[64:67], v[236:239], v[196:199], v[64:67]
	ds_read_b128 v[220:223], v174 offset:38912
	v_mfma_f32_16x16x32_bf16 v[44:47], v[224:227], v[200:203], v[44:47]
	s_mov_b32 m0, s101
	v_mfma_f32_16x16x32_bf16 v[40:43], v[228:231], v[200:203], v[40:43]
	global_load_lds_dwordx4 v[138:139], off
	v_lshl_add_u64 v[138:139], v[138:139], 0, s[34:35]
	v_mfma_f32_16x16x32_bf16 v[36:39], v[232:235], v[200:203], v[36:39]
	s_add_u32 m0, s101, 0x2000
	v_mfma_f32_16x16x32_bf16 v[32:35], v[236:239], v[200:203], v[32:35]
	global_load_lds_dwordx4 v[140:141], off
	v_lshl_add_u64 v[140:141], v[140:141], 0, s[34:35]
	v_mfma_f32_16x16x32_bf16 v[12:15], v[224:227], v[204:207], v[12:15]
	s_add_u32 m0, s101, 0x4000
	v_mfma_f32_16x16x32_bf16 v[8:11], v[228:231], v[204:207], v[8:11]
	global_load_lds_dwordx4 v[250:251], off
	v_lshl_add_u64 v[250:251], v[250:251], 0, s[34:35]
	v_mfma_f32_16x16x32_bf16 v[4:7], v[232:235], v[204:207], v[4:7]
	s_add_u32 m0, s101, 0x6000
	v_mfma_f32_16x16x32_bf16 v[0:3], v[236:239], v[204:207], v[0:3]
	global_load_lds_dwordx4 v[252:253], off
	v_lshl_add_u64 v[252:253], v[252:253], 0, s[34:35]
	s_waitcnt lgkmcnt(0)
	v_mfma_f32_16x16x32_bf16 v[124:127], v[208:211], v[176:179], v[124:127]
	ds_read_b128 v[224:227], v174 offset:40960
	v_mfma_f32_16x16x32_bf16 v[120:123], v[212:215], v[176:179], v[120:123]
	ds_read_b128 v[228:231], v174 offset:43008
	v_mfma_f32_16x16x32_bf16 v[116:119], v[216:219], v[176:179], v[116:119]
	ds_read_b128 v[232:235], v174 offset:45056
	v_mfma_f32_16x16x32_bf16 v[112:115], v[220:223], v[176:179], v[112:115]
	ds_read_b128 v[236:239], v174 offset:47104
	v_mfma_f32_16x16x32_bf16 v[92:95], v[208:211], v[180:183], v[92:95]
	s_add_u32 m0, s100, 0x20000
	v_mfma_f32_16x16x32_bf16 v[88:91], v[212:215], v[180:183], v[88:91]
	global_load_lds_dwordx4 v[240:241], off
	v_lshl_add_u64 v[240:241], v[240:241], 0, s[34:35]
	v_mfma_f32_16x16x32_bf16 v[84:87], v[216:219], v[180:183], v[84:87]
	s_add_u32 m0, s100, 0x22000
	v_mfma_f32_16x16x32_bf16 v[80:83], v[220:223], v[180:183], v[80:83]
	global_load_lds_dwordx4 v[242:243], off
	v_lshl_add_u64 v[242:243], v[242:243], 0, s[34:35]
	v_mfma_f32_16x16x32_bf16 v[60:63], v[208:211], v[184:187], v[60:63]
	s_add_u32 m0, s100, 0x24000
	v_mfma_f32_16x16x32_bf16 v[56:59], v[212:215], v[184:187], v[56:59]
	global_load_lds_dwordx4 v[244:245], off
	v_lshl_add_u64 v[244:245], v[244:245], 0, s[34:35]
	v_mfma_f32_16x16x32_bf16 v[52:55], v[216:219], v[184:187], v[52:55]
	s_add_u32 m0, s100, 0x26000
	v_mfma_f32_16x16x32_bf16 v[48:51], v[220:223], v[184:187], v[48:51]
	global_load_lds_dwordx4 v[246:247], off
	v_lshl_add_u64 v[246:247], v[246:247], 0, s[34:35]
	v_mfma_f32_16x16x32_bf16 v[28:31], v[208:211], v[188:191], v[28:31]
	v_mfma_f32_16x16x32_bf16 v[24:27], v[212:215], v[188:191], v[24:27]
	v_mfma_f32_16x16x32_bf16 v[20:23], v[216:219], v[188:191], v[20:23]
	v_mfma_f32_16x16x32_bf16 v[16:19], v[220:223], v[188:191], v[16:19]
	s_waitcnt lgkmcnt(0)
	v_mfma_f32_16x16x32_bf16 v[108:111], v[224:227], v[176:179], v[108:111]
	ds_read_b128 v[192:195], v173 offset:0
	v_mfma_f32_16x16x32_bf16 v[104:107], v[228:231], v[176:179], v[104:107]
	ds_read_b128 v[196:199], v173 offset:2048
	v_mfma_f32_16x16x32_bf16 v[100:103], v[232:235], v[176:179], v[100:103]
	ds_read_b128 v[200:203], v173 offset:4096
	v_mfma_f32_16x16x32_bf16 v[96:99], v[236:239], v[176:179], v[96:99]
	ds_read_b128 v[204:207], v173 offset:6144
	v_mfma_f32_16x16x32_bf16 v[76:79], v[224:227], v[180:183], v[76:79]
	ds_read_b128 v[208:211], v175 offset:32768
	v_mfma_f32_16x16x32_bf16 v[72:75], v[228:231], v[180:183], v[72:75]
	ds_read_b128 v[212:215], v175 offset:34816
	v_mfma_f32_16x16x32_bf16 v[68:71], v[232:235], v[180:183], v[68:71]
	ds_read_b128 v[216:219], v175 offset:36864
	v_mfma_f32_16x16x32_bf16 v[64:67], v[236:239], v[180:183], v[64:67]
	ds_read_b128 v[220:223], v175 offset:38912
	v_mfma_f32_16x16x32_bf16 v[44:47], v[224:227], v[184:187], v[44:47]
	v_mfma_f32_16x16x32_bf16 v[40:43], v[228:231], v[184:187], v[40:43]
	v_mfma_f32_16x16x32_bf16 v[36:39], v[232:235], v[184:187], v[36:39]
	v_mfma_f32_16x16x32_bf16 v[32:35], v[236:239], v[184:187], v[32:35]
	v_mfma_f32_16x16x32_bf16 v[12:15], v[224:227], v[188:191], v[12:15]
	v_mfma_f32_16x16x32_bf16 v[8:11], v[228:231], v[188:191], v[8:11]
	v_mfma_f32_16x16x32_bf16 v[4:7], v[232:235], v[188:191], v[4:7]
	v_mfma_f32_16x16x32_bf16 v[0:3], v[236:239], v[188:191], v[0:3]
	s_waitcnt lgkmcnt(0)
	v_mfma_f32_16x16x32_bf16 v[124:127], v[208:211], v[192:195], v[124:127]
	ds_read_b128 v[224:227], v175 offset:40960
	v_mfma_f32_16x16x32_bf16 v[120:123], v[212:215], v[192:195], v[120:123]
	ds_read_b128 v[228:231], v175 offset:43008
	v_mfma_f32_16x16x32_bf16 v[116:119], v[216:219], v[192:195], v[116:119]
	ds_read_b128 v[232:235], v175 offset:45056
	v_mfma_f32_16x16x32_bf16 v[112:115], v[220:223], v[192:195], v[112:115]
	ds_read_b128 v[236:239], v175 offset:47104
	v_mfma_f32_16x16x32_bf16 v[92:95], v[208:211], v[196:199], v[92:95]
	v_mfma_f32_16x16x32_bf16 v[88:91], v[212:215], v[196:199], v[88:91]
	v_mfma_f32_16x16x32_bf16 v[84:87], v[216:219], v[196:199], v[84:87]
	v_mfma_f32_16x16x32_bf16 v[80:83], v[220:223], v[196:199], v[80:83]
	v_mfma_f32_16x16x32_bf16 v[60:63], v[208:211], v[200:203], v[60:63]
	v_mfma_f32_16x16x32_bf16 v[56:59], v[212:215], v[200:203], v[56:59]
	v_mfma_f32_16x16x32_bf16 v[52:55], v[216:219], v[200:203], v[52:55]
	v_mfma_f32_16x16x32_bf16 v[48:51], v[220:223], v[200:203], v[48:51]
	v_mfma_f32_16x16x32_bf16 v[28:31], v[208:211], v[204:207], v[28:31]
	v_mfma_f32_16x16x32_bf16 v[24:27], v[212:215], v[204:207], v[24:27]
	v_mfma_f32_16x16x32_bf16 v[20:23], v[216:219], v[204:207], v[20:23]
	v_mfma_f32_16x16x32_bf16 v[16:19], v[220:223], v[204:207], v[16:19]
	s_waitcnt lgkmcnt(0)
	s_waitcnt vmcnt(4)
	s_barrier
	v_mfma_f32_16x16x32_bf16 v[108:111], v[224:227], v[192:195], v[108:111]
	ds_read_b128 v[176:179], v172 offset:32768
	v_mfma_f32_16x16x32_bf16 v[104:107], v[228:231], v[192:195], v[104:107]
	ds_read_b128 v[180:183], v172 offset:34816
	v_mfma_f32_16x16x32_bf16 v[100:103], v[232:235], v[192:195], v[100:103]
	ds_read_b128 v[184:187], v172 offset:36864
	v_mfma_f32_16x16x32_bf16 v[96:99], v[236:239], v[192:195], v[96:99]
	ds_read_b128 v[188:191], v172 offset:38912
	v_mfma_f32_16x16x32_bf16 v[76:79], v[224:227], v[196:199], v[76:79]
	ds_read_b128 v[208:211], v174 offset:0
	v_mfma_f32_16x16x32_bf16 v[72:75], v[228:231], v[196:199], v[72:75]
	ds_read_b128 v[212:215], v174 offset:2048
	v_mfma_f32_16x16x32_bf16 v[68:71], v[232:235], v[196:199], v[68:71]
	ds_read_b128 v[216:219], v174 offset:4096
	v_mfma_f32_16x16x32_bf16 v[64:67], v[236:239], v[196:199], v[64:67]
	ds_read_b128 v[220:223], v174 offset:6144
	v_mfma_f32_16x16x32_bf16 v[44:47], v[224:227], v[200:203], v[44:47]
	s_add_u32 m0, s101, 0x8000
	v_mfma_f32_16x16x32_bf16 v[40:43], v[228:231], v[200:203], v[40:43]
	global_load_lds_dwordx4 v[138:139], off
	v_lshl_add_u64 v[138:139], v[138:139], 0, s[34:35]
	v_mfma_f32_16x16x32_bf16 v[36:39], v[232:235], v[200:203], v[36:39]
	s_add_u32 m0, s101, 0xa000
	v_mfma_f32_16x16x32_bf16 v[32:35], v[236:239], v[200:203], v[32:35]
	global_load_lds_dwordx4 v[140:141], off
	v_lshl_add_u64 v[140:141], v[140:141], 0, s[34:35]
	v_mfma_f32_16x16x32_bf16 v[12:15], v[224:227], v[204:207], v[12:15]
	s_add_u32 m0, s101, 0xc000
	v_mfma_f32_16x16x32_bf16 v[8:11], v[228:231], v[204:207], v[8:11]
	global_load_lds_dwordx4 v[250:251], off
	v_lshl_add_u64 v[250:251], v[250:251], 0, s[34:35]
	v_mfma_f32_16x16x32_bf16 v[4:7], v[232:235], v[204:207], v[4:7]
	s_add_u32 m0, s101, 0xe000
	v_mfma_f32_16x16x32_bf16 v[0:3], v[236:239], v[204:207], v[0:3]
	global_load_lds_dwordx4 v[252:253], off
	v_lshl_add_u64 v[252:253], v[252:253], 0, s[34:35]
	s_waitcnt lgkmcnt(0)
	v_mfma_f32_16x16x32_bf16 v[124:127], v[208:211], v[176:179], v[124:127]
	ds_read_b128 v[224:227], v174 offset:8192
	v_mfma_f32_16x16x32_bf16 v[120:123], v[212:215], v[176:179], v[120:123]
	ds_read_b128 v[228:231], v174 offset:10240
	v_mfma_f32_16x16x32_bf16 v[116:119], v[216:219], v[176:179], v[116:119]
	ds_read_b128 v[232:235], v174 offset:12288
	v_mfma_f32_16x16x32_bf16 v[112:115], v[220:223], v[176:179], v[112:115]
	ds_read_b128 v[236:239], v174 offset:14336
	v_mfma_f32_16x16x32_bf16 v[92:95], v[208:211], v[180:183], v[92:95]
	s_mov_b32 m0, s100
	v_mfma_f32_16x16x32_bf16 v[88:91], v[212:215], v[180:183], v[88:91]
	global_load_lds_dwordx4 v[240:241], off
	v_lshl_add_u64 v[240:241], v[240:241], 0, s[34:35]
	v_mfma_f32_16x16x32_bf16 v[84:87], v[216:219], v[180:183], v[84:87]
	s_add_u32 m0, s100, 0x2000
	v_mfma_f32_16x16x32_bf16 v[80:83], v[220:223], v[180:183], v[80:83]
	global_load_lds_dwordx4 v[242:243], off
	v_lshl_add_u64 v[242:243], v[242:243], 0, s[34:35]
	v_mfma_f32_16x16x32_bf16 v[60:63], v[208:211], v[184:187], v[60:63]
	s_add_u32 m0, s100, 0x4000
	v_mfma_f32_16x16x32_bf16 v[56:59], v[212:215], v[184:187], v[56:59]
	global_load_lds_dwordx4 v[244:245], off
	v_lshl_add_u64 v[244:245], v[244:245], 0, s[34:35]
	v_mfma_f32_16x16x32_bf16 v[52:55], v[216:219], v[184:187], v[52:55]
	s_add_u32 m0, s100, 0x6000
	v_mfma_f32_16x16x32_bf16 v[48:51], v[220:223], v[184:187], v[48:51]
	global_load_lds_dwordx4 v[246:247], off
	v_lshl_add_u64 v[246:247], v[246:247], 0, s[34:35]
	v_mfma_f32_16x16x32_bf16 v[28:31], v[208:211], v[188:191], v[28:31]
	v_mfma_f32_16x16x32_bf16 v[24:27], v[212:215], v[188:191], v[24:27]
	v_mfma_f32_16x16x32_bf16 v[20:23], v[216:219], v[188:191], v[20:23]
	v_mfma_f32_16x16x32_bf16 v[16:19], v[220:223], v[188:191], v[16:19]
	s_waitcnt lgkmcnt(0)
	v_mfma_f32_16x16x32_bf16 v[108:111], v[224:227], v[176:179], v[108:111]
	ds_read_b128 v[192:195], v173 offset:32768
	v_mfma_f32_16x16x32_bf16 v[104:107], v[228:231], v[176:179], v[104:107]
	ds_read_b128 v[196:199], v173 offset:34816
	v_mfma_f32_16x16x32_bf16 v[100:103], v[232:235], v[176:179], v[100:103]
	ds_read_b128 v[200:203], v173 offset:36864
	v_mfma_f32_16x16x32_bf16 v[96:99], v[236:239], v[176:179], v[96:99]
	ds_read_b128 v[204:207], v173 offset:38912
	v_mfma_f32_16x16x32_bf16 v[76:79], v[224:227], v[180:183], v[76:79]
	ds_read_b128 v[208:211], v175 offset:0
	v_mfma_f32_16x16x32_bf16 v[72:75], v[228:231], v[180:183], v[72:75]
	ds_read_b128 v[212:215], v175 offset:2048
	v_mfma_f32_16x16x32_bf16 v[68:71], v[232:235], v[180:183], v[68:71]
	ds_read_b128 v[216:219], v175 offset:4096
	v_mfma_f32_16x16x32_bf16 v[64:67], v[236:239], v[180:183], v[64:67]
	ds_read_b128 v[220:223], v175 offset:6144
	v_mfma_f32_16x16x32_bf16 v[44:47], v[224:227], v[184:187], v[44:47]
	v_mfma_f32_16x16x32_bf16 v[40:43], v[228:231], v[184:187], v[40:43]
	v_mfma_f32_16x16x32_bf16 v[36:39], v[232:235], v[184:187], v[36:39]
	v_mfma_f32_16x16x32_bf16 v[32:35], v[236:239], v[184:187], v[32:35]
	v_mfma_f32_16x16x32_bf16 v[12:15], v[224:227], v[188:191], v[12:15]
	v_mfma_f32_16x16x32_bf16 v[8:11], v[228:231], v[188:191], v[8:11]
	v_mfma_f32_16x16x32_bf16 v[4:7], v[232:235], v[188:191], v[4:7]
	v_mfma_f32_16x16x32_bf16 v[0:3], v[236:239], v[188:191], v[0:3]
	s_waitcnt lgkmcnt(0)
	v_mfma_f32_16x16x32_bf16 v[124:127], v[208:211], v[192:195], v[124:127]
	ds_read_b128 v[224:227], v175 offset:8192
	v_mfma_f32_16x16x32_bf16 v[120:123], v[212:215], v[192:195], v[120:123]
	ds_read_b128 v[228:231], v175 offset:10240
	v_mfma_f32_16x16x32_bf16 v[116:119], v[216:219], v[192:195], v[116:119]
	ds_read_b128 v[232:235], v175 offset:12288
	v_mfma_f32_16x16x32_bf16 v[112:115], v[220:223], v[192:195], v[112:115]
	ds_read_b128 v[236:239], v175 offset:14336
	v_mfma_f32_16x16x32_bf16 v[92:95], v[208:211], v[196:199], v[92:95]
	v_mfma_f32_16x16x32_bf16 v[88:91], v[212:215], v[196:199], v[88:91]
	v_mfma_f32_16x16x32_bf16 v[84:87], v[216:219], v[196:199], v[84:87]
	v_mfma_f32_16x16x32_bf16 v[80:83], v[220:223], v[196:199], v[80:83]
	v_mfma_f32_16x16x32_bf16 v[60:63], v[208:211], v[200:203], v[60:63]
	v_mfma_f32_16x16x32_bf16 v[56:59], v[212:215], v[200:203], v[56:59]
	v_mfma_f32_16x16x32_bf16 v[52:55], v[216:219], v[200:203], v[52:55]
	v_mfma_f32_16x16x32_bf16 v[48:51], v[220:223], v[200:203], v[48:51]
	v_mfma_f32_16x16x32_bf16 v[28:31], v[208:211], v[204:207], v[28:31]
	v_mfma_f32_16x16x32_bf16 v[24:27], v[212:215], v[204:207], v[24:27]
	v_mfma_f32_16x16x32_bf16 v[20:23], v[216:219], v[204:207], v[20:23]
	v_mfma_f32_16x16x32_bf16 v[16:19], v[220:223], v[204:207], v[16:19]
	s_waitcnt lgkmcnt(0)
	s_waitcnt vmcnt(4)
	s_barrier
	v_mfma_f32_16x16x32_bf16 v[108:111], v[224:227], v[192:195], v[108:111]
	ds_read_b128 v[176:179], v254 offset:0
	v_mfma_f32_16x16x32_bf16 v[104:107], v[228:231], v[192:195], v[104:107]
	ds_read_b128 v[180:183], v254 offset:2048
	v_mfma_f32_16x16x32_bf16 v[100:103], v[232:235], v[192:195], v[100:103]
	ds_read_b128 v[184:187], v254 offset:4096
	v_mfma_f32_16x16x32_bf16 v[96:99], v[236:239], v[192:195], v[96:99]
	ds_read_b128 v[188:191], v254 offset:6144
	v_mfma_f32_16x16x32_bf16 v[76:79], v[224:227], v[196:199], v[76:79]
	ds_read_b128 v[208:211], v174 offset:32768
	v_mfma_f32_16x16x32_bf16 v[72:75], v[228:231], v[196:199], v[72:75]
	ds_read_b128 v[212:215], v174 offset:34816
	v_mfma_f32_16x16x32_bf16 v[68:71], v[232:235], v[196:199], v[68:71]
	ds_read_b128 v[216:219], v174 offset:36864
	v_mfma_f32_16x16x32_bf16 v[64:67], v[236:239], v[196:199], v[64:67]
	ds_read_b128 v[220:223], v174 offset:38912
	v_mfma_f32_16x16x32_bf16 v[44:47], v[224:227], v[200:203], v[44:47]
	s_mov_b32 m0, s101
	v_mfma_f32_16x16x32_bf16 v[40:43], v[228:231], v[200:203], v[40:43]
	global_load_lds_dwordx4 v[138:139], off
	v_lshl_add_u64 v[138:139], v[138:139], 0, s[34:35]
	v_mfma_f32_16x16x32_bf16 v[36:39], v[232:235], v[200:203], v[36:39]
	s_add_u32 m0, s101, 0x2000
	v_mfma_f32_16x16x32_bf16 v[32:35], v[236:239], v[200:203], v[32:35]
	global_load_lds_dwordx4 v[140:141], off
	v_lshl_add_u64 v[140:141], v[140:141], 0, s[34:35]
	v_mfma_f32_16x16x32_bf16 v[12:15], v[224:227], v[204:207], v[12:15]
	s_add_u32 m0, s101, 0x4000
	v_mfma_f32_16x16x32_bf16 v[8:11], v[228:231], v[204:207], v[8:11]
	global_load_lds_dwordx4 v[250:251], off
	v_lshl_add_u64 v[250:251], v[250:251], 0, s[34:35]
	v_mfma_f32_16x16x32_bf16 v[4:7], v[232:235], v[204:207], v[4:7]
	s_add_u32 m0, s101, 0x6000
	v_mfma_f32_16x16x32_bf16 v[0:3], v[236:239], v[204:207], v[0:3]
	global_load_lds_dwordx4 v[252:253], off
	v_lshl_add_u64 v[252:253], v[252:253], 0, s[34:35]
	s_waitcnt lgkmcnt(0)
	v_mfma_f32_16x16x32_bf16 v[124:127], v[208:211], v[176:179], v[124:127]
	ds_read_b128 v[224:227], v174 offset:40960
	v_mfma_f32_16x16x32_bf16 v[120:123], v[212:215], v[176:179], v[120:123]
	ds_read_b128 v[228:231], v174 offset:43008
	v_mfma_f32_16x16x32_bf16 v[116:119], v[216:219], v[176:179], v[116:119]
	ds_read_b128 v[232:235], v174 offset:45056
	v_mfma_f32_16x16x32_bf16 v[112:115], v[220:223], v[176:179], v[112:115]
	ds_read_b128 v[236:239], v174 offset:47104
	v_mfma_f32_16x16x32_bf16 v[92:95], v[208:211], v[180:183], v[92:95]
	s_add_u32 m0, s100, 0x8000
	v_mfma_f32_16x16x32_bf16 v[88:91], v[212:215], v[180:183], v[88:91]
	global_load_lds_dwordx4 v[240:241], off
	v_lshl_add_u64 v[240:241], v[240:241], 0, s[34:35]
	v_mfma_f32_16x16x32_bf16 v[84:87], v[216:219], v[180:183], v[84:87]
	s_add_u32 m0, s100, 0xa000
	v_mfma_f32_16x16x32_bf16 v[80:83], v[220:223], v[180:183], v[80:83]
	global_load_lds_dwordx4 v[242:243], off
	v_lshl_add_u64 v[242:243], v[242:243], 0, s[34:35]
	v_mfma_f32_16x16x32_bf16 v[60:63], v[208:211], v[184:187], v[60:63]
	s_add_u32 m0, s100, 0xc000
	v_mfma_f32_16x16x32_bf16 v[56:59], v[212:215], v[184:187], v[56:59]
	global_load_lds_dwordx4 v[244:245], off
	v_lshl_add_u64 v[244:245], v[244:245], 0, s[34:35]
	v_mfma_f32_16x16x32_bf16 v[52:55], v[216:219], v[184:187], v[52:55]
	s_add_u32 m0, s100, 0xe000
	v_mfma_f32_16x16x32_bf16 v[48:51], v[220:223], v[184:187], v[48:51]
	global_load_lds_dwordx4 v[246:247], off
	v_lshl_add_u64 v[246:247], v[246:247], 0, s[34:35]
	v_mfma_f32_16x16x32_bf16 v[28:31], v[208:211], v[188:191], v[28:31]
	v_mfma_f32_16x16x32_bf16 v[24:27], v[212:215], v[188:191], v[24:27]
	v_mfma_f32_16x16x32_bf16 v[20:23], v[216:219], v[188:191], v[20:23]
	v_mfma_f32_16x16x32_bf16 v[16:19], v[220:223], v[188:191], v[16:19]
	s_waitcnt lgkmcnt(0)
	v_mfma_f32_16x16x32_bf16 v[108:111], v[224:227], v[176:179], v[108:111]
	ds_read_b128 v[192:195], v255 offset:0
	v_mfma_f32_16x16x32_bf16 v[104:107], v[228:231], v[176:179], v[104:107]
	ds_read_b128 v[196:199], v255 offset:2048
	v_mfma_f32_16x16x32_bf16 v[100:103], v[232:235], v[176:179], v[100:103]
	ds_read_b128 v[200:203], v255 offset:4096
	v_mfma_f32_16x16x32_bf16 v[96:99], v[236:239], v[176:179], v[96:99]
	ds_read_b128 v[204:207], v255 offset:6144
	v_mfma_f32_16x16x32_bf16 v[76:79], v[224:227], v[180:183], v[76:79]
	ds_read_b128 v[208:211], v175 offset:32768
	v_mfma_f32_16x16x32_bf16 v[72:75], v[228:231], v[180:183], v[72:75]
	ds_read_b128 v[212:215], v175 offset:34816
	v_mfma_f32_16x16x32_bf16 v[68:71], v[232:235], v[180:183], v[68:71]
	ds_read_b128 v[216:219], v175 offset:36864
	v_mfma_f32_16x16x32_bf16 v[64:67], v[236:239], v[180:183], v[64:67]
	ds_read_b128 v[220:223], v175 offset:38912
	v_mfma_f32_16x16x32_bf16 v[44:47], v[224:227], v[184:187], v[44:47]
	v_mfma_f32_16x16x32_bf16 v[40:43], v[228:231], v[184:187], v[40:43]
	v_mfma_f32_16x16x32_bf16 v[36:39], v[232:235], v[184:187], v[36:39]
	v_mfma_f32_16x16x32_bf16 v[32:35], v[236:239], v[184:187], v[32:35]
	v_mfma_f32_16x16x32_bf16 v[12:15], v[224:227], v[188:191], v[12:15]
	v_mfma_f32_16x16x32_bf16 v[8:11], v[228:231], v[188:191], v[8:11]
	v_mfma_f32_16x16x32_bf16 v[4:7], v[232:235], v[188:191], v[4:7]
	v_mfma_f32_16x16x32_bf16 v[0:3], v[236:239], v[188:191], v[0:3]
	s_waitcnt lgkmcnt(0)
	v_mfma_f32_16x16x32_bf16 v[124:127], v[208:211], v[192:195], v[124:127]
	ds_read_b128 v[224:227], v175 offset:40960
	v_mfma_f32_16x16x32_bf16 v[120:123], v[212:215], v[192:195], v[120:123]
	ds_read_b128 v[228:231], v175 offset:43008
	v_mfma_f32_16x16x32_bf16 v[116:119], v[216:219], v[192:195], v[116:119]
	ds_read_b128 v[232:235], v175 offset:45056
	v_mfma_f32_16x16x32_bf16 v[112:115], v[220:223], v[192:195], v[112:115]
	ds_read_b128 v[236:239], v175 offset:47104
	v_mfma_f32_16x16x32_bf16 v[92:95], v[208:211], v[196:199], v[92:95]
	v_mfma_f32_16x16x32_bf16 v[88:91], v[212:215], v[196:199], v[88:91]
	v_mfma_f32_16x16x32_bf16 v[84:87], v[216:219], v[196:199], v[84:87]
	v_mfma_f32_16x16x32_bf16 v[80:83], v[220:223], v[196:199], v[80:83]
	v_mfma_f32_16x16x32_bf16 v[60:63], v[208:211], v[200:203], v[60:63]
	v_mfma_f32_16x16x32_bf16 v[56:59], v[212:215], v[200:203], v[56:59]
	v_mfma_f32_16x16x32_bf16 v[52:55], v[216:219], v[200:203], v[52:55]
	v_mfma_f32_16x16x32_bf16 v[48:51], v[220:223], v[200:203], v[48:51]
	v_mfma_f32_16x16x32_bf16 v[28:31], v[208:211], v[204:207], v[28:31]
	v_mfma_f32_16x16x32_bf16 v[24:27], v[212:215], v[204:207], v[24:27]
	v_mfma_f32_16x16x32_bf16 v[20:23], v[216:219], v[204:207], v[20:23]
	v_mfma_f32_16x16x32_bf16 v[16:19], v[220:223], v[204:207], v[16:19]
	s_waitcnt lgkmcnt(0)
	s_waitcnt vmcnt(4)
	s_barrier
	v_mfma_f32_16x16x32_bf16 v[108:111], v[224:227], v[192:195], v[108:111]
	ds_read_b128 v[176:179], v172 offset:0
	v_mfma_f32_16x16x32_bf16 v[104:107], v[228:231], v[192:195], v[104:107]
	ds_read_b128 v[180:183], v172 offset:2048
	v_mfma_f32_16x16x32_bf16 v[100:103], v[232:235], v[192:195], v[100:103]
	ds_read_b128 v[184:187], v172 offset:4096
	v_mfma_f32_16x16x32_bf16 v[96:99], v[236:239], v[192:195], v[96:99]
	ds_read_b128 v[188:191], v172 offset:6144
	v_mfma_f32_16x16x32_bf16 v[76:79], v[224:227], v[196:199], v[76:79]
	ds_read_b128 v[208:211], v174 offset:0
	v_mfma_f32_16x16x32_bf16 v[72:75], v[228:231], v[196:199], v[72:75]
	ds_read_b128 v[212:215], v174 offset:2048
	v_mfma_f32_16x16x32_bf16 v[68:71], v[232:235], v[196:199], v[68:71]
	ds_read_b128 v[216:219], v174 offset:4096
	v_mfma_f32_16x16x32_bf16 v[64:67], v[236:239], v[196:199], v[64:67]
	ds_read_b128 v[220:223], v174 offset:6144
	v_mfma_f32_16x16x32_bf16 v[44:47], v[224:227], v[200:203], v[44:47]
	s_add_u32 m0, s101, 0x8000
	v_mfma_f32_16x16x32_bf16 v[40:43], v[228:231], v[200:203], v[40:43]
	global_load_lds_dwordx4 v[138:139], off
	v_lshl_add_u64 v[138:139], v[138:139], 0, s[34:35]
	v_mfma_f32_16x16x32_bf16 v[36:39], v[232:235], v[200:203], v[36:39]
	s_add_u32 m0, s101, 0xa000
	v_mfma_f32_16x16x32_bf16 v[32:35], v[236:239], v[200:203], v[32:35]
	global_load_lds_dwordx4 v[140:141], off
	v_lshl_add_u64 v[140:141], v[140:141], 0, s[34:35]
	v_mfma_f32_16x16x32_bf16 v[12:15], v[224:227], v[204:207], v[12:15]
	s_add_u32 m0, s101, 0xc000
	v_mfma_f32_16x16x32_bf16 v[8:11], v[228:231], v[204:207], v[8:11]
	global_load_lds_dwordx4 v[250:251], off
	v_lshl_add_u64 v[250:251], v[250:251], 0, s[34:35]
	v_mfma_f32_16x16x32_bf16 v[4:7], v[232:235], v[204:207], v[4:7]
	s_add_u32 m0, s101, 0xe000
	v_mfma_f32_16x16x32_bf16 v[0:3], v[236:239], v[204:207], v[0:3]
	global_load_lds_dwordx4 v[252:253], off
	v_lshl_add_u64 v[252:253], v[252:253], 0, s[34:35]
	s_waitcnt lgkmcnt(0)
	v_mfma_f32_16x16x32_bf16 v[124:127], v[208:211], v[176:179], v[124:127]
	ds_read_b128 v[224:227], v174 offset:8192
	v_mfma_f32_16x16x32_bf16 v[120:123], v[212:215], v[176:179], v[120:123]
	ds_read_b128 v[228:231], v174 offset:10240
	v_mfma_f32_16x16x32_bf16 v[116:119], v[216:219], v[176:179], v[116:119]
	ds_read_b128 v[232:235], v174 offset:12288
	v_mfma_f32_16x16x32_bf16 v[112:115], v[220:223], v[176:179], v[112:115]
	ds_read_b128 v[236:239], v174 offset:14336
	v_mfma_f32_16x16x32_bf16 v[92:95], v[208:211], v[180:183], v[92:95]
	s_add_u32 m0, s100, 0x20000
	v_mfma_f32_16x16x32_bf16 v[88:91], v[212:215], v[180:183], v[88:91]
	global_load_lds_dwordx4 v[240:241], off
	v_lshl_add_u64 v[240:241], v[240:241], 0, s[34:35]
	v_mfma_f32_16x16x32_bf16 v[84:87], v[216:219], v[180:183], v[84:87]
	s_add_u32 m0, s100, 0x22000
	v_mfma_f32_16x16x32_bf16 v[80:83], v[220:223], v[180:183], v[80:83]
	global_load_lds_dwordx4 v[242:243], off
	v_lshl_add_u64 v[242:243], v[242:243], 0, s[34:35]
	v_mfma_f32_16x16x32_bf16 v[60:63], v[208:211], v[184:187], v[60:63]
	s_add_u32 m0, s100, 0x24000
	v_mfma_f32_16x16x32_bf16 v[56:59], v[212:215], v[184:187], v[56:59]
	global_load_lds_dwordx4 v[244:245], off
	v_lshl_add_u64 v[244:245], v[244:245], 0, s[34:35]
	v_mfma_f32_16x16x32_bf16 v[52:55], v[216:219], v[184:187], v[52:55]
	s_add_u32 m0, s100, 0x26000
	v_mfma_f32_16x16x32_bf16 v[48:51], v[220:223], v[184:187], v[48:51]
	global_load_lds_dwordx4 v[246:247], off
	v_lshl_add_u64 v[246:247], v[246:247], 0, s[34:35]
	v_mfma_f32_16x16x32_bf16 v[28:31], v[208:211], v[188:191], v[28:31]
	v_mfma_f32_16x16x32_bf16 v[24:27], v[212:215], v[188:191], v[24:27]
	v_mfma_f32_16x16x32_bf16 v[20:23], v[216:219], v[188:191], v[20:23]
	v_mfma_f32_16x16x32_bf16 v[16:19], v[220:223], v[188:191], v[16:19]
	s_waitcnt lgkmcnt(0)
	v_mfma_f32_16x16x32_bf16 v[108:111], v[224:227], v[176:179], v[108:111]
	ds_read_b128 v[192:195], v173 offset:0
	v_mfma_f32_16x16x32_bf16 v[104:107], v[228:231], v[176:179], v[104:107]
	ds_read_b128 v[196:199], v173 offset:2048
	v_mfma_f32_16x16x32_bf16 v[100:103], v[232:235], v[176:179], v[100:103]
	ds_read_b128 v[200:203], v173 offset:4096
	v_mfma_f32_16x16x32_bf16 v[96:99], v[236:239], v[176:179], v[96:99]
	ds_read_b128 v[204:207], v173 offset:6144
	v_mfma_f32_16x16x32_bf16 v[76:79], v[224:227], v[180:183], v[76:79]
	ds_read_b128 v[208:211], v175 offset:0
	v_mfma_f32_16x16x32_bf16 v[72:75], v[228:231], v[180:183], v[72:75]
	ds_read_b128 v[212:215], v175 offset:2048
	v_mfma_f32_16x16x32_bf16 v[68:71], v[232:235], v[180:183], v[68:71]
	ds_read_b128 v[216:219], v175 offset:4096
	v_mfma_f32_16x16x32_bf16 v[64:67], v[236:239], v[180:183], v[64:67]
	ds_read_b128 v[220:223], v175 offset:6144
	v_mfma_f32_16x16x32_bf16 v[44:47], v[224:227], v[184:187], v[44:47]
	v_mfma_f32_16x16x32_bf16 v[40:43], v[228:231], v[184:187], v[40:43]
	v_mfma_f32_16x16x32_bf16 v[36:39], v[232:235], v[184:187], v[36:39]
	v_mfma_f32_16x16x32_bf16 v[32:35], v[236:239], v[184:187], v[32:35]
	v_mfma_f32_16x16x32_bf16 v[12:15], v[224:227], v[188:191], v[12:15]
	v_mfma_f32_16x16x32_bf16 v[8:11], v[228:231], v[188:191], v[8:11]
	v_mfma_f32_16x16x32_bf16 v[4:7], v[232:235], v[188:191], v[4:7]
	v_mfma_f32_16x16x32_bf16 v[0:3], v[236:239], v[188:191], v[0:3]
	s_waitcnt lgkmcnt(0)
	v_mfma_f32_16x16x32_bf16 v[124:127], v[208:211], v[192:195], v[124:127]
	ds_read_b128 v[224:227], v175 offset:8192
	v_mfma_f32_16x16x32_bf16 v[120:123], v[212:215], v[192:195], v[120:123]
	ds_read_b128 v[228:231], v175 offset:10240
	v_mfma_f32_16x16x32_bf16 v[116:119], v[216:219], v[192:195], v[116:119]
	ds_read_b128 v[232:235], v175 offset:12288
	v_mfma_f32_16x16x32_bf16 v[112:115], v[220:223], v[192:195], v[112:115]
	ds_read_b128 v[236:239], v175 offset:14336
	v_mfma_f32_16x16x32_bf16 v[92:95], v[208:211], v[196:199], v[92:95]
	v_mfma_f32_16x16x32_bf16 v[88:91], v[212:215], v[196:199], v[88:91]
	v_mfma_f32_16x16x32_bf16 v[84:87], v[216:219], v[196:199], v[84:87]
	v_mfma_f32_16x16x32_bf16 v[80:83], v[220:223], v[196:199], v[80:83]
	v_mfma_f32_16x16x32_bf16 v[60:63], v[208:211], v[200:203], v[60:63]
	v_mfma_f32_16x16x32_bf16 v[56:59], v[212:215], v[200:203], v[56:59]
	v_mfma_f32_16x16x32_bf16 v[52:55], v[216:219], v[200:203], v[52:55]
	v_mfma_f32_16x16x32_bf16 v[48:51], v[220:223], v[200:203], v[48:51]
	v_mfma_f32_16x16x32_bf16 v[28:31], v[208:211], v[204:207], v[28:31]
	v_mfma_f32_16x16x32_bf16 v[24:27], v[212:215], v[204:207], v[24:27]
	v_mfma_f32_16x16x32_bf16 v[20:23], v[216:219], v[204:207], v[20:23]
	v_mfma_f32_16x16x32_bf16 v[16:19], v[220:223], v[204:207], v[16:19]
	s_waitcnt lgkmcnt(0)
	s_waitcnt vmcnt(4)
	s_barrier
	s_add_i32 s46, s46, -1
	s_cmp_lg_u32 s46, 0
	s_cbranch_scc1 .Lgemm_p7_loop
	v_mfma_f32_16x16x32_bf16 v[108:111], v[224:227], v[192:195], v[108:111]
	ds_read_b128 v[176:179], v172 offset:32768
	v_mfma_f32_16x16x32_bf16 v[104:107], v[228:231], v[192:195], v[104:107]
	ds_read_b128 v[180:183], v172 offset:34816
	v_mfma_f32_16x16x32_bf16 v[100:103], v[232:235], v[192:195], v[100:103]
	ds_read_b128 v[184:187], v172 offset:36864
	v_mfma_f32_16x16x32_bf16 v[96:99], v[236:239], v[192:195], v[96:99]
	ds_read_b128 v[188:191], v172 offset:38912
	v_mfma_f32_16x16x32_bf16 v[76:79], v[224:227], v[196:199], v[76:79]
	ds_read_b128 v[208:211], v174 offset:32768
	v_mfma_f32_16x16x32_bf16 v[72:75], v[228:231], v[196:199], v[72:75]
	ds_read_b128 v[212:215], v174 offset:34816
	v_mfma_f32_16x16x32_bf16 v[68:71], v[232:235], v[196:199], v[68:71]
	ds_read_b128 v[216:219], v174 offset:36864
	v_mfma_f32_16x16x32_bf16 v[64:67], v[236:239], v[196:199], v[64:67]
	ds_read_b128 v[220:223], v174 offset:38912
	v_mfma_f32_16x16x32_bf16 v[44:47], v[224:227], v[200:203], v[44:47]
	s_mov_b32 m0, s101
	v_mfma_f32_16x16x32_bf16 v[40:43], v[228:231], v[200:203], v[40:43]
	global_load_lds_dwordx4 v[138:139], off
	v_lshl_add_u64 v[138:139], v[138:139], 0, s[34:35]
	v_mfma_f32_16x16x32_bf16 v[36:39], v[232:235], v[200:203], v[36:39]
	s_add_u32 m0, s101, 0x2000
	v_mfma_f32_16x16x32_bf16 v[32:35], v[236:239], v[200:203], v[32:35]
	global_load_lds_dwordx4 v[140:141], off
	v_lshl_add_u64 v[140:141], v[140:141], 0, s[34:35]
	v_mfma_f32_16x16x32_bf16 v[12:15], v[224:227], v[204:207], v[12:15]
	s_add_u32 m0, s101, 0x4000
	v_mfma_f32_16x16x32_bf16 v[8:11], v[228:231], v[204:207], v[8:11]
	global_load_lds_dwordx4 v[250:251], off
	v_lshl_add_u64 v[250:251], v[250:251], 0, s[34:35]
	v_mfma_f32_16x16x32_bf16 v[4:7], v[232:235], v[204:207], v[4:7]
	s_add_u32 m0, s101, 0x6000
	v_mfma_f32_16x16x32_bf16 v[0:3], v[236:239], v[204:207], v[0:3]
	global_load_lds_dwordx4 v[252:253], off
	v_lshl_add_u64 v[252:253], v[252:253], 0, s[34:35]
	s_waitcnt lgkmcnt(0)
	v_mfma_f32_16x16x32_bf16 v[124:127], v[208:211], v[176:179], v[124:127]
	ds_read_b128 v[224:227], v174 offset:40960
	v_mfma_f32_16x16x32_bf16 v[120:123], v[212:215], v[176:179], v[120:123]
	ds_read_b128 v[228:231], v174 offset:43008
	v_mfma_f32_16x16x32_bf16 v[116:119], v[216:219], v[176:179], v[116:119]
	ds_read_b128 v[232:235], v174 offset:45056
	v_mfma_f32_16x16x32_bf16 v[112:115], v[220:223], v[176:179], v[112:115]
	ds_read_b128 v[236:239], v174 offset:47104
	v_mfma_f32_16x16x32_bf16 v[92:95], v[208:211], v[180:183], v[92:95]
	s_mov_b32 m0, s100
	v_mfma_f32_16x16x32_bf16 v[88:91], v[212:215], v[180:183], v[88:91]
	global_load_lds_dwordx4 v[240:241], off
	v_lshl_add_u64 v[240:241], v[240:241], 0, s[34:35]
	v_mfma_f32_16x16x32_bf16 v[84:87], v[216:219], v[180:183], v[84:87]
	s_add_u32 m0, s100, 0x2000
	v_mfma_f32_16x16x32_bf16 v[80:83], v[220:223], v[180:183], v[80:83]
	global_load_lds_dwordx4 v[242:243], off
	v_lshl_add_u64 v[242:243], v[242:243], 0, s[34:35]
	v_mfma_f32_16x16x32_bf16 v[60:63], v[208:211], v[184:187], v[60:63]
	s_add_u32 m0, s100, 0x4000
	v_mfma_f32_16x16x32_bf16 v[56:59], v[212:215], v[184:187], v[56:59]
	global_load_lds_dwordx4 v[244:245], off
	v_lshl_add_u64 v[244:245], v[244:245], 0, s[34:35]
	v_mfma_f32_16x16x32_bf16 v[52:55], v[216:219], v[184:187], v[52:55]
	s_add_u32 m0, s100, 0x6000
	v_mfma_f32_16x16x32_bf16 v[48:51], v[220:223], v[184:187], v[48:51]
	global_load_lds_dwordx4 v[246:247], off
	v_lshl_add_u64 v[246:247], v[246:247], 0, s[34:35]
	v_mfma_f32_16x16x32_bf16 v[28:31], v[208:211], v[188:191], v[28:31]
	v_mfma_f32_16x16x32_bf16 v[24:27], v[212:215], v[188:191], v[24:27]
	v_mfma_f32_16x16x32_bf16 v[20:23], v[216:219], v[188:191], v[20:23]
	v_mfma_f32_16x16x32_bf16 v[16:19], v[220:223], v[188:191], v[16:19]
	s_waitcnt lgkmcnt(0)
	v_mfma_f32_16x16x32_bf16 v[108:111], v[224:227], v[176:179], v[108:111]
	ds_read_b128 v[192:195], v173 offset:32768
	v_mfma_f32_16x16x32_bf16 v[104:107], v[228:231], v[176:179], v[104:107]
	ds_read_b128 v[196:199], v173 offset:34816
	v_mfma_f32_16x16x32_bf16 v[100:103], v[232:235], v[176:179], v[100:103]
	ds_read_b128 v[200:203], v173 offset:36864
	v_mfma_f32_16x16x32_bf16 v[96:99], v[236:239], v[176:179], v[96:99]
	ds_read_b128 v[204:207], v173 offset:38912
	v_mfma_f32_16x16x32_bf16 v[76:79], v[224:227], v[180:183], v[76:79]
	ds_read_b128 v[208:211], v175 offset:32768
	v_mfma_f32_16x16x32_bf16 v[72:75], v[228:231], v[180:183], v[72:75]
	ds_read_b128 v[212:215], v175 offset:34816
	v_mfma_f32_16x16x32_bf16 v[68:71], v[232:235], v[180:183], v[68:71]
	ds_read_b128 v[216:219], v175 offset:36864
	v_mfma_f32_16x16x32_bf16 v[64:67], v[236:239], v[180:183], v[64:67]
	ds_read_b128 v[220:223], v175 offset:38912
	v_mfma_f32_16x16x32_bf16 v[44:47], v[224:227], v[184:187], v[44:47]
	v_mfma_f32_16x16x32_bf16 v[40:43], v[228:231], v[184:187], v[40:43]
	v_mfma_f32_16x16x32_bf16 v[36:39], v[232:235], v[184:187], v[36:39]
	v_mfma_f32_16x16x32_bf16 v[32:35], v[236:239], v[184:187], v[32:35]
	v_mfma_f32_16x16x32_bf16 v[12:15], v[224:227], v[188:191], v[12:15]
	v_mfma_f32_16x16x32_bf16 v[8:11], v[228:231], v[188:191], v[8:11]
	v_mfma_f32_16x16x32_bf16 v[4:7], v[232:235], v[188:191], v[4:7]
	v_mfma_f32_16x16x32_bf16 v[0:3], v[236:239], v[188:191], v[0:3]
	s_waitcnt lgkmcnt(0)
	v_mfma_f32_16x16x32_bf16 v[124:127], v[208:211], v[192:195], v[124:127]
	ds_read_b128 v[224:227], v175 offset:40960
	v_mfma_f32_16x16x32_bf16 v[120:123], v[212:215], v[192:195], v[120:123]
	ds_read_b128 v[228:231], v175 offset:43008
	v_mfma_f32_16x16x32_bf16 v[116:119], v[216:219], v[192:195], v[116:119]
	ds_read_b128 v[232:235], v175 offset:45056
	v_mfma_f32_16x16x32_bf16 v[112:115], v[220:223], v[192:195], v[112:115]
	ds_read_b128 v[236:239], v175 offset:47104
	v_mfma_f32_16x16x32_bf16 v[92:95], v[208:211], v[196:199], v[92:95]
	v_mfma_f32_16x16x32_bf16 v[88:91], v[212:215], v[196:199], v[88:91]
	v_mfma_f32_16x16x32_bf16 v[84:87], v[216:219], v[196:199], v[84:87]
	v_mfma_f32_16x16x32_bf16 v[80:83], v[220:223], v[196:199], v[80:83]
	v_mfma_f32_16x16x32_bf16 v[60:63], v[208:211], v[200:203], v[60:63]
	v_mfma_f32_16x16x32_bf16 v[56:59], v[212:215], v[200:203], v[56:59]
	v_mfma_f32_16x16x32_bf16 v[52:55], v[216:219], v[200:203], v[52:55]
	v_mfma_f32_16x16x32_bf16 v[48:51], v[220:223], v[200:203], v[48:51]
	v_mfma_f32_16x16x32_bf16 v[28:31], v[208:211], v[204:207], v[28:31]
	v_mfma_f32_16x16x32_bf16 v[24:27], v[212:215], v[204:207], v[24:27]
	v_mfma_f32_16x16x32_bf16 v[20:23], v[216:219], v[204:207], v[20:23]
	v_mfma_f32_16x16x32_bf16 v[16:19], v[220:223], v[204:207], v[16:19]
	s_waitcnt lgkmcnt(0)
	s_waitcnt vmcnt(4)
	s_barrier
	v_mfma_f32_16x16x32_bf16 v[108:111], v[224:227], v[192:195], v[108:111]
	ds_read_b128 v[176:179], v254 offset:0
	v_mfma_f32_16x16x32_bf16 v[104:107], v[228:231], v[192:195], v[104:107]
	ds_read_b128 v[180:183], v254 offset:2048
	v_mfma_f32_16x16x32_bf16 v[100:103], v[232:235], v[192:195], v[100:103]
	ds_read_b128 v[184:187], v254 offset:4096
	v_mfma_f32_16x16x32_bf16 v[96:99], v[236:239], v[192:195], v[96:99]
	ds_read_b128 v[188:191], v254 offset:6144
	v_mfma_f32_16x16x32_bf16 v[76:79], v[224:227], v[196:199], v[76:79]
	ds_read_b128 v[208:211], v174 offset:0
	v_mfma_f32_16x16x32_bf16 v[72:75], v[228:231], v[196:199], v[72:75]
	ds_read_b128 v[212:215], v174 offset:2048
	v_mfma_f32_16x16x32_bf16 v[68:71], v[232:235], v[196:199], v[68:71]
	ds_read_b128 v[216:219], v174 offset:4096
	v_mfma_f32_16x16x32_bf16 v[64:67], v[236:239], v[196:199], v[64:67]
	ds_read_b128 v[220:223], v174 offset:6144
	v_mfma_f32_16x16x32_bf16 v[44:47], v[224:227], v[200:203], v[44:47]
	s_add_u32 m0, s101, 0x8000
	v_mfma_f32_16x16x32_bf16 v[40:43], v[228:231], v[200:203], v[40:43]
	global_load_lds_dwordx4 v[138:139], off
	v_lshl_add_u64 v[138:139], v[138:139], 0, s[34:35]
	v_mfma_f32_16x16x32_bf16 v[36:39], v[232:235], v[200:203], v[36:39]
	s_add_u32 m0, s101, 0xa000
	v_mfma_f32_16x16x32_bf16 v[32:35], v[236:239], v[200:203], v[32:35]
	global_load_lds_dwordx4 v[140:141], off
	v_lshl_add_u64 v[140:141], v[140:141], 0, s[34:35]
	v_mfma_f32_16x16x32_bf16 v[12:15], v[224:227], v[204:207], v[12:15]
	s_add_u32 m0, s101, 0xc000
	v_mfma_f32_16x16x32_bf16 v[8:11], v[228:231], v[204:207], v[8:11]
	global_load_lds_dwordx4 v[250:251], off
	v_lshl_add_u64 v[250:251], v[250:251], 0, s[34:35]
	v_mfma_f32_16x16x32_bf16 v[4:7], v[232:235], v[204:207], v[4:7]
	s_add_u32 m0, s101, 0xe000
	v_mfma_f32_16x16x32_bf16 v[0:3], v[236:239], v[204:207], v[0:3]
	global_load_lds_dwordx4 v[252:253], off
	v_lshl_add_u64 v[252:253], v[252:253], 0, s[34:35]
	s_waitcnt lgkmcnt(0)
	v_mfma_f32_16x16x32_bf16 v[124:127], v[208:211], v[176:179], v[124:127]
	ds_read_b128 v[224:227], v174 offset:8192
	v_mfma_f32_16x16x32_bf16 v[120:123], v[212:215], v[176:179], v[120:123]
	ds_read_b128 v[228:231], v174 offset:10240
	v_mfma_f32_16x16x32_bf16 v[116:119], v[216:219], v[176:179], v[116:119]
	ds_read_b128 v[232:235], v174 offset:12288
	v_mfma_f32_16x16x32_bf16 v[112:115], v[220:223], v[176:179], v[112:115]
	ds_read_b128 v[236:239], v174 offset:14336
	v_mfma_f32_16x16x32_bf16 v[92:95], v[208:211], v[180:183], v[92:95]
	v_mfma_f32_16x16x32_bf16 v[88:91], v[212:215], v[180:183], v[88:91]
	v_mfma_f32_16x16x32_bf16 v[84:87], v[216:219], v[180:183], v[84:87]
	v_mfma_f32_16x16x32_bf16 v[80:83], v[220:223], v[180:183], v[80:83]
	v_mfma_f32_16x16x32_bf16 v[60:63], v[208:211], v[184:187], v[60:63]
	v_mfma_f32_16x16x32_bf16 v[56:59], v[212:215], v[184:187], v[56:59]
	v_mfma_f32_16x16x32_bf16 v[52:55], v[216:219], v[184:187], v[52:55]
	v_mfma_f32_16x16x32_bf16 v[48:51], v[220:223], v[184:187], v[48:51]
	v_mfma_f32_16x16x32_bf16 v[28:31], v[208:211], v[188:191], v[28:31]
	v_mfma_f32_16x16x32_bf16 v[24:27], v[212:215], v[188:191], v[24:27]
	v_mfma_f32_16x16x32_bf16 v[20:23], v[216:219], v[188:191], v[20:23]
	v_mfma_f32_16x16x32_bf16 v[16:19], v[220:223], v[188:191], v[16:19]
	s_waitcnt lgkmcnt(0)
	v_mfma_f32_16x16x32_bf16 v[108:111], v[224:227], v[176:179], v[108:111]
	ds_read_b128 v[192:195], v255 offset:0
	v_mfma_f32_16x16x32_bf16 v[104:107], v[228:231], v[176:179], v[104:107]
	ds_read_b128 v[196:199], v255 offset:2048
	v_mfma_f32_16x16x32_bf16 v[100:103], v[232:235], v[176:179], v[100:103]
	ds_read_b128 v[200:203], v255 offset:4096
	v_mfma_f32_16x16x32_bf16 v[96:99], v[236:239], v[176:179], v[96:99]
	ds_read_b128 v[204:207], v255 offset:6144
	v_mfma_f32_16x16x32_bf16 v[76:79], v[224:227], v[180:183], v[76:79]
	ds_read_b128 v[208:211], v175 offset:0
	v_mfma_f32_16x16x32_bf16 v[72:75], v[228:231], v[180:183], v[72:75]
	ds_read_b128 v[212:215], v175 offset:2048
	v_mfma_f32_16x16x32_bf16 v[68:71], v[232:235], v[180:183], v[68:71]
	ds_read_b128 v[216:219], v175 offset:4096
	v_mfma_f32_16x16x32_bf16 v[64:67], v[236:239], v[180:183], v[64:67]
	ds_read_b128 v[220:223], v175 offset:6144
	v_mfma_f32_16x16x32_bf16 v[44:47], v[224:227], v[184:187], v[44:47]
	v_mfma_f32_16x16x32_bf16 v[40:43], v[228:231], v[184:187], v[40:43]
	v_mfma_f32_16x16x32_bf16 v[36:39], v[232:235], v[184:187], v[36:39]
	v_mfma_f32_16x16x32_bf16 v[32:35], v[236:239], v[184:187], v[32:35]
	v_mfma_f32_16x16x32_bf16 v[12:15], v[224:227], v[188:191], v[12:15]
	v_mfma_f32_16x16x32_bf16 v[8:11], v[228:231], v[188:191], v[8:11]
	v_mfma_f32_16x16x32_bf16 v[4:7], v[232:235], v[188:191], v[4:7]
	v_mfma_f32_16x16x32_bf16 v[0:3], v[236:239], v[188:191], v[0:3]
	s_waitcnt lgkmcnt(0)
	v_mfma_f32_16x16x32_bf16 v[124:127], v[208:211], v[192:195], v[124:127]
	ds_read_b128 v[224:227], v175 offset:8192
	v_mfma_f32_16x16x32_bf16 v[120:123], v[212:215], v[192:195], v[120:123]
	ds_read_b128 v[228:231], v175 offset:10240
	v_mfma_f32_16x16x32_bf16 v[116:119], v[216:219], v[192:195], v[116:119]
	ds_read_b128 v[232:235], v175 offset:12288
	v_mfma_f32_16x16x32_bf16 v[112:115], v[220:223], v[192:195], v[112:115]
	ds_read_b128 v[236:239], v175 offset:14336
	v_mfma_f32_16x16x32_bf16 v[92:95], v[208:211], v[196:199], v[92:95]
	v_mfma_f32_16x16x32_bf16 v[88:91], v[212:215], v[196:199], v[88:91]
	v_mfma_f32_16x16x32_bf16 v[84:87], v[216:219], v[196:199], v[84:87]
	v_mfma_f32_16x16x32_bf16 v[80:83], v[220:223], v[196:199], v[80:83]
	v_mfma_f32_16x16x32_bf16 v[60:63], v[208:211], v[200:203], v[60:63]
	v_mfma_f32_16x16x32_bf16 v[56:59], v[212:215], v[200:203], v[56:59]
	v_mfma_f32_16x16x32_bf16 v[52:55], v[216:219], v[200:203], v[52:55]
	v_mfma_f32_16x16x32_bf16 v[48:51], v[220:223], v[200:203], v[48:51]
	v_mfma_f32_16x16x32_bf16 v[28:31], v[208:211], v[204:207], v[28:31]
	v_mfma_f32_16x16x32_bf16 v[24:27], v[212:215], v[204:207], v[24:27]
	v_mfma_f32_16x16x32_bf16 v[20:23], v[216:219], v[204:207], v[20:23]
	v_mfma_f32_16x16x32_bf16 v[16:19], v[220:223], v[204:207], v[16:19]
	s_waitcnt lgkmcnt(0)
	s_waitcnt vmcnt(0)
	s_barrier
	v_mfma_f32_16x16x32_bf16 v[108:111], v[224:227], v[192:195], v[108:111]
	ds_read_b128 v[176:179], v172 offset:0
	v_mfma_f32_16x16x32_bf16 v[104:107], v[228:231], v[192:195], v[104:107]
	ds_read_b128 v[180:183], v172 offset:2048
	v_mfma_f32_16x16x32_bf16 v[100:103], v[232:235], v[192:195], v[100:103]
	ds_read_b128 v[184:187], v172 offset:4096
	v_mfma_f32_16x16x32_bf16 v[96:99], v[236:239], v[192:195], v[96:99]
	ds_read_b128 v[188:191], v172 offset:6144
	v_mfma_f32_16x16x32_bf16 v[76:79], v[224:227], v[196:199], v[76:79]
	ds_read_b128 v[208:211], v174 offset:32768
	v_mfma_f32_16x16x32_bf16 v[72:75], v[228:231], v[196:199], v[72:75]
	ds_read_b128 v[212:215], v174 offset:34816
	v_mfma_f32_16x16x32_bf16 v[68:71], v[232:235], v[196:199], v[68:71]
	ds_read_b128 v[216:219], v174 offset:36864
	v_mfma_f32_16x16x32_bf16 v[64:67], v[236:239], v[196:199], v[64:67]
	ds_read_b128 v[220:223], v174 offset:38912
	v_mfma_f32_16x16x32_bf16 v[44:47], v[224:227], v[200:203], v[44:47]
	v_mfma_f32_16x16x32_bf16 v[40:43], v[228:231], v[200:203], v[40:43]
	v_mfma_f32_16x16x32_bf16 v[36:39], v[232:235], v[200:203], v[36:39]
	v_mfma_f32_16x16x32_bf16 v[32:35], v[236:239], v[200:203], v[32:35]
	v_mfma_f32_16x16x32_bf16 v[12:15], v[224:227], v[204:207], v[12:15]
	v_mfma_f32_16x16x32_bf16 v[8:11], v[228:231], v[204:207], v[8:11]
	v_mfma_f32_16x16x32_bf16 v[4:7], v[232:235], v[204:207], v[4:7]
	v_mfma_f32_16x16x32_bf16 v[0:3], v[236:239], v[204:207], v[0:3]
	s_waitcnt lgkmcnt(0)
	v_mfma_f32_16x16x32_bf16 v[124:127], v[208:211], v[176:179], v[124:127]
	ds_read_b128 v[224:227], v174 offset:40960
	v_mfma_f32_16x16x32_bf16 v[120:123], v[212:215], v[176:179], v[120:123]
	ds_read_b128 v[228:231], v174 offset:43008
	v_mfma_f32_16x16x32_bf16 v[116:119], v[216:219], v[176:179], v[116:119]
	ds_read_b128 v[232:235], v174 offset:45056
	v_mfma_f32_16x16x32_bf16 v[112:115], v[220:223], v[176:179], v[112:115]
	ds_read_b128 v[236:239], v174 offset:47104
	v_mfma_f32_16x16x32_bf16 v[92:95], v[208:211], v[180:183], v[92:95]
	v_mfma_f32_16x16x32_bf16 v[88:91], v[212:215], v[180:183], v[88:91]
	v_mfma_f32_16x16x32_bf16 v[84:87], v[216:219], v[180:183], v[84:87]
	v_mfma_f32_16x16x32_bf16 v[80:83], v[220:223], v[180:183], v[80:83]
	v_mfma_f32_16x16x32_bf16 v[60:63], v[208:211], v[184:187], v[60:63]
	v_mfma_f32_16x16x32_bf16 v[56:59], v[212:215], v[184:187], v[56:59]
	v_mfma_f32_16x16x32_bf16 v[52:55], v[216:219], v[184:187], v[52:55]
	v_mfma_f32_16x16x32_bf16 v[48:51], v[220:223], v[184:187], v[48:51]
	v_mfma_f32_16x16x32_bf16 v[28:31], v[208:211], v[188:191], v[28:31]
	v_mfma_f32_16x16x32_bf16 v[24:27], v[212:215], v[188:191], v[24:27]
	v_mfma_f32_16x16x32_bf16 v[20:23], v[216:219], v[188:191], v[20:23]
	v_mfma_f32_16x16x32_bf16 v[16:19], v[220:223], v[188:191], v[16:19]
	s_waitcnt lgkmcnt(0)
	v_mfma_f32_16x16x32_bf16 v[108:111], v[224:227], v[176:179], v[108:111]
	ds_read_b128 v[192:195], v173 offset:0
	v_mfma_f32_16x16x32_bf16 v[104:107], v[228:231], v[176:179], v[104:107]
	ds_read_b128 v[196:199], v173 offset:2048
	v_mfma_f32_16x16x32_bf16 v[100:103], v[232:235], v[176:179], v[100:103]
	ds_read_b128 v[200:203], v173 offset:4096
	v_mfma_f32_16x16x32_bf16 v[96:99], v[236:239], v[176:179], v[96:99]
	ds_read_b128 v[204:207], v173 offset:6144
	v_mfma_f32_16x16x32_bf16 v[76:79], v[224:227], v[180:183], v[76:79]
	ds_read_b128 v[208:211], v175 offset:32768
	v_mfma_f32_16x16x32_bf16 v[72:75], v[228:231], v[180:183], v[72:75]
	ds_read_b128 v[212:215], v175 offset:34816
	v_mfma_f32_16x16x32_bf16 v[68:71], v[232:235], v[180:183], v[68:71]
	ds_read_b128 v[216:219], v175 offset:36864
	v_mfma_f32_16x16x32_bf16 v[64:67], v[236:239], v[180:183], v[64:67]
	ds_read_b128 v[220:223], v175 offset:38912
	v_mfma_f32_16x16x32_bf16 v[44:47], v[224:227], v[184:187], v[44:47]
	v_mfma_f32_16x16x32_bf16 v[40:43], v[228:231], v[184:187], v[40:43]
	v_mfma_f32_16x16x32_bf16 v[36:39], v[232:235], v[184:187], v[36:39]
	v_mfma_f32_16x16x32_bf16 v[32:35], v[236:239], v[184:187], v[32:35]
	v_mfma_f32_16x16x32_bf16 v[12:15], v[224:227], v[188:191], v[12:15]
	v_mfma_f32_16x16x32_bf16 v[8:11], v[228:231], v[188:191], v[8:11]
	v_mfma_f32_16x16x32_bf16 v[4:7], v[232:235], v[188:191], v[4:7]
	v_mfma_f32_16x16x32_bf16 v[0:3], v[236:239], v[188:191], v[0:3]
	s_waitcnt lgkmcnt(0)
	v_mfma_f32_16x16x32_bf16 v[124:127], v[208:211], v[192:195], v[124:127]
	ds_read_b128 v[224:227], v175 offset:40960
	v_mfma_f32_16x16x32_bf16 v[120:123], v[212:215], v[192:195], v[120:123]
	ds_read_b128 v[228:231], v175 offset:43008
	v_mfma_f32_16x16x32_bf16 v[116:119], v[216:219], v[192:195], v[116:119]
	ds_read_b128 v[232:235], v175 offset:45056
	v_mfma_f32_16x16x32_bf16 v[112:115], v[220:223], v[192:195], v[112:115]
	ds_read_b128 v[236:239], v175 offset:47104
	v_mfma_f32_16x16x32_bf16 v[92:95], v[208:211], v[196:199], v[92:95]
	v_mfma_f32_16x16x32_bf16 v[88:91], v[212:215], v[196:199], v[88:91]
	v_mfma_f32_16x16x32_bf16 v[84:87], v[216:219], v[196:199], v[84:87]
	v_mfma_f32_16x16x32_bf16 v[80:83], v[220:223], v[196:199], v[80:83]
	v_mfma_f32_16x16x32_bf16 v[60:63], v[208:211], v[200:203], v[60:63]
	v_mfma_f32_16x16x32_bf16 v[56:59], v[212:215], v[200:203], v[56:59]
	v_mfma_f32_16x16x32_bf16 v[52:55], v[216:219], v[200:203], v[52:55]
	v_mfma_f32_16x16x32_bf16 v[48:51], v[220:223], v[200:203], v[48:51]
	v_mfma_f32_16x16x32_bf16 v[28:31], v[208:211], v[204:207], v[28:31]
	v_mfma_f32_16x16x32_bf16 v[24:27], v[212:215], v[204:207], v[24:27]
	v_mfma_f32_16x16x32_bf16 v[20:23], v[216:219], v[204:207], v[20:23]
	v_mfma_f32_16x16x32_bf16 v[16:19], v[220:223], v[204:207], v[16:19]
	s_waitcnt lgkmcnt(0)
	s_barrier
	v_mfma_f32_16x16x32_bf16 v[108:111], v[224:227], v[192:195], v[108:111]
	v_mfma_f32_16x16x32_bf16 v[104:107], v[228:231], v[192:195], v[104:107]
	v_mfma_f32_16x16x32_bf16 v[100:103], v[232:235], v[192:195], v[100:103]
	v_mfma_f32_16x16x32_bf16 v[96:99], v[236:239], v[192:195], v[96:99]
	v_mfma_f32_16x16x32_bf16 v[76:79], v[224:227], v[196:199], v[76:79]
	v_mfma_f32_16x16x32_bf16 v[72:75], v[228:231], v[196:199], v[72:75]
	v_mfma_f32_16x16x32_bf16 v[68:71], v[232:235], v[196:199], v[68:71]
	v_mfma_f32_16x16x32_bf16 v[64:67], v[236:239], v[196:199], v[64:67]
	v_mfma_f32_16x16x32_bf16 v[44:47], v[224:227], v[200:203], v[44:47]
	v_mfma_f32_16x16x32_bf16 v[40:43], v[228:231], v[200:203], v[40:43]
	v_mfma_f32_16x16x32_bf16 v[36:39], v[232:235], v[200:203], v[36:39]
	v_mfma_f32_16x16x32_bf16 v[32:35], v[236:239], v[200:203], v[32:35]
	v_mfma_f32_16x16x32_bf16 v[12:15], v[224:227], v[204:207], v[12:15]
	v_mfma_f32_16x16x32_bf16 v[8:11], v[228:231], v[204:207], v[8:11]
	v_mfma_f32_16x16x32_bf16 v[4:7], v[232:235], v[204:207], v[4:7]
	v_mfma_f32_16x16x32_bf16 v[0:3], v[236:239], v[204:207], v[0:3]
	s_nop 7
	s_nop 3
	s_branch .LBB0_1093

.LBB0_1136:
	v_add_u32_e32 v172, v153, v170
	v_add_u32_e32 v173, v153, v171
	v_add_u32_e32 v174, v169, v170
	v_add_u32_e32 v175, v169, v171
	s_mov_b64 s[100:101], 0x80
	v_lshl_add_u64 v[240:241], v[128:129], 0, s[100:101]
	s_mov_b64 s[100:101], 0x20080
	v_lshl_add_u64 v[242:243], v[128:129], 0, s[100:101]
	s_mov_b64 s[100:101], 0x40080
	v_lshl_add_u64 v[244:245], v[128:129], 0, s[100:101]
	s_mov_b64 s[100:101], 0x60080
	v_lshl_add_u64 v[246:247], v[128:129], 0, s[100:101]
	s_mov_b64 s[100:101], 0x80
	v_lshl_add_u64 v[138:139], v[130:131], 0, s[100:101]
	s_mov_b64 s[100:101], 0x20080
	v_lshl_add_u64 v[140:141], v[130:131], 0, s[100:101]
	s_mov_b64 s[100:101], 0x40080
	v_lshl_add_u64 v[250:251], v[130:131], 0, s[100:101]
	s_mov_b64 s[100:101], 0x60080
	v_lshl_add_u64 v[252:253], v[130:131], 0, s[100:101]
	v_readfirstlane_b32 s100, v144
	v_readfirstlane_b32 s101, v145
	v_add_u32_e32 v254, 0x20000, v172
	v_add_u32_e32 v255, 0x20000, v173
	s_nop 3
	ds_read_b128 v[176:179], v172 offset:0
	ds_read_b128 v[180:183], v172 offset:2048
	ds_read_b128 v[184:187], v172 offset:4096
	ds_read_b128 v[188:191], v172 offset:6144
	ds_read_b128 v[208:211], v174 offset:0
	ds_read_b128 v[212:215], v174 offset:2048
	ds_read_b128 v[216:219], v174 offset:4096
	ds_read_b128 v[220:223], v174 offset:6144
	s_add_u32 m0, s100, 0x8000
	s_nop 0
	global_load_lds_dwordx4 v[240:241], off
	v_lshl_add_u64 v[240:241], v[240:241], 0, s[34:35]
	s_add_u32 m0, s100, 0xa000
	s_nop 0
	global_load_lds_dwordx4 v[242:243], off
	v_lshl_add_u64 v[242:243], v[242:243], 0, s[34:35]
	s_add_u32 m0, s100, 0xc000
	s_nop 0
	global_load_lds_dwordx4 v[244:245], off
	v_lshl_add_u64 v[244:245], v[244:245], 0, s[34:35]
	s_add_u32 m0, s100, 0xe000
	s_nop 0
	global_load_lds_dwordx4 v[246:247], off
	v_lshl_add_u64 v[246:247], v[246:247], 0, s[34:35]
	s_add_u32 m0, s101, 0x8000
	s_nop 0
	global_load_lds_dwordx4 v[138:139], off
	v_lshl_add_u64 v[138:139], v[138:139], 0, s[34:35]
	s_add_u32 m0, s101, 0xa000
	s_nop 0
	global_load_lds_dwordx4 v[140:141], off
	v_lshl_add_u64 v[140:141], v[140:141], 0, s[34:35]
	s_add_u32 m0, s101, 0xc000
	s_nop 0
	global_load_lds_dwordx4 v[250:251], off
	v_lshl_add_u64 v[250:251], v[250:251], 0, s[34:35]
	s_add_u32 m0, s101, 0xe000
	s_nop 0
	global_load_lds_dwordx4 v[252:253], off
	v_lshl_add_u64 v[252:253], v[252:253], 0, s[34:35]
	s_waitcnt lgkmcnt(0)
	v_mfma_f32_16x16x32_bf16 v[124:127], v[208:211], v[176:179], v[124:127]
	ds_read_b128 v[224:227], v174 offset:8192
	v_mfma_f32_16x16x32_bf16 v[120:123], v[212:215], v[176:179], v[120:123]
	ds_read_b128 v[228:231], v174 offset:10240
	v_mfma_f32_16x16x32_bf16 v[116:119], v[216:219], v[176:179], v[116:119]
	ds_read_b128 v[232:235], v174 offset:12288
	v_mfma_f32_16x16x32_bf16 v[112:115], v[220:223], v[176:179], v[112:115]
	ds_read_b128 v[236:239], v174 offset:14336
	v_mfma_f32_16x16x32_bf16 v[92:95], v[208:211], v[180:183], v[92:95]
	s_add_u32 m0, s100, 0x20000
	v_mfma_f32_16x16x32_bf16 v[88:91], v[212:215], v[180:183], v[88:91]
	global_load_lds_dwordx4 v[240:241], off
	v_lshl_add_u64 v[240:241], v[240:241], 0, s[34:35]
	v_mfma_f32_16x16x32_bf16 v[84:87], v[216:219], v[180:183], v[84:87]
	s_add_u32 m0, s100, 0x22000
	v_mfma_f32_16x16x32_bf16 v[80:83], v[220:223], v[180:183], v[80:83]
	global_load_lds_dwordx4 v[242:243], off
	v_lshl_add_u64 v[242:243], v[242:243], 0, s[34:35]
	v_mfma_f32_16x16x32_bf16 v[60:63], v[208:211], v[184:187], v[60:63]
	s_add_u32 m0, s100, 0x24000
	v_mfma_f32_16x16x32_bf16 v[56:59], v[212:215], v[184:187], v[56:59]
	global_load_lds_dwordx4 v[244:245], off
	v_lshl_add_u64 v[244:245], v[244:245], 0, s[34:35]
	v_mfma_f32_16x16x32_bf16 v[52:55], v[216:219], v[184:187], v[52:55]
	s_add_u32 m0, s100, 0x26000
	v_mfma_f32_16x16x32_bf16 v[48:51], v[220:223], v[184:187], v[48:51]
	global_load_lds_dwordx4 v[246:247], off
	v_lshl_add_u64 v[246:247], v[246:247], 0, s[34:35]
	v_mfma_f32_16x16x32_bf16 v[28:31], v[208:211], v[188:191], v[28:31]
	v_mfma_f32_16x16x32_bf16 v[24:27], v[212:215], v[188:191], v[24:27]
	v_mfma_f32_16x16x32_bf16 v[20:23], v[216:219], v[188:191], v[20:23]
	v_mfma_f32_16x16x32_bf16 v[16:19], v[220:223], v[188:191], v[16:19]
	s_waitcnt lgkmcnt(0)
	v_mfma_f32_16x16x32_bf16 v[108:111], v[224:227], v[176:179], v[108:111]
	ds_read_b128 v[192:195], v173 offset:0
	v_mfma_f32_16x16x32_bf16 v[104:107], v[228:231], v[176:179], v[104:107]
	ds_read_b128 v[196:199], v173 offset:2048
	v_mfma_f32_16x16x32_bf16 v[100:103], v[232:235], v[176:179], v[100:103]
	ds_read_b128 v[200:203], v173 offset:4096
	v_mfma_f32_16x16x32_bf16 v[96:99], v[236:239], v[176:179], v[96:99]
	ds_read_b128 v[204:207], v173 offset:6144
	v_mfma_f32_16x16x32_bf16 v[76:79], v[224:227], v[180:183], v[76:79]
	ds_read_b128 v[208:211], v175 offset:0
	v_mfma_f32_16x16x32_bf16 v[72:75], v[228:231], v[180:183], v[72:75]
	ds_read_b128 v[212:215], v175 offset:2048
	v_mfma_f32_16x16x32_bf16 v[68:71], v[232:235], v[180:183], v[68:71]
	ds_read_b128 v[216:219], v175 offset:4096
	v_mfma_f32_16x16x32_bf16 v[64:67], v[236:239], v[180:183], v[64:67]
	ds_read_b128 v[220:223], v175 offset:6144
	v_mfma_f32_16x16x32_bf16 v[44:47], v[224:227], v[184:187], v[44:47]
	v_mfma_f32_16x16x32_bf16 v[40:43], v[228:231], v[184:187], v[40:43]
	v_mfma_f32_16x16x32_bf16 v[36:39], v[232:235], v[184:187], v[36:39]
	v_mfma_f32_16x16x32_bf16 v[32:35], v[236:239], v[184:187], v[32:35]
	v_mfma_f32_16x16x32_bf16 v[12:15], v[224:227], v[188:191], v[12:15]
	v_mfma_f32_16x16x32_bf16 v[8:11], v[228:231], v[188:191], v[8:11]
	v_mfma_f32_16x16x32_bf16 v[4:7], v[232:235], v[188:191], v[4:7]
	v_mfma_f32_16x16x32_bf16 v[0:3], v[236:239], v[188:191], v[0:3]
	s_waitcnt lgkmcnt(0)
	v_mfma_f32_16x16x32_bf16 v[124:127], v[208:211], v[192:195], v[124:127]
	ds_read_b128 v[224:227], v175 offset:8192
	v_mfma_f32_16x16x32_bf16 v[120:123], v[212:215], v[192:195], v[120:123]
	ds_read_b128 v[228:231], v175 offset:10240
	v_mfma_f32_16x16x32_bf16 v[116:119], v[216:219], v[192:195], v[116:119]
	ds_read_b128 v[232:235], v175 offset:12288
	v_mfma_f32_16x16x32_bf16 v[112:115], v[220:223], v[192:195], v[112:115]
	ds_read_b128 v[236:239], v175 offset:14336
	v_mfma_f32_16x16x32_bf16 v[92:95], v[208:211], v[196:199], v[92:95]
	v_mfma_f32_16x16x32_bf16 v[88:91], v[212:215], v[196:199], v[88:91]
	v_mfma_f32_16x16x32_bf16 v[84:87], v[216:219], v[196:199], v[84:87]
	v_mfma_f32_16x16x32_bf16 v[80:83], v[220:223], v[196:199], v[80:83]
	v_mfma_f32_16x16x32_bf16 v[60:63], v[208:211], v[200:203], v[60:63]
	v_mfma_f32_16x16x32_bf16 v[56:59], v[212:215], v[200:203], v[56:59]
	v_mfma_f32_16x16x32_bf16 v[52:55], v[216:219], v[200:203], v[52:55]
	v_mfma_f32_16x16x32_bf16 v[48:51], v[220:223], v[200:203], v[48:51]
	v_mfma_f32_16x16x32_bf16 v[28:31], v[208:211], v[204:207], v[28:31]
	v_mfma_f32_16x16x32_bf16 v[24:27], v[212:215], v[204:207], v[24:27]
	v_mfma_f32_16x16x32_bf16 v[20:23], v[216:219], v[204:207], v[20:23]
	v_mfma_f32_16x16x32_bf16 v[16:19], v[220:223], v[204:207], v[16:19]
	s_waitcnt lgkmcnt(0)
	s_waitcnt vmcnt(4)
	s_barrier
	s_mov_b32 s44, 2
.Lgemm_p9_loop:
	v_mfma_f32_16x16x32_bf16 v[108:111], v[224:227], v[192:195], v[108:111]
	ds_read_b128 v[176:179], v172 offset:32768
	v_mfma_f32_16x16x32_bf16 v[104:107], v[228:231], v[192:195], v[104:107]
	ds_read_b128 v[180:183], v172 offset:34816
	v_mfma_f32_16x16x32_bf16 v[100:103], v[232:235], v[192:195], v[100:103]
	ds_read_b128 v[184:187], v172 offset:36864
	v_mfma_f32_16x16x32_bf16 v[96:99], v[236:239], v[192:195], v[96:99]
	ds_read_b128 v[188:191], v172 offset:38912
	v_mfma_f32_16x16x32_bf16 v[76:79], v[224:227], v[196:199], v[76:79]
	ds_read_b128 v[208:211], v174 offset:32768
	v_mfma_f32_16x16x32_bf16 v[72:75], v[228:231], v[196:199], v[72:75]
	ds_read_b128 v[212:215], v174 offset:34816
	v_mfma_f32_16x16x32_bf16 v[68:71], v[232:235], v[196:199], v[68:71]
	ds_read_b128 v[216:219], v174 offset:36864
	v_mfma_f32_16x16x32_bf16 v[64:67], v[236:239], v[196:199], v[64:67]
	ds_read_b128 v[220:223], v174 offset:38912
	v_mfma_f32_16x16x32_bf16 v[44:47], v[224:227], v[200:203], v[44:47]
	s_mov_b32 m0, s101
	v_mfma_f32_16x16x32_bf16 v[40:43], v[228:231], v[200:203], v[40:43]
	global_load_lds_dwordx4 v[138:139], off
	v_lshl_add_u64 v[138:139], v[138:139], 0, s[34:35]
	v_mfma_f32_16x16x32_bf16 v[36:39], v[232:235], v[200:203], v[36:39]
	s_add_u32 m0, s101, 0x2000
	v_mfma_f32_16x16x32_bf16 v[32:35], v[236:239], v[200:203], v[32:35]
	global_load_lds_dwordx4 v[140:141], off
	v_lshl_add_u64 v[140:141], v[140:141], 0, s[34:35]
	v_mfma_f32_16x16x32_bf16 v[12:15], v[224:227], v[204:207], v[12:15]
	s_add_u32 m0, s101, 0x4000
	v_mfma_f32_16x16x32_bf16 v[8:11], v[228:231], v[204:207], v[8:11]
	global_load_lds_dwordx4 v[250:251], off
	v_lshl_add_u64 v[250:251], v[250:251], 0, s[34:35]
	v_mfma_f32_16x16x32_bf16 v[4:7], v[232:235], v[204:207], v[4:7]
	s_add_u32 m0, s101, 0x6000
	v_mfma_f32_16x16x32_bf16 v[0:3], v[236:239], v[204:207], v[0:3]
	global_load_lds_dwordx4 v[252:253], off
	v_lshl_add_u64 v[252:253], v[252:253], 0, s[34:35]
	s_waitcnt lgkmcnt(0)
	v_mfma_f32_16x16x32_bf16 v[124:127], v[208:211], v[176:179], v[124:127]
	ds_read_b128 v[224:227], v174 offset:40960
	v_mfma_f32_16x16x32_bf16 v[120:123], v[212:215], v[176:179], v[120:123]
	ds_read_b128 v[228:231], v174 offset:43008
	v_mfma_f32_16x16x32_bf16 v[116:119], v[216:219], v[176:179], v[116:119]
	ds_read_b128 v[232:235], v174 offset:45056
	v_mfma_f32_16x16x32_bf16 v[112:115], v[220:223], v[176:179], v[112:115]
	ds_read_b128 v[236:239], v174 offset:47104
	v_mfma_f32_16x16x32_bf16 v[92:95], v[208:211], v[180:183], v[92:95]
	s_mov_b32 m0, s100
	v_mfma_f32_16x16x32_bf16 v[88:91], v[212:215], v[180:183], v[88:91]
	global_load_lds_dwordx4 v[240:241], off
	v_lshl_add_u64 v[240:241], v[240:241], 0, s[34:35]
	v_mfma_f32_16x16x32_bf16 v[84:87], v[216:219], v[180:183], v[84:87]
	s_add_u32 m0, s100, 0x2000
	v_mfma_f32_16x16x32_bf16 v[80:83], v[220:223], v[180:183], v[80:83]
	global_load_lds_dwordx4 v[242:243], off
	v_lshl_add_u64 v[242:243], v[242:243], 0, s[34:35]
	v_mfma_f32_16x16x32_bf16 v[60:63], v[208:211], v[184:187], v[60:63]
	s_add_u32 m0, s100, 0x4000
	v_mfma_f32_16x16x32_bf16 v[56:59], v[212:215], v[184:187], v[56:59]
	global_load_lds_dwordx4 v[244:245], off
	v_lshl_add_u64 v[244:245], v[244:245], 0, s[34:35]
	v_mfma_f32_16x16x32_bf16 v[52:55], v[216:219], v[184:187], v[52:55]
	s_add_u32 m0, s100, 0x6000
	v_mfma_f32_16x16x32_bf16 v[48:51], v[220:223], v[184:187], v[48:51]
	global_load_lds_dwordx4 v[246:247], off
	v_lshl_add_u64 v[246:247], v[246:247], 0, s[34:35]
	v_mfma_f32_16x16x32_bf16 v[28:31], v[208:211], v[188:191], v[28:31]
	v_mfma_f32_16x16x32_bf16 v[24:27], v[212:215], v[188:191], v[24:27]
	v_mfma_f32_16x16x32_bf16 v[20:23], v[216:219], v[188:191], v[20:23]
	v_mfma_f32_16x16x32_bf16 v[16:19], v[220:223], v[188:191], v[16:19]
	s_waitcnt lgkmcnt(0)
	v_mfma_f32_16x16x32_bf16 v[108:111], v[224:227], v[176:179], v[108:111]
	ds_read_b128 v[192:195], v173 offset:32768
	v_mfma_f32_16x16x32_bf16 v[104:107], v[228:231], v[176:179], v[104:107]
	ds_read_b128 v[196:199], v173 offset:34816
	v_mfma_f32_16x16x32_bf16 v[100:103], v[232:235], v[176:179], v[100:103]
	ds_read_b128 v[200:203], v173 offset:36864
	v_mfma_f32_16x16x32_bf16 v[96:99], v[236:239], v[176:179], v[96:99]
	ds_read_b128 v[204:207], v173 offset:38912
	v_mfma_f32_16x16x32_bf16 v[76:79], v[224:227], v[180:183], v[76:79]
	ds_read_b128 v[208:211], v175 offset:32768
	v_mfma_f32_16x16x32_bf16 v[72:75], v[228:231], v[180:183], v[72:75]
	ds_read_b128 v[212:215], v175 offset:34816
	v_mfma_f32_16x16x32_bf16 v[68:71], v[232:235], v[180:183], v[68:71]
	ds_read_b128 v[216:219], v175 offset:36864
	v_mfma_f32_16x16x32_bf16 v[64:67], v[236:239], v[180:183], v[64:67]
	ds_read_b128 v[220:223], v175 offset:38912
	v_mfma_f32_16x16x32_bf16 v[44:47], v[224:227], v[184:187], v[44:47]
	v_mfma_f32_16x16x32_bf16 v[40:43], v[228:231], v[184:187], v[40:43]
	v_mfma_f32_16x16x32_bf16 v[36:39], v[232:235], v[184:187], v[36:39]
	v_mfma_f32_16x16x32_bf16 v[32:35], v[236:239], v[184:187], v[32:35]
	v_mfma_f32_16x16x32_bf16 v[12:15], v[224:227], v[188:191], v[12:15]
	v_mfma_f32_16x16x32_bf16 v[8:11], v[228:231], v[188:191], v[8:11]
	v_mfma_f32_16x16x32_bf16 v[4:7], v[232:235], v[188:191], v[4:7]
	v_mfma_f32_16x16x32_bf16 v[0:3], v[236:239], v[188:191], v[0:3]
	s_waitcnt lgkmcnt(0)
	v_mfma_f32_16x16x32_bf16 v[124:127], v[208:211], v[192:195], v[124:127]
	ds_read_b128 v[224:227], v175 offset:40960
	v_mfma_f32_16x16x32_bf16 v[120:123], v[212:215], v[192:195], v[120:123]
	ds_read_b128 v[228:231], v175 offset:43008
	v_mfma_f32_16x16x32_bf16 v[116:119], v[216:219], v[192:195], v[116:119]
	ds_read_b128 v[232:235], v175 offset:45056
	v_mfma_f32_16x16x32_bf16 v[112:115], v[220:223], v[192:195], v[112:115]
	ds_read_b128 v[236:239], v175 offset:47104
	v_mfma_f32_16x16x32_bf16 v[92:95], v[208:211], v[196:199], v[92:95]
	v_mfma_f32_16x16x32_bf16 v[88:91], v[212:215], v[196:199], v[88:91]
	v_mfma_f32_16x16x32_bf16 v[84:87], v[216:219], v[196:199], v[84:87]
	v_mfma_f32_16x16x32_bf16 v[80:83], v[220:223], v[196:199], v[80:83]
	v_mfma_f32_16x16x32_bf16 v[60:63], v[208:211], v[200:203], v[60:63]
	v_mfma_f32_16x16x32_bf16 v[56:59], v[212:215], v[200:203], v[56:59]
	v_mfma_f32_16x16x32_bf16 v[52:55], v[216:219], v[200:203], v[52:55]
	v_mfma_f32_16x16x32_bf16 v[48:51], v[220:223], v[200:203], v[48:51]
	v_mfma_f32_16x16x32_bf16 v[28:31], v[208:211], v[204:207], v[28:31]
	v_mfma_f32_16x16x32_bf16 v[24:27], v[212:215], v[204:207], v[24:27]
	v_mfma_f32_16x16x32_bf16 v[20:23], v[216:219], v[204:207], v[20:23]
	v_mfma_f32_16x16x32_bf16 v[16:19], v[220:223], v[204:207], v[16:19]
	s_waitcnt lgkmcnt(0)
	s_waitcnt vmcnt(4)
	s_barrier
	v_mfma_f32_16x16x32_bf16 v[108:111], v[224:227], v[192:195], v[108:111]
	ds_read_b128 v[176:179], v254 offset:0
	v_mfma_f32_16x16x32_bf16 v[104:107], v[228:231], v[192:195], v[104:107]
	ds_read_b128 v[180:183], v254 offset:2048
	v_mfma_f32_16x16x32_bf16 v[100:103], v[232:235], v[192:195], v[100:103]
	ds_read_b128 v[184:187], v254 offset:4096
	v_mfma_f32_16x16x32_bf16 v[96:99], v[236:239], v[192:195], v[96:99]
	ds_read_b128 v[188:191], v254 offset:6144
	v_mfma_f32_16x16x32_bf16 v[76:79], v[224:227], v[196:199], v[76:79]
	ds_read_b128 v[208:211], v174 offset:0
	v_mfma_f32_16x16x32_bf16 v[72:75], v[228:231], v[196:199], v[72:75]
	ds_read_b128 v[212:215], v174 offset:2048
	v_mfma_f32_16x16x32_bf16 v[68:71], v[232:235], v[196:199], v[68:71]
	ds_read_b128 v[216:219], v174 offset:4096
	v_mfma_f32_16x16x32_bf16 v[64:67], v[236:239], v[196:199], v[64:67]
	ds_read_b128 v[220:223], v174 offset:6144
	v_mfma_f32_16x16x32_bf16 v[44:47], v[224:227], v[200:203], v[44:47]
	s_add_u32 m0, s101, 0x8000
	v_mfma_f32_16x16x32_bf16 v[40:43], v[228:231], v[200:203], v[40:43]
	global_load_lds_dwordx4 v[138:139], off
	v_lshl_add_u64 v[138:139], v[138:139], 0, s[34:35]
	v_mfma_f32_16x16x32_bf16 v[36:39], v[232:235], v[200:203], v[36:39]
	s_add_u32 m0, s101, 0xa000
	v_mfma_f32_16x16x32_bf16 v[32:35], v[236:239], v[200:203], v[32:35]
	global_load_lds_dwordx4 v[140:141], off
	v_lshl_add_u64 v[140:141], v[140:141], 0, s[34:35]
	v_mfma_f32_16x16x32_bf16 v[12:15], v[224:227], v[204:207], v[12:15]
	s_add_u32 m0, s101, 0xc000
	v_mfma_f32_16x16x32_bf16 v[8:11], v[228:231], v[204:207], v[8:11]
	global_load_lds_dwordx4 v[250:251], off
	v_lshl_add_u64 v[250:251], v[250:251], 0, s[34:35]
	v_mfma_f32_16x16x32_bf16 v[4:7], v[232:235], v[204:207], v[4:7]
	s_add_u32 m0, s101, 0xe000
	v_mfma_f32_16x16x32_bf16 v[0:3], v[236:239], v[204:207], v[0:3]
	global_load_lds_dwordx4 v[252:253], off
	v_lshl_add_u64 v[252:253], v[252:253], 0, s[34:35]
	s_waitcnt lgkmcnt(0)
	v_mfma_f32_16x16x32_bf16 v[124:127], v[208:211], v[176:179], v[124:127]
	ds_read_b128 v[224:227], v174 offset:8192
	v_mfma_f32_16x16x32_bf16 v[120:123], v[212:215], v[176:179], v[120:123]
	ds_read_b128 v[228:231], v174 offset:10240
	v_mfma_f32_16x16x32_bf16 v[116:119], v[216:219], v[176:179], v[116:119]
	ds_read_b128 v[232:235], v174 offset:12288
	v_mfma_f32_16x16x32_bf16 v[112:115], v[220:223], v[176:179], v[112:115]
	ds_read_b128 v[236:239], v174 offset:14336
	v_mfma_f32_16x16x32_bf16 v[92:95], v[208:211], v[180:183], v[92:95]
	s_add_u32 m0, s100, 0x8000
	v_mfma_f32_16x16x32_bf16 v[88:91], v[212:215], v[180:183], v[88:91]
	global_load_lds_dwordx4 v[240:241], off
	v_lshl_add_u64 v[240:241], v[240:241], 0, s[34:35]
	v_mfma_f32_16x16x32_bf16 v[84:87], v[216:219], v[180:183], v[84:87]
	s_add_u32 m0, s100, 0xa000
	v_mfma_f32_16x16x32_bf16 v[80:83], v[220:223], v[180:183], v[80:83]
	global_load_lds_dwordx4 v[242:243], off
	v_lshl_add_u64 v[242:243], v[242:243], 0, s[34:35]
	v_mfma_f32_16x16x32_bf16 v[60:63], v[208:211], v[184:187], v[60:63]
	s_add_u32 m0, s100, 0xc000
	v_mfma_f32_16x16x32_bf16 v[56:59], v[212:215], v[184:187], v[56:59]
	global_load_lds_dwordx4 v[244:245], off
	v_lshl_add_u64 v[244:245], v[244:245], 0, s[34:35]
	v_mfma_f32_16x16x32_bf16 v[52:55], v[216:219], v[184:187], v[52:55]
	s_add_u32 m0, s100, 0xe000
	v_mfma_f32_16x16x32_bf16 v[48:51], v[220:223], v[184:187], v[48:51]
	global_load_lds_dwordx4 v[246:247], off
	v_lshl_add_u64 v[246:247], v[246:247], 0, s[34:35]
	v_mfma_f32_16x16x32_bf16 v[28:31], v[208:211], v[188:191], v[28:31]
	v_mfma_f32_16x16x32_bf16 v[24:27], v[212:215], v[188:191], v[24:27]
	v_mfma_f32_16x16x32_bf16 v[20:23], v[216:219], v[188:191], v[20:23]
	v_mfma_f32_16x16x32_bf16 v[16:19], v[220:223], v[188:191], v[16:19]
	s_waitcnt lgkmcnt(0)
	v_mfma_f32_16x16x32_bf16 v[108:111], v[224:227], v[176:179], v[108:111]
	ds_read_b128 v[192:195], v255 offset:0
	v_mfma_f32_16x16x32_bf16 v[104:107], v[228:231], v[176:179], v[104:107]
	ds_read_b128 v[196:199], v255 offset:2048
	v_mfma_f32_16x16x32_bf16 v[100:103], v[232:235], v[176:179], v[100:103]
	ds_read_b128 v[200:203], v255 offset:4096
	v_mfma_f32_16x16x32_bf16 v[96:99], v[236:239], v[176:179], v[96:99]
	ds_read_b128 v[204:207], v255 offset:6144
	v_mfma_f32_16x16x32_bf16 v[76:79], v[224:227], v[180:183], v[76:79]
	ds_read_b128 v[208:211], v175 offset:0
	v_mfma_f32_16x16x32_bf16 v[72:75], v[228:231], v[180:183], v[72:75]
	ds_read_b128 v[212:215], v175 offset:2048
	v_mfma_f32_16x16x32_bf16 v[68:71], v[232:235], v[180:183], v[68:71]
	ds_read_b128 v[216:219], v175 offset:4096
	v_mfma_f32_16x16x32_bf16 v[64:67], v[236:239], v[180:183], v[64:67]
	ds_read_b128 v[220:223], v175 offset:6144
	v_mfma_f32_16x16x32_bf16 v[44:47], v[224:227], v[184:187], v[44:47]
	v_mfma_f32_16x16x32_bf16 v[40:43], v[228:231], v[184:187], v[40:43]
	v_mfma_f32_16x16x32_bf16 v[36:39], v[232:235], v[184:187], v[36:39]
	v_mfma_f32_16x16x32_bf16 v[32:35], v[236:239], v[184:187], v[32:35]
	v_mfma_f32_16x16x32_bf16 v[12:15], v[224:227], v[188:191], v[12:15]
	v_mfma_f32_16x16x32_bf16 v[8:11], v[228:231], v[188:191], v[8:11]
	v_mfma_f32_16x16x32_bf16 v[4:7], v[232:235], v[188:191], v[4:7]
	v_mfma_f32_16x16x32_bf16 v[0:3], v[236:239], v[188:191], v[0:3]
	s_waitcnt lgkmcnt(0)
	v_mfma_f32_16x16x32_bf16 v[124:127], v[208:211], v[192:195], v[124:127]
	ds_read_b128 v[224:227], v175 offset:8192
	v_mfma_f32_16x16x32_bf16 v[120:123], v[212:215], v[192:195], v[120:123]
	ds_read_b128 v[228:231], v175 offset:10240
	v_mfma_f32_16x16x32_bf16 v[116:119], v[216:219], v[192:195], v[116:119]
	ds_read_b128 v[232:235], v175 offset:12288
	v_mfma_f32_16x16x32_bf16 v[112:115], v[220:223], v[192:195], v[112:115]
	ds_read_b128 v[236:239], v175 offset:14336
	v_mfma_f32_16x16x32_bf16 v[92:95], v[208:211], v[196:199], v[92:95]
	v_mfma_f32_16x16x32_bf16 v[88:91], v[212:215], v[196:199], v[88:91]
	v_mfma_f32_16x16x32_bf16 v[84:87], v[216:219], v[196:199], v[84:87]
	v_mfma_f32_16x16x32_bf16 v[80:83], v[220:223], v[196:199], v[80:83]
	v_mfma_f32_16x16x32_bf16 v[60:63], v[208:211], v[200:203], v[60:63]
	v_mfma_f32_16x16x32_bf16 v[56:59], v[212:215], v[200:203], v[56:59]
	v_mfma_f32_16x16x32_bf16 v[52:55], v[216:219], v[200:203], v[52:55]
	v_mfma_f32_16x16x32_bf16 v[48:51], v[220:223], v[200:203], v[48:51]
	v_mfma_f32_16x16x32_bf16 v[28:31], v[208:211], v[204:207], v[28:31]
	v_mfma_f32_16x16x32_bf16 v[24:27], v[212:215], v[204:207], v[24:27]
	v_mfma_f32_16x16x32_bf16 v[20:23], v[216:219], v[204:207], v[20:23]
	v_mfma_f32_16x16x32_bf16 v[16:19], v[220:223], v[204:207], v[16:19]
	s_waitcnt lgkmcnt(0)
	s_waitcnt vmcnt(4)
	s_barrier
	v_mfma_f32_16x16x32_bf16 v[108:111], v[224:227], v[192:195], v[108:111]
	ds_read_b128 v[176:179], v172 offset:0
	v_mfma_f32_16x16x32_bf16 v[104:107], v[228:231], v[192:195], v[104:107]
	ds_read_b128 v[180:183], v172 offset:2048
	v_mfma_f32_16x16x32_bf16 v[100:103], v[232:235], v[192:195], v[100:103]
	ds_read_b128 v[184:187], v172 offset:4096
	v_mfma_f32_16x16x32_bf16 v[96:99], v[236:239], v[192:195], v[96:99]
	ds_read_b128 v[188:191], v172 offset:6144
	v_mfma_f32_16x16x32_bf16 v[76:79], v[224:227], v[196:199], v[76:79]
	ds_read_b128 v[208:211], v174 offset:32768
	v_mfma_f32_16x16x32_bf16 v[72:75], v[228:231], v[196:199], v[72:75]
	ds_read_b128 v[212:215], v174 offset:34816
	v_mfma_f32_16x16x32_bf16 v[68:71], v[232:235], v[196:199], v[68:71]
	ds_read_b128 v[216:219], v174 offset:36864
	v_mfma_f32_16x16x32_bf16 v[64:67], v[236:239], v[196:199], v[64:67]
	ds_read_b128 v[220:223], v174 offset:38912
	v_mfma_f32_16x16x32_bf16 v[44:47], v[224:227], v[200:203], v[44:47]
	s_mov_b32 m0, s101
	v_mfma_f32_16x16x32_bf16 v[40:43], v[228:231], v[200:203], v[40:43]
	global_load_lds_dwordx4 v[138:139], off
	v_lshl_add_u64 v[138:139], v[138:139], 0, s[34:35]
	v_mfma_f32_16x16x32_bf16 v[36:39], v[232:235], v[200:203], v[36:39]
	s_add_u32 m0, s101, 0x2000
	v_mfma_f32_16x16x32_bf16 v[32:35], v[236:239], v[200:203], v[32:35]
	global_load_lds_dwordx4 v[140:141], off
	v_lshl_add_u64 v[140:141], v[140:141], 0, s[34:35]
	v_mfma_f32_16x16x32_bf16 v[12:15], v[224:227], v[204:207], v[12:15]
	s_add_u32 m0, s101, 0x4000
	v_mfma_f32_16x16x32_bf16 v[8:11], v[228:231], v[204:207], v[8:11]
	global_load_lds_dwordx4 v[250:251], off
	v_lshl_add_u64 v[250:251], v[250:251], 0, s[34:35]
	v_mfma_f32_16x16x32_bf16 v[4:7], v[232:235], v[204:207], v[4:7]
	s_add_u32 m0, s101, 0x6000
	v_mfma_f32_16x16x32_bf16 v[0:3], v[236:239], v[204:207], v[0:3]
	global_load_lds_dwordx4 v[252:253], off
	v_lshl_add_u64 v[252:253], v[252:253], 0, s[34:35]
	s_waitcnt lgkmcnt(0)
	v_mfma_f32_16x16x32_bf16 v[124:127], v[208:211], v[176:179], v[124:127]
	ds_read_b128 v[224:227], v174 offset:40960
	v_mfma_f32_16x16x32_bf16 v[120:123], v[212:215], v[176:179], v[120:123]
	ds_read_b128 v[228:231], v174 offset:43008
	v_mfma_f32_16x16x32_bf16 v[116:119], v[216:219], v[176:179], v[116:119]
	ds_read_b128 v[232:235], v174 offset:45056
	v_mfma_f32_16x16x32_bf16 v[112:115], v[220:223], v[176:179], v[112:115]
	ds_read_b128 v[236:239], v174 offset:47104
	v_mfma_f32_16x16x32_bf16 v[92:95], v[208:211], v[180:183], v[92:95]
	s_add_u32 m0, s100, 0x20000
	v_mfma_f32_16x16x32_bf16 v[88:91], v[212:215], v[180:183], v[88:91]
	global_load_lds_dwordx4 v[240:241], off
	v_lshl_add_u64 v[240:241], v[240:241], 0, s[34:35]
	v_mfma_f32_16x16x32_bf16 v[84:87], v[216:219], v[180:183], v[84:87]
	s_add_u32 m0, s100, 0x22000
	v_mfma_f32_16x16x32_bf16 v[80:83], v[220:223], v[180:183], v[80:83]
	global_load_lds_dwordx4 v[242:243], off
	v_lshl_add_u64 v[242:243], v[242:243], 0, s[34:35]
	v_mfma_f32_16x16x32_bf16 v[60:63], v[208:211], v[184:187], v[60:63]
	s_add_u32 m0, s100, 0x24000
	v_mfma_f32_16x16x32_bf16 v[56:59], v[212:215], v[184:187], v[56:59]
	global_load_lds_dwordx4 v[244:245], off
	v_lshl_add_u64 v[244:245], v[244:245], 0, s[34:35]
	v_mfma_f32_16x16x32_bf16 v[52:55], v[216:219], v[184:187], v[52:55]
	s_add_u32 m0, s100, 0x26000
	v_mfma_f32_16x16x32_bf16 v[48:51], v[220:223], v[184:187], v[48:51]
	global_load_lds_dwordx4 v[246:247], off
	v_lshl_add_u64 v[246:247], v[246:247], 0, s[34:35]
	v_mfma_f32_16x16x32_bf16 v[28:31], v[208:211], v[188:191], v[28:31]
	v_mfma_f32_16x16x32_bf16 v[24:27], v[212:215], v[188:191], v[24:27]
	v_mfma_f32_16x16x32_bf16 v[20:23], v[216:219], v[188:191], v[20:23]
	v_mfma_f32_16x16x32_bf16 v[16:19], v[220:223], v[188:191], v[16:19]
	s_waitcnt lgkmcnt(0)
	v_mfma_f32_16x16x32_bf16 v[108:111], v[224:227], v[176:179], v[108:111]
	ds_read_b128 v[192:195], v173 offset:0
	v_mfma_f32_16x16x32_bf16 v[104:107], v[228:231], v[176:179], v[104:107]
	ds_read_b128 v[196:199], v173 offset:2048
	v_mfma_f32_16x16x32_bf16 v[100:103], v[232:235], v[176:179], v[100:103]
	ds_read_b128 v[200:203], v173 offset:4096
	v_mfma_f32_16x16x32_bf16 v[96:99], v[236:239], v[176:179], v[96:99]
	ds_read_b128 v[204:207], v173 offset:6144
	v_mfma_f32_16x16x32_bf16 v[76:79], v[224:227], v[180:183], v[76:79]
	ds_read_b128 v[208:211], v175 offset:32768
	v_mfma_f32_16x16x32_bf16 v[72:75], v[228:231], v[180:183], v[72:75]
	ds_read_b128 v[212:215], v175 offset:34816
	v_mfma_f32_16x16x32_bf16 v[68:71], v[232:235], v[180:183], v[68:71]
	ds_read_b128 v[216:219], v175 offset:36864
	v_mfma_f32_16x16x32_bf16 v[64:67], v[236:239], v[180:183], v[64:67]
	ds_read_b128 v[220:223], v175 offset:38912
	v_mfma_f32_16x16x32_bf16 v[44:47], v[224:227], v[184:187], v[44:47]
	v_mfma_f32_16x16x32_bf16 v[40:43], v[228:231], v[184:187], v[40:43]
	v_mfma_f32_16x16x32_bf16 v[36:39], v[232:235], v[184:187], v[36:39]
	v_mfma_f32_16x16x32_bf16 v[32:35], v[236:239], v[184:187], v[32:35]
	v_mfma_f32_16x16x32_bf16 v[12:15], v[224:227], v[188:191], v[12:15]
	v_mfma_f32_16x16x32_bf16 v[8:11], v[228:231], v[188:191], v[8:11]
	v_mfma_f32_16x16x32_bf16 v[4:7], v[232:235], v[188:191], v[4:7]
	v_mfma_f32_16x16x32_bf16 v[0:3], v[236:239], v[188:191], v[0:3]
	s_waitcnt lgkmcnt(0)
	v_mfma_f32_16x16x32_bf16 v[124:127], v[208:211], v[192:195], v[124:127]
	ds_read_b128 v[224:227], v175 offset:40960
	v_mfma_f32_16x16x32_bf16 v[120:123], v[212:215], v[192:195], v[120:123]
	ds_read_b128 v[228:231], v175 offset:43008
	v_mfma_f32_16x16x32_bf16 v[116:119], v[216:219], v[192:195], v[116:119]
	ds_read_b128 v[232:235], v175 offset:45056
	v_mfma_f32_16x16x32_bf16 v[112:115], v[220:223], v[192:195], v[112:115]
	ds_read_b128 v[236:239], v175 offset:47104
	v_mfma_f32_16x16x32_bf16 v[92:95], v[208:211], v[196:199], v[92:95]
	v_mfma_f32_16x16x32_bf16 v[88:91], v[212:215], v[196:199], v[88:91]
	v_mfma_f32_16x16x32_bf16 v[84:87], v[216:219], v[196:199], v[84:87]
	v_mfma_f32_16x16x32_bf16 v[80:83], v[220:223], v[196:199], v[80:83]
	v_mfma_f32_16x16x32_bf16 v[60:63], v[208:211], v[200:203], v[60:63]
	v_mfma_f32_16x16x32_bf16 v[56:59], v[212:215], v[200:203], v[56:59]
	v_mfma_f32_16x16x32_bf16 v[52:55], v[216:219], v[200:203], v[52:55]
	v_mfma_f32_16x16x32_bf16 v[48:51], v[220:223], v[200:203], v[48:51]
	v_mfma_f32_16x16x32_bf16 v[28:31], v[208:211], v[204:207], v[28:31]
	v_mfma_f32_16x16x32_bf16 v[24:27], v[212:215], v[204:207], v[24:27]
	v_mfma_f32_16x16x32_bf16 v[20:23], v[216:219], v[204:207], v[20:23]
	v_mfma_f32_16x16x32_bf16 v[16:19], v[220:223], v[204:207], v[16:19]
	s_waitcnt lgkmcnt(0)
	s_waitcnt vmcnt(4)
	s_barrier
	v_mfma_f32_16x16x32_bf16 v[108:111], v[224:227], v[192:195], v[108:111]
	ds_read_b128 v[176:179], v172 offset:32768
	v_mfma_f32_16x16x32_bf16 v[104:107], v[228:231], v[192:195], v[104:107]
	ds_read_b128 v[180:183], v172 offset:34816
	v_mfma_f32_16x16x32_bf16 v[100:103], v[232:235], v[192:195], v[100:103]
	ds_read_b128 v[184:187], v172 offset:36864
	v_mfma_f32_16x16x32_bf16 v[96:99], v[236:239], v[192:195], v[96:99]
	ds_read_b128 v[188:191], v172 offset:38912
	v_mfma_f32_16x16x32_bf16 v[76:79], v[224:227], v[196:199], v[76:79]
	ds_read_b128 v[208:211], v174 offset:0
	v_mfma_f32_16x16x32_bf16 v[72:75], v[228:231], v[196:199], v[72:75]
	ds_read_b128 v[212:215], v174 offset:2048
	v_mfma_f32_16x16x32_bf16 v[68:71], v[232:235], v[196:199], v[68:71]
	ds_read_b128 v[216:219], v174 offset:4096
	v_mfma_f32_16x16x32_bf16 v[64:67], v[236:239], v[196:199], v[64:67]
	ds_read_b128 v[220:223], v174 offset:6144
	v_mfma_f32_16x16x32_bf16 v[44:47], v[224:227], v[200:203], v[44:47]
	s_add_u32 m0, s101, 0x8000
	v_mfma_f32_16x16x32_bf16 v[40:43], v[228:231], v[200:203], v[40:43]
	global_load_lds_dwordx4 v[138:139], off
	v_lshl_add_u64 v[138:139], v[138:139], 0, s[34:35]
	v_mfma_f32_16x16x32_bf16 v[36:39], v[232:235], v[200:203], v[36:39]
	s_add_u32 m0, s101, 0xa000
	v_mfma_f32_16x16x32_bf16 v[32:35], v[236:239], v[200:203], v[32:35]
	global_load_lds_dwordx4 v[140:141], off
	v_lshl_add_u64 v[140:141], v[140:141], 0, s[34:35]
	v_mfma_f32_16x16x32_bf16 v[12:15], v[224:227], v[204:207], v[12:15]
	s_add_u32 m0, s101, 0xc000
	v_mfma_f32_16x16x32_bf16 v[8:11], v[228:231], v[204:207], v[8:11]
	global_load_lds_dwordx4 v[250:251], off
	v_lshl_add_u64 v[250:251], v[250:251], 0, s[34:35]
	v_mfma_f32_16x16x32_bf16 v[4:7], v[232:235], v[204:207], v[4:7]
	s_add_u32 m0, s101, 0xe000
	v_mfma_f32_16x16x32_bf16 v[0:3], v[236:239], v[204:207], v[0:3]
	global_load_lds_dwordx4 v[252:253], off
	v_lshl_add_u64 v[252:253], v[252:253], 0, s[34:35]
	s_waitcnt lgkmcnt(0)
	v_mfma_f32_16x16x32_bf16 v[124:127], v[208:211], v[176:179], v[124:127]
	ds_read_b128 v[224:227], v174 offset:8192
	v_mfma_f32_16x16x32_bf16 v[120:123], v[212:215], v[176:179], v[120:123]
	ds_read_b128 v[228:231], v174 offset:10240
	v_mfma_f32_16x16x32_bf16 v[116:119], v[216:219], v[176:179], v[116:119]
	ds_read_b128 v[232:235], v174 offset:12288
	v_mfma_f32_16x16x32_bf16 v[112:115], v[220:223], v[176:179], v[112:115]
	ds_read_b128 v[236:239], v174 offset:14336
	v_mfma_f32_16x16x32_bf16 v[92:95], v[208:211], v[180:183], v[92:95]
	s_mov_b32 m0, s100
	v_mfma_f32_16x16x32_bf16 v[88:91], v[212:215], v[180:183], v[88:91]
	global_load_lds_dwordx4 v[240:241], off
	v_lshl_add_u64 v[240:241], v[240:241], 0, s[34:35]
	v_mfma_f32_16x16x32_bf16 v[84:87], v[216:219], v[180:183], v[84:87]
	s_add_u32 m0, s100, 0x2000
	v_mfma_f32_16x16x32_bf16 v[80:83], v[220:223], v[180:183], v[80:83]
	global_load_lds_dwordx4 v[242:243], off
	v_lshl_add_u64 v[242:243], v[242:243], 0, s[34:35]
	v_mfma_f32_16x16x32_bf16 v[60:63], v[208:211], v[184:187], v[60:63]
	s_add_u32 m0, s100, 0x4000
	v_mfma_f32_16x16x32_bf16 v[56:59], v[212:215], v[184:187], v[56:59]
	global_load_lds_dwordx4 v[244:245], off
	v_lshl_add_u64 v[244:245], v[244:245], 0, s[34:35]
	v_mfma_f32_16x16x32_bf16 v[52:55], v[216:219], v[184:187], v[52:55]
	s_add_u32 m0, s100, 0x6000
	v_mfma_f32_16x16x32_bf16 v[48:51], v[220:223], v[184:187], v[48:51]
	global_load_lds_dwordx4 v[246:247], off
	v_lshl_add_u64 v[246:247], v[246:247], 0, s[34:35]
	v_mfma_f32_16x16x32_bf16 v[28:31], v[208:211], v[188:191], v[28:31]
	v_mfma_f32_16x16x32_bf16 v[24:27], v[212:215], v[188:191], v[24:27]
	v_mfma_f32_16x16x32_bf16 v[20:23], v[216:219], v[188:191], v[20:23]
	v_mfma_f32_16x16x32_bf16 v[16:19], v[220:223], v[188:191], v[16:19]
	s_waitcnt lgkmcnt(0)
	v_mfma_f32_16x16x32_bf16 v[108:111], v[224:227], v[176:179], v[108:111]
	ds_read_b128 v[192:195], v173 offset:32768
	v_mfma_f32_16x16x32_bf16 v[104:107], v[228:231], v[176:179], v[104:107]
	ds_read_b128 v[196:199], v173 offset:34816
	v_mfma_f32_16x16x32_bf16 v[100:103], v[232:235], v[176:179], v[100:103]
	ds_read_b128 v[200:203], v173 offset:36864
	v_mfma_f32_16x16x32_bf16 v[96:99], v[236:239], v[176:179], v[96:99]
	ds_read_b128 v[204:207], v173 offset:38912
	v_mfma_f32_16x16x32_bf16 v[76:79], v[224:227], v[180:183], v[76:79]
	ds_read_b128 v[208:211], v175 offset:0
	v_mfma_f32_16x16x32_bf16 v[72:75], v[228:231], v[180:183], v[72:75]
	ds_read_b128 v[212:215], v175 offset:2048
	v_mfma_f32_16x16x32_bf16 v[68:71], v[232:235], v[180:183], v[68:71]
	ds_read_b128 v[216:219], v175 offset:4096
	v_mfma_f32_16x16x32_bf16 v[64:67], v[236:239], v[180:183], v[64:67]
	ds_read_b128 v[220:223], v175 offset:6144
	v_mfma_f32_16x16x32_bf16 v[44:47], v[224:227], v[184:187], v[44:47]
	v_mfma_f32_16x16x32_bf16 v[40:43], v[228:231], v[184:187], v[40:43]
	v_mfma_f32_16x16x32_bf16 v[36:39], v[232:235], v[184:187], v[36:39]
	v_mfma_f32_16x16x32_bf16 v[32:35], v[236:239], v[184:187], v[32:35]
	v_mfma_f32_16x16x32_bf16 v[12:15], v[224:227], v[188:191], v[12:15]
	v_mfma_f32_16x16x32_bf16 v[8:11], v[228:231], v[188:191], v[8:11]
	v_mfma_f32_16x16x32_bf16 v[4:7], v[232:235], v[188:191], v[4:7]
	v_mfma_f32_16x16x32_bf16 v[0:3], v[236:239], v[188:191], v[0:3]
	s_waitcnt lgkmcnt(0)
	v_mfma_f32_16x16x32_bf16 v[124:127], v[208:211], v[192:195], v[124:127]
	ds_read_b128 v[224:227], v175 offset:8192
	v_mfma_f32_16x16x32_bf16 v[120:123], v[212:215], v[192:195], v[120:123]
	ds_read_b128 v[228:231], v175 offset:10240
	v_mfma_f32_16x16x32_bf16 v[116:119], v[216:219], v[192:195], v[116:119]
	ds_read_b128 v[232:235], v175 offset:12288
	v_mfma_f32_16x16x32_bf16 v[112:115], v[220:223], v[192:195], v[112:115]
	ds_read_b128 v[236:239], v175 offset:14336
	v_mfma_f32_16x16x32_bf16 v[92:95], v[208:211], v[196:199], v[92:95]
	v_mfma_f32_16x16x32_bf16 v[88:91], v[212:215], v[196:199], v[88:91]
	v_mfma_f32_16x16x32_bf16 v[84:87], v[216:219], v[196:199], v[84:87]
	v_mfma_f32_16x16x32_bf16 v[80:83], v[220:223], v[196:199], v[80:83]
	v_mfma_f32_16x16x32_bf16 v[60:63], v[208:211], v[200:203], v[60:63]
	v_mfma_f32_16x16x32_bf16 v[56:59], v[212:215], v[200:203], v[56:59]
	v_mfma_f32_16x16x32_bf16 v[52:55], v[216:219], v[200:203], v[52:55]
	v_mfma_f32_16x16x32_bf16 v[48:51], v[220:223], v[200:203], v[48:51]
	v_mfma_f32_16x16x32_bf16 v[28:31], v[208:211], v[204:207], v[28:31]
	v_mfma_f32_16x16x32_bf16 v[24:27], v[212:215], v[204:207], v[24:27]
	v_mfma_f32_16x16x32_bf16 v[20:23], v[216:219], v[204:207], v[20:23]
	v_mfma_f32_16x16x32_bf16 v[16:19], v[220:223], v[204:207], v[16:19]
	s_waitcnt lgkmcnt(0)
	s_waitcnt vmcnt(4)
	s_barrier
	v_mfma_f32_16x16x32_bf16 v[108:111], v[224:227], v[192:195], v[108:111]
	ds_read_b128 v[176:179], v254 offset:0
	v_mfma_f32_16x16x32_bf16 v[104:107], v[228:231], v[192:195], v[104:107]
	ds_read_b128 v[180:183], v254 offset:2048
	v_mfma_f32_16x16x32_bf16 v[100:103], v[232:235], v[192:195], v[100:103]
	ds_read_b128 v[184:187], v254 offset:4096
	v_mfma_f32_16x16x32_bf16 v[96:99], v[236:239], v[192:195], v[96:99]
	ds_read_b128 v[188:191], v254 offset:6144
	v_mfma_f32_16x16x32_bf16 v[76:79], v[224:227], v[196:199], v[76:79]
	ds_read_b128 v[208:211], v174 offset:32768
	v_mfma_f32_16x16x32_bf16 v[72:75], v[228:231], v[196:199], v[72:75]
	ds_read_b128 v[212:215], v174 offset:34816
	v_mfma_f32_16x16x32_bf16 v[68:71], v[232:235], v[196:199], v[68:71]
	ds_read_b128 v[216:219], v174 offset:36864
	v_mfma_f32_16x16x32_bf16 v[64:67], v[236:239], v[196:199], v[64:67]
	ds_read_b128 v[220:223], v174 offset:38912
	v_mfma_f32_16x16x32_bf16 v[44:47], v[224:227], v[200:203], v[44:47]
	s_mov_b32 m0, s101
	v_mfma_f32_16x16x32_bf16 v[40:43], v[228:231], v[200:203], v[40:43]
	global_load_lds_dwordx4 v[138:139], off
	v_lshl_add_u64 v[138:139], v[138:139], 0, s[34:35]
	v_mfma_f32_16x16x32_bf16 v[36:39], v[232:235], v[200:203], v[36:39]
	s_add_u32 m0, s101, 0x2000
	v_mfma_f32_16x16x32_bf16 v[32:35], v[236:239], v[200:203], v[32:35]
	global_load_lds_dwordx4 v[140:141], off
	v_lshl_add_u64 v[140:141], v[140:141], 0, s[34:35]
	v_mfma_f32_16x16x32_bf16 v[12:15], v[224:227], v[204:207], v[12:15]
	s_add_u32 m0, s101, 0x4000
	v_mfma_f32_16x16x32_bf16 v[8:11], v[228:231], v[204:207], v[8:11]
	global_load_lds_dwordx4 v[250:251], off
	v_lshl_add_u64 v[250:251], v[250:251], 0, s[34:35]
	v_mfma_f32_16x16x32_bf16 v[4:7], v[232:235], v[204:207], v[4:7]
	s_add_u32 m0, s101, 0x6000
	v_mfma_f32_16x16x32_bf16 v[0:3], v[236:239], v[204:207], v[0:3]
	global_load_lds_dwordx4 v[252:253], off
	v_lshl_add_u64 v[252:253], v[252:253], 0, s[34:35]
	s_waitcnt lgkmcnt(0)
	v_mfma_f32_16x16x32_bf16 v[124:127], v[208:211], v[176:179], v[124:127]
	ds_read_b128 v[224:227], v174 offset:40960
	v_mfma_f32_16x16x32_bf16 v[120:123], v[212:215], v[176:179], v[120:123]
	ds_read_b128 v[228:231], v174 offset:43008
	v_mfma_f32_16x16x32_bf16 v[116:119], v[216:219], v[176:179], v[116:119]
	ds_read_b128 v[232:235], v174 offset:45056
	v_mfma_f32_16x16x32_bf16 v[112:115], v[220:223], v[176:179], v[112:115]
	ds_read_b128 v[236:239], v174 offset:47104
	v_mfma_f32_16x16x32_bf16 v[92:95], v[208:211], v[180:183], v[92:95]
	s_add_u32 m0, s100, 0x8000
	v_mfma_f32_16x16x32_bf16 v[88:91], v[212:215], v[180:183], v[88:91]
	global_load_lds_dwordx4 v[240:241], off
	v_lshl_add_u64 v[240:241], v[240:241], 0, s[34:35]
	v_mfma_f32_16x16x32_bf16 v[84:87], v[216:219], v[180:183], v[84:87]
	s_add_u32 m0, s100, 0xa000
	v_mfma_f32_16x16x32_bf16 v[80:83], v[220:223], v[180:183], v[80:83]
	global_load_lds_dwordx4 v[242:243], off
	v_lshl_add_u64 v[242:243], v[242:243], 0, s[34:35]
	v_mfma_f32_16x16x32_bf16 v[60:63], v[208:211], v[184:187], v[60:63]
	s_add_u32 m0, s100, 0xc000
	v_mfma_f32_16x16x32_bf16 v[56:59], v[212:215], v[184:187], v[56:59]
	global_load_lds_dwordx4 v[244:245], off
	v_lshl_add_u64 v[244:245], v[244:245], 0, s[34:35]
	v_mfma_f32_16x16x32_bf16 v[52:55], v[216:219], v[184:187], v[52:55]
	s_add_u32 m0, s100, 0xe000
	v_mfma_f32_16x16x32_bf16 v[48:51], v[220:223], v[184:187], v[48:51]
	global_load_lds_dwordx4 v[246:247], off
	v_lshl_add_u64 v[246:247], v[246:247], 0, s[34:35]
	v_mfma_f32_16x16x32_bf16 v[28:31], v[208:211], v[188:191], v[28:31]
	v_mfma_f32_16x16x32_bf16 v[24:27], v[212:215], v[188:191], v[24:27]
	v_mfma_f32_16x16x32_bf16 v[20:23], v[216:219], v[188:191], v[20:23]
	v_mfma_f32_16x16x32_bf16 v[16:19], v[220:223], v[188:191], v[16:19]
	s_waitcnt lgkmcnt(0)
	v_mfma_f32_16x16x32_bf16 v[108:111], v[224:227], v[176:179], v[108:111]
	ds_read_b128 v[192:195], v255 offset:0
	v_mfma_f32_16x16x32_bf16 v[104:107], v[228:231], v[176:179], v[104:107]
	ds_read_b128 v[196:199], v255 offset:2048
	v_mfma_f32_16x16x32_bf16 v[100:103], v[232:235], v[176:179], v[100:103]
	ds_read_b128 v[200:203], v255 offset:4096
	v_mfma_f32_16x16x32_bf16 v[96:99], v[236:239], v[176:179], v[96:99]
	ds_read_b128 v[204:207], v255 offset:6144
	v_mfma_f32_16x16x32_bf16 v[76:79], v[224:227], v[180:183], v[76:79]
	ds_read_b128 v[208:211], v175 offset:32768
	v_mfma_f32_16x16x32_bf16 v[72:75], v[228:231], v[180:183], v[72:75]
	ds_read_b128 v[212:215], v175 offset:34816
	v_mfma_f32_16x16x32_bf16 v[68:71], v[232:235], v[180:183], v[68:71]
	ds_read_b128 v[216:219], v175 offset:36864
	v_mfma_f32_16x16x32_bf16 v[64:67], v[236:239], v[180:183], v[64:67]
	ds_read_b128 v[220:223], v175 offset:38912
	v_mfma_f32_16x16x32_bf16 v[44:47], v[224:227], v[184:187], v[44:47]
	v_mfma_f32_16x16x32_bf16 v[40:43], v[228:231], v[184:187], v[40:43]
	v_mfma_f32_16x16x32_bf16 v[36:39], v[232:235], v[184:187], v[36:39]
	v_mfma_f32_16x16x32_bf16 v[32:35], v[236:239], v[184:187], v[32:35]
	v_mfma_f32_16x16x32_bf16 v[12:15], v[224:227], v[188:191], v[12:15]
	v_mfma_f32_16x16x32_bf16 v[8:11], v[228:231], v[188:191], v[8:11]
	v_mfma_f32_16x16x32_bf16 v[4:7], v[232:235], v[188:191], v[4:7]
	v_mfma_f32_16x16x32_bf16 v[0:3], v[236:239], v[188:191], v[0:3]
	s_waitcnt lgkmcnt(0)
	v_mfma_f32_16x16x32_bf16 v[124:127], v[208:211], v[192:195], v[124:127]
	ds_read_b128 v[224:227], v175 offset:40960
	v_mfma_f32_16x16x32_bf16 v[120:123], v[212:215], v[192:195], v[120:123]
	ds_read_b128 v[228:231], v175 offset:43008
	v_mfma_f32_16x16x32_bf16 v[116:119], v[216:219], v[192:195], v[116:119]
	ds_read_b128 v[232:235], v175 offset:45056
	v_mfma_f32_16x16x32_bf16 v[112:115], v[220:223], v[192:195], v[112:115]
	ds_read_b128 v[236:239], v175 offset:47104
	v_mfma_f32_16x16x32_bf16 v[92:95], v[208:211], v[196:199], v[92:95]
	v_mfma_f32_16x16x32_bf16 v[88:91], v[212:215], v[196:199], v[88:91]
	v_mfma_f32_16x16x32_bf16 v[84:87], v[216:219], v[196:199], v[84:87]
	v_mfma_f32_16x16x32_bf16 v[80:83], v[220:223], v[196:199], v[80:83]
	v_mfma_f32_16x16x32_bf16 v[60:63], v[208:211], v[200:203], v[60:63]
	v_mfma_f32_16x16x32_bf16 v[56:59], v[212:215], v[200:203], v[56:59]
	v_mfma_f32_16x16x32_bf16 v[52:55], v[216:219], v[200:203], v[52:55]
	v_mfma_f32_16x16x32_bf16 v[48:51], v[220:223], v[200:203], v[48:51]
	v_mfma_f32_16x16x32_bf16 v[28:31], v[208:211], v[204:207], v[28:31]
	v_mfma_f32_16x16x32_bf16 v[24:27], v[212:215], v[204:207], v[24:27]
	v_mfma_f32_16x16x32_bf16 v[20:23], v[216:219], v[204:207], v[20:23]
	v_mfma_f32_16x16x32_bf16 v[16:19], v[220:223], v[204:207], v[16:19]
	s_waitcnt lgkmcnt(0)
	s_waitcnt vmcnt(4)
	s_barrier
	v_mfma_f32_16x16x32_bf16 v[108:111], v[224:227], v[192:195], v[108:111]
	ds_read_b128 v[176:179], v172 offset:0
	v_mfma_f32_16x16x32_bf16 v[104:107], v[228:231], v[192:195], v[104:107]
	ds_read_b128 v[180:183], v172 offset:2048
	v_mfma_f32_16x16x32_bf16 v[100:103], v[232:235], v[192:195], v[100:103]
	ds_read_b128 v[184:187], v172 offset:4096
	v_mfma_f32_16x16x32_bf16 v[96:99], v[236:239], v[192:195], v[96:99]
	ds_read_b128 v[188:191], v172 offset:6144
	v_mfma_f32_16x16x32_bf16 v[76:79], v[224:227], v[196:199], v[76:79]
	ds_read_b128 v[208:211], v174 offset:0
	v_mfma_f32_16x16x32_bf16 v[72:75], v[228:231], v[196:199], v[72:75]
	ds_read_b128 v[212:215], v174 offset:2048
	v_mfma_f32_16x16x32_bf16 v[68:71], v[232:235], v[196:199], v[68:71]
	ds_read_b128 v[216:219], v174 offset:4096
	v_mfma_f32_16x16x32_bf16 v[64:67], v[236:239], v[196:199], v[64:67]
	ds_read_b128 v[220:223], v174 offset:6144
	v_mfma_f32_16x16x32_bf16 v[44:47], v[224:227], v[200:203], v[44:47]
	s_add_u32 m0, s101, 0x8000
	v_mfma_f32_16x16x32_bf16 v[40:43], v[228:231], v[200:203], v[40:43]
	global_load_lds_dwordx4 v[138:139], off
	v_lshl_add_u64 v[138:139], v[138:139], 0, s[34:35]
	v_mfma_f32_16x16x32_bf16 v[36:39], v[232:235], v[200:203], v[36:39]
	s_add_u32 m0, s101, 0xa000
	v_mfma_f32_16x16x32_bf16 v[32:35], v[236:239], v[200:203], v[32:35]
	global_load_lds_dwordx4 v[140:141], off
	v_lshl_add_u64 v[140:141], v[140:141], 0, s[34:35]
	v_mfma_f32_16x16x32_bf16 v[12:15], v[224:227], v[204:207], v[12:15]
	s_add_u32 m0, s101, 0xc000
	v_mfma_f32_16x16x32_bf16 v[8:11], v[228:231], v[204:207], v[8:11]
	global_load_lds_dwordx4 v[250:251], off
	v_lshl_add_u64 v[250:251], v[250:251], 0, s[34:35]
	v_mfma_f32_16x16x32_bf16 v[4:7], v[232:235], v[204:207], v[4:7]
	s_add_u32 m0, s101, 0xe000
	v_mfma_f32_16x16x32_bf16 v[0:3], v[236:239], v[204:207], v[0:3]
	global_load_lds_dwordx4 v[252:253], off
	v_lshl_add_u64 v[252:253], v[252:253], 0, s[34:35]
	s_waitcnt lgkmcnt(0)
	v_mfma_f32_16x16x32_bf16 v[124:127], v[208:211], v[176:179], v[124:127]
	ds_read_b128 v[224:227], v174 offset:8192
	v_mfma_f32_16x16x32_bf16 v[120:123], v[212:215], v[176:179], v[120:123]
	ds_read_b128 v[228:231], v174 offset:10240
	v_mfma_f32_16x16x32_bf16 v[116:119], v[216:219], v[176:179], v[116:119]
	ds_read_b128 v[232:235], v174 offset:12288
	v_mfma_f32_16x16x32_bf16 v[112:115], v[220:223], v[176:179], v[112:115]
	ds_read_b128 v[236:239], v174 offset:14336
	v_mfma_f32_16x16x32_bf16 v[92:95], v[208:211], v[180:183], v[92:95]
	s_add_u32 m0, s100, 0x20000
	v_mfma_f32_16x16x32_bf16 v[88:91], v[212:215], v[180:183], v[88:91]
	global_load_lds_dwordx4 v[240:241], off
	v_lshl_add_u64 v[240:241], v[240:241], 0, s[34:35]
	v_mfma_f32_16x16x32_bf16 v[84:87], v[216:219], v[180:183], v[84:87]
	s_add_u32 m0, s100, 0x22000
	v_mfma_f32_16x16x32_bf16 v[80:83], v[220:223], v[180:183], v[80:83]
	global_load_lds_dwordx4 v[242:243], off
	v_lshl_add_u64 v[242:243], v[242:243], 0, s[34:35]
	v_mfma_f32_16x16x32_bf16 v[60:63], v[208:211], v[184:187], v[60:63]
	s_add_u32 m0, s100, 0x24000
	v_mfma_f32_16x16x32_bf16 v[56:59], v[212:215], v[184:187], v[56:59]
	global_load_lds_dwordx4 v[244:245], off
	v_lshl_add_u64 v[244:245], v[244:245], 0, s[34:35]
	v_mfma_f32_16x16x32_bf16 v[52:55], v[216:219], v[184:187], v[52:55]
	s_add_u32 m0, s100, 0x26000
	v_mfma_f32_16x16x32_bf16 v[48:51], v[220:223], v[184:187], v[48:51]
	global_load_lds_dwordx4 v[246:247], off
	v_lshl_add_u64 v[246:247], v[246:247], 0, s[34:35]
	v_mfma_f32_16x16x32_bf16 v[28:31], v[208:211], v[188:191], v[28:31]
	v_mfma_f32_16x16x32_bf16 v[24:27], v[212:215], v[188:191], v[24:27]
	v_mfma_f32_16x16x32_bf16 v[20:23], v[216:219], v[188:191], v[20:23]
	v_mfma_f32_16x16x32_bf16 v[16:19], v[220:223], v[188:191], v[16:19]
	s_waitcnt lgkmcnt(0)
	v_mfma_f32_16x16x32_bf16 v[108:111], v[224:227], v[176:179], v[108:111]
	ds_read_b128 v[192:195], v173 offset:0
	v_mfma_f32_16x16x32_bf16 v[104:107], v[228:231], v[176:179], v[104:107]
	ds_read_b128 v[196:199], v173 offset:2048
	v_mfma_f32_16x16x32_bf16 v[100:103], v[232:235], v[176:179], v[100:103]
	ds_read_b128 v[200:203], v173 offset:4096
	v_mfma_f32_16x16x32_bf16 v[96:99], v[236:239], v[176:179], v[96:99]
	ds_read_b128 v[204:207], v173 offset:6144
	v_mfma_f32_16x16x32_bf16 v[76:79], v[224:227], v[180:183], v[76:79]
	ds_read_b128 v[208:211], v175 offset:0
	v_mfma_f32_16x16x32_bf16 v[72:75], v[228:231], v[180:183], v[72:75]
	ds_read_b128 v[212:215], v175 offset:2048
	v_mfma_f32_16x16x32_bf16 v[68:71], v[232:235], v[180:183], v[68:71]
	ds_read_b128 v[216:219], v175 offset:4096
	v_mfma_f32_16x16x32_bf16 v[64:67], v[236:239], v[180:183], v[64:67]
	ds_read_b128 v[220:223], v175 offset:6144
	v_mfma_f32_16x16x32_bf16 v[44:47], v[224:227], v[184:187], v[44:47]
	v_mfma_f32_16x16x32_bf16 v[40:43], v[228:231], v[184:187], v[40:43]
	v_mfma_f32_16x16x32_bf16 v[36:39], v[232:235], v[184:187], v[36:39]
	v_mfma_f32_16x16x32_bf16 v[32:35], v[236:239], v[184:187], v[32:35]
	v_mfma_f32_16x16x32_bf16 v[12:15], v[224:227], v[188:191], v[12:15]
	v_mfma_f32_16x16x32_bf16 v[8:11], v[228:231], v[188:191], v[8:11]
	v_mfma_f32_16x16x32_bf16 v[4:7], v[232:235], v[188:191], v[4:7]
	v_mfma_f32_16x16x32_bf16 v[0:3], v[236:239], v[188:191], v[0:3]
	s_waitcnt lgkmcnt(0)
	v_mfma_f32_16x16x32_bf16 v[124:127], v[208:211], v[192:195], v[124:127]
	ds_read_b128 v[224:227], v175 offset:8192
	v_mfma_f32_16x16x32_bf16 v[120:123], v[212:215], v[192:195], v[120:123]
	ds_read_b128 v[228:231], v175 offset:10240
	v_mfma_f32_16x16x32_bf16 v[116:119], v[216:219], v[192:195], v[116:119]
	ds_read_b128 v[232:235], v175 offset:12288
	v_mfma_f32_16x16x32_bf16 v[112:115], v[220:223], v[192:195], v[112:115]
	ds_read_b128 v[236:239], v175 offset:14336
	v_mfma_f32_16x16x32_bf16 v[92:95], v[208:211], v[196:199], v[92:95]
	v_mfma_f32_16x16x32_bf16 v[88:91], v[212:215], v[196:199], v[88:91]
	v_mfma_f32_16x16x32_bf16 v[84:87], v[216:219], v[196:199], v[84:87]
	v_mfma_f32_16x16x32_bf16 v[80:83], v[220:223], v[196:199], v[80:83]
	v_mfma_f32_16x16x32_bf16 v[60:63], v[208:211], v[200:203], v[60:63]
	v_mfma_f32_16x16x32_bf16 v[56:59], v[212:215], v[200:203], v[56:59]
	v_mfma_f32_16x16x32_bf16 v[52:55], v[216:219], v[200:203], v[52:55]
	v_mfma_f32_16x16x32_bf16 v[48:51], v[220:223], v[200:203], v[48:51]
	v_mfma_f32_16x16x32_bf16 v[28:31], v[208:211], v[204:207], v[28:31]
	v_mfma_f32_16x16x32_bf16 v[24:27], v[212:215], v[204:207], v[24:27]
	v_mfma_f32_16x16x32_bf16 v[20:23], v[216:219], v[204:207], v[20:23]
	v_mfma_f32_16x16x32_bf16 v[16:19], v[220:223], v[204:207], v[16:19]
	s_waitcnt lgkmcnt(0)
	s_waitcnt vmcnt(4)
	s_barrier
	s_add_i32 s44, s44, -1
	s_cmp_lg_u32 s44, 0
	s_cbranch_scc1 .Lgemm_p9_loop
	v_mfma_f32_16x16x32_bf16 v[108:111], v[224:227], v[192:195], v[108:111]
	ds_read_b128 v[176:179], v172 offset:32768
	v_mfma_f32_16x16x32_bf16 v[104:107], v[228:231], v[192:195], v[104:107]
	ds_read_b128 v[180:183], v172 offset:34816
	v_mfma_f32_16x16x32_bf16 v[100:103], v[232:235], v[192:195], v[100:103]
	ds_read_b128 v[184:187], v172 offset:36864
	v_mfma_f32_16x16x32_bf16 v[96:99], v[236:239], v[192:195], v[96:99]
	ds_read_b128 v[188:191], v172 offset:38912
	v_mfma_f32_16x16x32_bf16 v[76:79], v[224:227], v[196:199], v[76:79]
	ds_read_b128 v[208:211], v174 offset:32768
	v_mfma_f32_16x16x32_bf16 v[72:75], v[228:231], v[196:199], v[72:75]
	ds_read_b128 v[212:215], v174 offset:34816
	v_mfma_f32_16x16x32_bf16 v[68:71], v[232:235], v[196:199], v[68:71]
	ds_read_b128 v[216:219], v174 offset:36864
	v_mfma_f32_16x16x32_bf16 v[64:67], v[236:239], v[196:199], v[64:67]
	ds_read_b128 v[220:223], v174 offset:38912
	v_mfma_f32_16x16x32_bf16 v[44:47], v[224:227], v[200:203], v[44:47]
	s_mov_b32 m0, s101
	v_mfma_f32_16x16x32_bf16 v[40:43], v[228:231], v[200:203], v[40:43]
	global_load_lds_dwordx4 v[138:139], off
	v_lshl_add_u64 v[138:139], v[138:139], 0, s[34:35]
	v_mfma_f32_16x16x32_bf16 v[36:39], v[232:235], v[200:203], v[36:39]
	s_add_u32 m0, s101, 0x2000
	v_mfma_f32_16x16x32_bf16 v[32:35], v[236:239], v[200:203], v[32:35]
	global_load_lds_dwordx4 v[140:141], off
	v_lshl_add_u64 v[140:141], v[140:141], 0, s[34:35]
	v_mfma_f32_16x16x32_bf16 v[12:15], v[224:227], v[204:207], v[12:15]
	s_add_u32 m0, s101, 0x4000
	v_mfma_f32_16x16x32_bf16 v[8:11], v[228:231], v[204:207], v[8:11]
	global_load_lds_dwordx4 v[250:251], off
	v_lshl_add_u64 v[250:251], v[250:251], 0, s[34:35]
	v_mfma_f32_16x16x32_bf16 v[4:7], v[232:235], v[204:207], v[4:7]
	s_add_u32 m0, s101, 0x6000
	v_mfma_f32_16x16x32_bf16 v[0:3], v[236:239], v[204:207], v[0:3]
	global_load_lds_dwordx4 v[252:253], off
	v_lshl_add_u64 v[252:253], v[252:253], 0, s[34:35]
	s_waitcnt lgkmcnt(0)
	v_mfma_f32_16x16x32_bf16 v[124:127], v[208:211], v[176:179], v[124:127]
	ds_read_b128 v[224:227], v174 offset:40960
	v_mfma_f32_16x16x32_bf16 v[120:123], v[212:215], v[176:179], v[120:123]
	ds_read_b128 v[228:231], v174 offset:43008
	v_mfma_f32_16x16x32_bf16 v[116:119], v[216:219], v[176:179], v[116:119]
	ds_read_b128 v[232:235], v174 offset:45056
	v_mfma_f32_16x16x32_bf16 v[112:115], v[220:223], v[176:179], v[112:115]
	ds_read_b128 v[236:239], v174 offset:47104
	v_mfma_f32_16x16x32_bf16 v[92:95], v[208:211], v[180:183], v[92:95]
	s_mov_b32 m0, s100
	v_mfma_f32_16x16x32_bf16 v[88:91], v[212:215], v[180:183], v[88:91]
	global_load_lds_dwordx4 v[240:241], off
	v_lshl_add_u64 v[240:241], v[240:241], 0, s[34:35]
	v_mfma_f32_16x16x32_bf16 v[84:87], v[216:219], v[180:183], v[84:87]
	s_add_u32 m0, s100, 0x2000
	v_mfma_f32_16x16x32_bf16 v[80:83], v[220:223], v[180:183], v[80:83]
	global_load_lds_dwordx4 v[242:243], off
	v_lshl_add_u64 v[242:243], v[242:243], 0, s[34:35]
	v_mfma_f32_16x16x32_bf16 v[60:63], v[208:211], v[184:187], v[60:63]
	s_add_u32 m0, s100, 0x4000
	v_mfma_f32_16x16x32_bf16 v[56:59], v[212:215], v[184:187], v[56:59]
	global_load_lds_dwordx4 v[244:245], off
	v_lshl_add_u64 v[244:245], v[244:245], 0, s[34:35]
	v_mfma_f32_16x16x32_bf16 v[52:55], v[216:219], v[184:187], v[52:55]
	s_add_u32 m0, s100, 0x6000
	v_mfma_f32_16x16x32_bf16 v[48:51], v[220:223], v[184:187], v[48:51]
	global_load_lds_dwordx4 v[246:247], off
	v_lshl_add_u64 v[246:247], v[246:247], 0, s[34:35]
	v_mfma_f32_16x16x32_bf16 v[28:31], v[208:211], v[188:191], v[28:31]
	v_mfma_f32_16x16x32_bf16 v[24:27], v[212:215], v[188:191], v[24:27]
	v_mfma_f32_16x16x32_bf16 v[20:23], v[216:219], v[188:191], v[20:23]
	v_mfma_f32_16x16x32_bf16 v[16:19], v[220:223], v[188:191], v[16:19]
	s_waitcnt lgkmcnt(0)
	v_mfma_f32_16x16x32_bf16 v[108:111], v[224:227], v[176:179], v[108:111]
	ds_read_b128 v[192:195], v173 offset:32768
	v_mfma_f32_16x16x32_bf16 v[104:107], v[228:231], v[176:179], v[104:107]
	ds_read_b128 v[196:199], v173 offset:34816
	v_mfma_f32_16x16x32_bf16 v[100:103], v[232:235], v[176:179], v[100:103]
	ds_read_b128 v[200:203], v173 offset:36864
	v_mfma_f32_16x16x32_bf16 v[96:99], v[236:239], v[176:179], v[96:99]
	ds_read_b128 v[204:207], v173 offset:38912
	v_mfma_f32_16x16x32_bf16 v[76:79], v[224:227], v[180:183], v[76:79]
	ds_read_b128 v[208:211], v175 offset:32768
	v_mfma_f32_16x16x32_bf16 v[72:75], v[228:231], v[180:183], v[72:75]
	ds_read_b128 v[212:215], v175 offset:34816
	v_mfma_f32_16x16x32_bf16 v[68:71], v[232:235], v[180:183], v[68:71]
	ds_read_b128 v[216:219], v175 offset:36864
	v_mfma_f32_16x16x32_bf16 v[64:67], v[236:239], v[180:183], v[64:67]
	ds_read_b128 v[220:223], v175 offset:38912
	v_mfma_f32_16x16x32_bf16 v[44:47], v[224:227], v[184:187], v[44:47]
	v_mfma_f32_16x16x32_bf16 v[40:43], v[228:231], v[184:187], v[40:43]
	v_mfma_f32_16x16x32_bf16 v[36:39], v[232:235], v[184:187], v[36:39]
	v_mfma_f32_16x16x32_bf16 v[32:35], v[236:239], v[184:187], v[32:35]
	v_mfma_f32_16x16x32_bf16 v[12:15], v[224:227], v[188:191], v[12:15]
	v_mfma_f32_16x16x32_bf16 v[8:11], v[228:231], v[188:191], v[8:11]
	v_mfma_f32_16x16x32_bf16 v[4:7], v[232:235], v[188:191], v[4:7]
	v_mfma_f32_16x16x32_bf16 v[0:3], v[236:239], v[188:191], v[0:3]
	s_waitcnt lgkmcnt(0)
	v_mfma_f32_16x16x32_bf16 v[124:127], v[208:211], v[192:195], v[124:127]
	ds_read_b128 v[224:227], v175 offset:40960
	v_mfma_f32_16x16x32_bf16 v[120:123], v[212:215], v[192:195], v[120:123]
	ds_read_b128 v[228:231], v175 offset:43008
	v_mfma_f32_16x16x32_bf16 v[116:119], v[216:219], v[192:195], v[116:119]
	ds_read_b128 v[232:235], v175 offset:45056
	v_mfma_f32_16x16x32_bf16 v[112:115], v[220:223], v[192:195], v[112:115]
	ds_read_b128 v[236:239], v175 offset:47104
	v_mfma_f32_16x16x32_bf16 v[92:95], v[208:211], v[196:199], v[92:95]
	v_mfma_f32_16x16x32_bf16 v[88:91], v[212:215], v[196:199], v[88:91]
	v_mfma_f32_16x16x32_bf16 v[84:87], v[216:219], v[196:199], v[84:87]
	v_mfma_f32_16x16x32_bf16 v[80:83], v[220:223], v[196:199], v[80:83]
	v_mfma_f32_16x16x32_bf16 v[60:63], v[208:211], v[200:203], v[60:63]
	v_mfma_f32_16x16x32_bf16 v[56:59], v[212:215], v[200:203], v[56:59]
	v_mfma_f32_16x16x32_bf16 v[52:55], v[216:219], v[200:203], v[52:55]
	v_mfma_f32_16x16x32_bf16 v[48:51], v[220:223], v[200:203], v[48:51]
	v_mfma_f32_16x16x32_bf16 v[28:31], v[208:211], v[204:207], v[28:31]
	v_mfma_f32_16x16x32_bf16 v[24:27], v[212:215], v[204:207], v[24:27]
	v_mfma_f32_16x16x32_bf16 v[20:23], v[216:219], v[204:207], v[20:23]
	v_mfma_f32_16x16x32_bf16 v[16:19], v[220:223], v[204:207], v[16:19]
	s_waitcnt lgkmcnt(0)
	s_waitcnt vmcnt(4)
	s_barrier
	v_mfma_f32_16x16x32_bf16 v[108:111], v[224:227], v[192:195], v[108:111]
	ds_read_b128 v[176:179], v254 offset:0
	v_mfma_f32_16x16x32_bf16 v[104:107], v[228:231], v[192:195], v[104:107]
	ds_read_b128 v[180:183], v254 offset:2048
	v_mfma_f32_16x16x32_bf16 v[100:103], v[232:235], v[192:195], v[100:103]
	ds_read_b128 v[184:187], v254 offset:4096
	v_mfma_f32_16x16x32_bf16 v[96:99], v[236:239], v[192:195], v[96:99]
	ds_read_b128 v[188:191], v254 offset:6144
	v_mfma_f32_16x16x32_bf16 v[76:79], v[224:227], v[196:199], v[76:79]
	ds_read_b128 v[208:211], v174 offset:0
	v_mfma_f32_16x16x32_bf16 v[72:75], v[228:231], v[196:199], v[72:75]
	ds_read_b128 v[212:215], v174 offset:2048
	v_mfma_f32_16x16x32_bf16 v[68:71], v[232:235], v[196:199], v[68:71]
	ds_read_b128 v[216:219], v174 offset:4096
	v_mfma_f32_16x16x32_bf16 v[64:67], v[236:239], v[196:199], v[64:67]
	ds_read_b128 v[220:223], v174 offset:6144
	v_mfma_f32_16x16x32_bf16 v[44:47], v[224:227], v[200:203], v[44:47]
	s_add_u32 m0, s101, 0x8000
	v_mfma_f32_16x16x32_bf16 v[40:43], v[228:231], v[200:203], v[40:43]
	global_load_lds_dwordx4 v[138:139], off
	v_lshl_add_u64 v[138:139], v[138:139], 0, s[34:35]
	v_mfma_f32_16x16x32_bf16 v[36:39], v[232:235], v[200:203], v[36:39]
	s_add_u32 m0, s101, 0xa000
	v_mfma_f32_16x16x32_bf16 v[32:35], v[236:239], v[200:203], v[32:35]
	global_load_lds_dwordx4 v[140:141], off
	v_lshl_add_u64 v[140:141], v[140:141], 0, s[34:35]
	v_mfma_f32_16x16x32_bf16 v[12:15], v[224:227], v[204:207], v[12:15]
	s_add_u32 m0, s101, 0xc000
	v_mfma_f32_16x16x32_bf16 v[8:11], v[228:231], v[204:207], v[8:11]
	global_load_lds_dwordx4 v[250:251], off
	v_lshl_add_u64 v[250:251], v[250:251], 0, s[34:35]
	v_mfma_f32_16x16x32_bf16 v[4:7], v[232:235], v[204:207], v[4:7]
	s_add_u32 m0, s101, 0xe000
	v_mfma_f32_16x16x32_bf16 v[0:3], v[236:239], v[204:207], v[0:3]
	global_load_lds_dwordx4 v[252:253], off
	v_lshl_add_u64 v[252:253], v[252:253], 0, s[34:35]
	s_waitcnt lgkmcnt(0)
	v_mfma_f32_16x16x32_bf16 v[124:127], v[208:211], v[176:179], v[124:127]
	ds_read_b128 v[224:227], v174 offset:8192
	v_mfma_f32_16x16x32_bf16 v[120:123], v[212:215], v[176:179], v[120:123]
	ds_read_b128 v[228:231], v174 offset:10240
	v_mfma_f32_16x16x32_bf16 v[116:119], v[216:219], v[176:179], v[116:119]
	ds_read_b128 v[232:235], v174 offset:12288
	v_mfma_f32_16x16x32_bf16 v[112:115], v[220:223], v[176:179], v[112:115]
	ds_read_b128 v[236:239], v174 offset:14336
	v_mfma_f32_16x16x32_bf16 v[92:95], v[208:211], v[180:183], v[92:95]
	v_mfma_f32_16x16x32_bf16 v[88:91], v[212:215], v[180:183], v[88:91]
	v_mfma_f32_16x16x32_bf16 v[84:87], v[216:219], v[180:183], v[84:87]
	v_mfma_f32_16x16x32_bf16 v[80:83], v[220:223], v[180:183], v[80:83]
	v_mfma_f32_16x16x32_bf16 v[60:63], v[208:211], v[184:187], v[60:63]
	v_mfma_f32_16x16x32_bf16 v[56:59], v[212:215], v[184:187], v[56:59]
	v_mfma_f32_16x16x32_bf16 v[52:55], v[216:219], v[184:187], v[52:55]
	v_mfma_f32_16x16x32_bf16 v[48:51], v[220:223], v[184:187], v[48:51]
	v_mfma_f32_16x16x32_bf16 v[28:31], v[208:211], v[188:191], v[28:31]
	v_mfma_f32_16x16x32_bf16 v[24:27], v[212:215], v[188:191], v[24:27]
	v_mfma_f32_16x16x32_bf16 v[20:23], v[216:219], v[188:191], v[20:23]
	v_mfma_f32_16x16x32_bf16 v[16:19], v[220:223], v[188:191], v[16:19]
	s_waitcnt lgkmcnt(0)
	v_mfma_f32_16x16x32_bf16 v[108:111], v[224:227], v[176:179], v[108:111]
	ds_read_b128 v[192:195], v255 offset:0
	v_mfma_f32_16x16x32_bf16 v[104:107], v[228:231], v[176:179], v[104:107]
	ds_read_b128 v[196:199], v255 offset:2048
	v_mfma_f32_16x16x32_bf16 v[100:103], v[232:235], v[176:179], v[100:103]
	ds_read_b128 v[200:203], v255 offset:4096
	v_mfma_f32_16x16x32_bf16 v[96:99], v[236:239], v[176:179], v[96:99]
	ds_read_b128 v[204:207], v255 offset:6144
	v_mfma_f32_16x16x32_bf16 v[76:79], v[224:227], v[180:183], v[76:79]
	ds_read_b128 v[208:211], v175 offset:0
	v_mfma_f32_16x16x32_bf16 v[72:75], v[228:231], v[180:183], v[72:75]
	ds_read_b128 v[212:215], v175 offset:2048
	v_mfma_f32_16x16x32_bf16 v[68:71], v[232:235], v[180:183], v[68:71]
	ds_read_b128 v[216:219], v175 offset:4096
	v_mfma_f32_16x16x32_bf16 v[64:67], v[236:239], v[180:183], v[64:67]
	ds_read_b128 v[220:223], v175 offset:6144
	v_mfma_f32_16x16x32_bf16 v[44:47], v[224:227], v[184:187], v[44:47]
	v_mfma_f32_16x16x32_bf16 v[40:43], v[228:231], v[184:187], v[40:43]
	v_mfma_f32_16x16x32_bf16 v[36:39], v[232:235], v[184:187], v[36:39]
	v_mfma_f32_16x16x32_bf16 v[32:35], v[236:239], v[184:187], v[32:35]
	v_mfma_f32_16x16x32_bf16 v[12:15], v[224:227], v[188:191], v[12:15]
	v_mfma_f32_16x16x32_bf16 v[8:11], v[228:231], v[188:191], v[8:11]
	v_mfma_f32_16x16x32_bf16 v[4:7], v[232:235], v[188:191], v[4:7]
	v_mfma_f32_16x16x32_bf16 v[0:3], v[236:239], v[188:191], v[0:3]
	s_waitcnt lgkmcnt(0)
	v_mfma_f32_16x16x32_bf16 v[124:127], v[208:211], v[192:195], v[124:127]
	ds_read_b128 v[224:227], v175 offset:8192
	v_mfma_f32_16x16x32_bf16 v[120:123], v[212:215], v[192:195], v[120:123]
	ds_read_b128 v[228:231], v175 offset:10240
	v_mfma_f32_16x16x32_bf16 v[116:119], v[216:219], v[192:195], v[116:119]
	ds_read_b128 v[232:235], v175 offset:12288
	v_mfma_f32_16x16x32_bf16 v[112:115], v[220:223], v[192:195], v[112:115]
	ds_read_b128 v[236:239], v175 offset:14336
	v_mfma_f32_16x16x32_bf16 v[92:95], v[208:211], v[196:199], v[92:95]
	v_mfma_f32_16x16x32_bf16 v[88:91], v[212:215], v[196:199], v[88:91]
	v_mfma_f32_16x16x32_bf16 v[84:87], v[216:219], v[196:199], v[84:87]
	v_mfma_f32_16x16x32_bf16 v[80:83], v[220:223], v[196:199], v[80:83]
	v_mfma_f32_16x16x32_bf16 v[60:63], v[208:211], v[200:203], v[60:63]
	v_mfma_f32_16x16x32_bf16 v[56:59], v[212:215], v[200:203], v[56:59]
	v_mfma_f32_16x16x32_bf16 v[52:55], v[216:219], v[200:203], v[52:55]
	v_mfma_f32_16x16x32_bf16 v[48:51], v[220:223], v[200:203], v[48:51]
	v_mfma_f32_16x16x32_bf16 v[28:31], v[208:211], v[204:207], v[28:31]
	v_mfma_f32_16x16x32_bf16 v[24:27], v[212:215], v[204:207], v[24:27]
	v_mfma_f32_16x16x32_bf16 v[20:23], v[216:219], v[204:207], v[20:23]
	v_mfma_f32_16x16x32_bf16 v[16:19], v[220:223], v[204:207], v[16:19]
	s_waitcnt lgkmcnt(0)
	s_waitcnt vmcnt(0)
	s_barrier
	v_mfma_f32_16x16x32_bf16 v[108:111], v[224:227], v[192:195], v[108:111]
	ds_read_b128 v[176:179], v172 offset:0
	v_mfma_f32_16x16x32_bf16 v[104:107], v[228:231], v[192:195], v[104:107]
	ds_read_b128 v[180:183], v172 offset:2048
	v_mfma_f32_16x16x32_bf16 v[100:103], v[232:235], v[192:195], v[100:103]
	ds_read_b128 v[184:187], v172 offset:4096
	v_mfma_f32_16x16x32_bf16 v[96:99], v[236:239], v[192:195], v[96:99]
	ds_read_b128 v[188:191], v172 offset:6144
	v_mfma_f32_16x16x32_bf16 v[76:79], v[224:227], v[196:199], v[76:79]
	ds_read_b128 v[208:211], v174 offset:32768
	v_mfma_f32_16x16x32_bf16 v[72:75], v[228:231], v[196:199], v[72:75]
	ds_read_b128 v[212:215], v174 offset:34816
	v_mfma_f32_16x16x32_bf16 v[68:71], v[232:235], v[196:199], v[68:71]
	ds_read_b128 v[216:219], v174 offset:36864
	v_mfma_f32_16x16x32_bf16 v[64:67], v[236:239], v[196:199], v[64:67]
	ds_read_b128 v[220:223], v174 offset:38912
	v_mfma_f32_16x16x32_bf16 v[44:47], v[224:227], v[200:203], v[44:47]
	v_mfma_f32_16x16x32_bf16 v[40:43], v[228:231], v[200:203], v[40:43]
	v_mfma_f32_16x16x32_bf16 v[36:39], v[232:235], v[200:203], v[36:39]
	v_mfma_f32_16x16x32_bf16 v[32:35], v[236:239], v[200:203], v[32:35]
	v_mfma_f32_16x16x32_bf16 v[12:15], v[224:227], v[204:207], v[12:15]
	v_mfma_f32_16x16x32_bf16 v[8:11], v[228:231], v[204:207], v[8:11]
	v_mfma_f32_16x16x32_bf16 v[4:7], v[232:235], v[204:207], v[4:7]
	v_mfma_f32_16x16x32_bf16 v[0:3], v[236:239], v[204:207], v[0:3]
	s_waitcnt lgkmcnt(0)
	v_mfma_f32_16x16x32_bf16 v[124:127], v[208:211], v[176:179], v[124:127]
	ds_read_b128 v[224:227], v174 offset:40960
	v_mfma_f32_16x16x32_bf16 v[120:123], v[212:215], v[176:179], v[120:123]
	ds_read_b128 v[228:231], v174 offset:43008
	v_mfma_f32_16x16x32_bf16 v[116:119], v[216:219], v[176:179], v[116:119]
	ds_read_b128 v[232:235], v174 offset:45056
	v_mfma_f32_16x16x32_bf16 v[112:115], v[220:223], v[176:179], v[112:115]
	ds_read_b128 v[236:239], v174 offset:47104
	v_mfma_f32_16x16x32_bf16 v[92:95], v[208:211], v[180:183], v[92:95]
	v_mfma_f32_16x16x32_bf16 v[88:91], v[212:215], v[180:183], v[88:91]
	v_mfma_f32_16x16x32_bf16 v[84:87], v[216:219], v[180:183], v[84:87]
	v_mfma_f32_16x16x32_bf16 v[80:83], v[220:223], v[180:183], v[80:83]
	v_mfma_f32_16x16x32_bf16 v[60:63], v[208:211], v[184:187], v[60:63]
	v_mfma_f32_16x16x32_bf16 v[56:59], v[212:215], v[184:187], v[56:59]
	v_mfma_f32_16x16x32_bf16 v[52:55], v[216:219], v[184:187], v[52:55]
	v_mfma_f32_16x16x32_bf16 v[48:51], v[220:223], v[184:187], v[48:51]
	v_mfma_f32_16x16x32_bf16 v[28:31], v[208:211], v[188:191], v[28:31]
	v_mfma_f32_16x16x32_bf16 v[24:27], v[212:215], v[188:191], v[24:27]
	v_mfma_f32_16x16x32_bf16 v[20:23], v[216:219], v[188:191], v[20:23]
	v_mfma_f32_16x16x32_bf16 v[16:19], v[220:223], v[188:191], v[16:19]
	s_waitcnt lgkmcnt(0)
	v_mfma_f32_16x16x32_bf16 v[108:111], v[224:227], v[176:179], v[108:111]
	ds_read_b128 v[192:195], v173 offset:0
	v_mfma_f32_16x16x32_bf16 v[104:107], v[228:231], v[176:179], v[104:107]
	ds_read_b128 v[196:199], v173 offset:2048
	v_mfma_f32_16x16x32_bf16 v[100:103], v[232:235], v[176:179], v[100:103]
	ds_read_b128 v[200:203], v173 offset:4096
	v_mfma_f32_16x16x32_bf16 v[96:99], v[236:239], v[176:179], v[96:99]
	ds_read_b128 v[204:207], v173 offset:6144
	v_mfma_f32_16x16x32_bf16 v[76:79], v[224:227], v[180:183], v[76:79]
	ds_read_b128 v[208:211], v175 offset:32768
	v_mfma_f32_16x16x32_bf16 v[72:75], v[228:231], v[180:183], v[72:75]
	ds_read_b128 v[212:215], v175 offset:34816
	v_mfma_f32_16x16x32_bf16 v[68:71], v[232:235], v[180:183], v[68:71]
	ds_read_b128 v[216:219], v175 offset:36864
	v_mfma_f32_16x16x32_bf16 v[64:67], v[236:239], v[180:183], v[64:67]
	ds_read_b128 v[220:223], v175 offset:38912
	v_mfma_f32_16x16x32_bf16 v[44:47], v[224:227], v[184:187], v[44:47]
	v_mfma_f32_16x16x32_bf16 v[40:43], v[228:231], v[184:187], v[40:43]
	v_mfma_f32_16x16x32_bf16 v[36:39], v[232:235], v[184:187], v[36:39]
	v_mfma_f32_16x16x32_bf16 v[32:35], v[236:239], v[184:187], v[32:35]
	v_mfma_f32_16x16x32_bf16 v[12:15], v[224:227], v[188:191], v[12:15]
	v_mfma_f32_16x16x32_bf16 v[8:11], v[228:231], v[188:191], v[8:11]
	v_mfma_f32_16x16x32_bf16 v[4:7], v[232:235], v[188:191], v[4:7]
	v_mfma_f32_16x16x32_bf16 v[0:3], v[236:239], v[188:191], v[0:3]
	s_waitcnt lgkmcnt(0)
	v_mfma_f32_16x16x32_bf16 v[124:127], v[208:211], v[192:195], v[124:127]
	ds_read_b128 v[224:227], v175 offset:40960
	v_mfma_f32_16x16x32_bf16 v[120:123], v[212:215], v[192:195], v[120:123]
	ds_read_b128 v[228:231], v175 offset:43008
	v_mfma_f32_16x16x32_bf16 v[116:119], v[216:219], v[192:195], v[116:119]
	ds_read_b128 v[232:235], v175 offset:45056
	v_mfma_f32_16x16x32_bf16 v[112:115], v[220:223], v[192:195], v[112:115]
	ds_read_b128 v[236:239], v175 offset:47104
	v_mfma_f32_16x16x32_bf16 v[92:95], v[208:211], v[196:199], v[92:95]
	v_mfma_f32_16x16x32_bf16 v[88:91], v[212:215], v[196:199], v[88:91]
	v_mfma_f32_16x16x32_bf16 v[84:87], v[216:219], v[196:199], v[84:87]
	v_mfma_f32_16x16x32_bf16 v[80:83], v[220:223], v[196:199], v[80:83]
	v_mfma_f32_16x16x32_bf16 v[60:63], v[208:211], v[200:203], v[60:63]
	v_mfma_f32_16x16x32_bf16 v[56:59], v[212:215], v[200:203], v[56:59]
	v_mfma_f32_16x16x32_bf16 v[52:55], v[216:219], v[200:203], v[52:55]
	v_mfma_f32_16x16x32_bf16 v[48:51], v[220:223], v[200:203], v[48:51]
	v_mfma_f32_16x16x32_bf16 v[28:31], v[208:211], v[204:207], v[28:31]
	v_mfma_f32_16x16x32_bf16 v[24:27], v[212:215], v[204:207], v[24:27]
	v_mfma_f32_16x16x32_bf16 v[20:23], v[216:219], v[204:207], v[20:23]
	v_mfma_f32_16x16x32_bf16 v[16:19], v[220:223], v[204:207], v[16:19]
	s_waitcnt lgkmcnt(0)
	s_barrier
	v_mfma_f32_16x16x32_bf16 v[108:111], v[224:227], v[192:195], v[108:111]
	v_mfma_f32_16x16x32_bf16 v[104:107], v[228:231], v[192:195], v[104:107]
	v_mfma_f32_16x16x32_bf16 v[100:103], v[232:235], v[192:195], v[100:103]
	v_mfma_f32_16x16x32_bf16 v[96:99], v[236:239], v[192:195], v[96:99]
	v_mfma_f32_16x16x32_bf16 v[76:79], v[224:227], v[196:199], v[76:79]
	v_mfma_f32_16x16x32_bf16 v[72:75], v[228:231], v[196:199], v[72:75]
	v_mfma_f32_16x16x32_bf16 v[68:71], v[232:235], v[196:199], v[68:71]
	v_mfma_f32_16x16x32_bf16 v[64:67], v[236:239], v[196:199], v[64:67]
	v_mfma_f32_16x16x32_bf16 v[44:47], v[224:227], v[200:203], v[44:47]
	v_mfma_f32_16x16x32_bf16 v[40:43], v[228:231], v[200:203], v[40:43]
	v_mfma_f32_16x16x32_bf16 v[36:39], v[232:235], v[200:203], v[36:39]
	v_mfma_f32_16x16x32_bf16 v[32:35], v[236:239], v[200:203], v[32:35]
	v_mfma_f32_16x16x32_bf16 v[12:15], v[224:227], v[204:207], v[12:15]
	v_mfma_f32_16x16x32_bf16 v[8:11], v[228:231], v[204:207], v[8:11]
	v_mfma_f32_16x16x32_bf16 v[4:7], v[232:235], v[204:207], v[4:7]
	v_mfma_f32_16x16x32_bf16 v[0:3], v[236:239], v[204:207], v[0:3]
	s_nop 7
	s_nop 3
	s_branch .LBB0_1124

.LBB0_1157:
	v_add_u32_e32 v172, v153, v170
	v_add_u32_e32 v173, v153, v171
	v_add_u32_e32 v174, v169, v170
	v_add_u32_e32 v175, v169, v171
	s_mov_b64 s[100:101], 0x80
	v_lshl_add_u64 v[240:241], v[128:129], 0, s[100:101]
	s_mov_b64 s[100:101], 0x80080
	v_lshl_add_u64 v[242:243], v[128:129], 0, s[100:101]
	s_mov_b64 s[100:101], 0x100080
	v_lshl_add_u64 v[244:245], v[128:129], 0, s[100:101]
	s_mov_b64 s[100:101], 0x180080
	v_lshl_add_u64 v[246:247], v[128:129], 0, s[100:101]
	s_mov_b64 s[100:101], 0x80
	v_lshl_add_u64 v[138:139], v[130:131], 0, s[100:101]
	s_mov_b64 s[100:101], 0x80080
	v_lshl_add_u64 v[140:141], v[130:131], 0, s[100:101]
	s_mov_b64 s[100:101], 0x100080
	v_lshl_add_u64 v[250:251], v[130:131], 0, s[100:101]
	s_mov_b64 s[100:101], 0x180080
	v_lshl_add_u64 v[252:253], v[130:131], 0, s[100:101]
	v_readfirstlane_b32 s100, v144
	v_readfirstlane_b32 s101, v145
	v_add_u32_e32 v254, 0x20000, v172
	v_add_u32_e32 v255, 0x20000, v173
	s_nop 3
	ds_read_b128 v[176:179], v172 offset:0
	ds_read_b128 v[180:183], v172 offset:2048
	ds_read_b128 v[184:187], v172 offset:4096
	ds_read_b128 v[188:191], v172 offset:6144
	ds_read_b128 v[208:211], v174 offset:0
	ds_read_b128 v[212:215], v174 offset:2048
	ds_read_b128 v[216:219], v174 offset:4096
	ds_read_b128 v[220:223], v174 offset:6144
	s_add_u32 m0, s100, 0x8000
	s_nop 0
	global_load_lds_dwordx4 v[240:241], off
	v_lshl_add_u64 v[240:241], v[240:241], 0, s[34:35]
	s_add_u32 m0, s100, 0xa000
	s_nop 0
	global_load_lds_dwordx4 v[242:243], off
	v_lshl_add_u64 v[242:243], v[242:243], 0, s[34:35]
	s_add_u32 m0, s100, 0xc000
	s_nop 0
	global_load_lds_dwordx4 v[244:245], off
	v_lshl_add_u64 v[244:245], v[244:245], 0, s[34:35]
	s_add_u32 m0, s100, 0xe000
	s_nop 0
	global_load_lds_dwordx4 v[246:247], off
	v_lshl_add_u64 v[246:247], v[246:247], 0, s[34:35]
	s_add_u32 m0, s101, 0x8000
	s_nop 0
	global_load_lds_dwordx4 v[138:139], off
	v_lshl_add_u64 v[138:139], v[138:139], 0, s[34:35]
	s_add_u32 m0, s101, 0xa000
	s_nop 0
	global_load_lds_dwordx4 v[140:141], off
	v_lshl_add_u64 v[140:141], v[140:141], 0, s[34:35]
	s_add_u32 m0, s101, 0xc000
	s_nop 0
	global_load_lds_dwordx4 v[250:251], off
	v_lshl_add_u64 v[250:251], v[250:251], 0, s[34:35]
	s_add_u32 m0, s101, 0xe000
	s_nop 0
	global_load_lds_dwordx4 v[252:253], off
	v_lshl_add_u64 v[252:253], v[252:253], 0, s[34:35]
	s_waitcnt lgkmcnt(0)
	v_mfma_f32_16x16x32_bf16 v[124:127], v[208:211], v[176:179], v[124:127]
	ds_read_b128 v[224:227], v174 offset:8192
	v_mfma_f32_16x16x32_bf16 v[120:123], v[212:215], v[176:179], v[120:123]
	ds_read_b128 v[228:231], v174 offset:10240
	v_mfma_f32_16x16x32_bf16 v[116:119], v[216:219], v[176:179], v[116:119]
	ds_read_b128 v[232:235], v174 offset:12288
	v_mfma_f32_16x16x32_bf16 v[112:115], v[220:223], v[176:179], v[112:115]
	ds_read_b128 v[236:239], v174 offset:14336
	v_mfma_f32_16x16x32_bf16 v[92:95], v[208:211], v[180:183], v[92:95]
	s_add_u32 m0, s100, 0x20000
	v_mfma_f32_16x16x32_bf16 v[88:91], v[212:215], v[180:183], v[88:91]
	global_load_lds_dwordx4 v[240:241], off
	v_lshl_add_u64 v[240:241], v[240:241], 0, s[34:35]
	v_mfma_f32_16x16x32_bf16 v[84:87], v[216:219], v[180:183], v[84:87]
	s_add_u32 m0, s100, 0x22000
	v_mfma_f32_16x16x32_bf16 v[80:83], v[220:223], v[180:183], v[80:83]
	global_load_lds_dwordx4 v[242:243], off
	v_lshl_add_u64 v[242:243], v[242:243], 0, s[34:35]
	v_mfma_f32_16x16x32_bf16 v[60:63], v[208:211], v[184:187], v[60:63]
	s_add_u32 m0, s100, 0x24000
	v_mfma_f32_16x16x32_bf16 v[56:59], v[212:215], v[184:187], v[56:59]
	global_load_lds_dwordx4 v[244:245], off
	v_lshl_add_u64 v[244:245], v[244:245], 0, s[34:35]
	v_mfma_f32_16x16x32_bf16 v[52:55], v[216:219], v[184:187], v[52:55]
	s_add_u32 m0, s100, 0x26000
	v_mfma_f32_16x16x32_bf16 v[48:51], v[220:223], v[184:187], v[48:51]
	global_load_lds_dwordx4 v[246:247], off
	v_lshl_add_u64 v[246:247], v[246:247], 0, s[34:35]
	v_mfma_f32_16x16x32_bf16 v[28:31], v[208:211], v[188:191], v[28:31]
	v_mfma_f32_16x16x32_bf16 v[24:27], v[212:215], v[188:191], v[24:27]
	v_mfma_f32_16x16x32_bf16 v[20:23], v[216:219], v[188:191], v[20:23]
	v_mfma_f32_16x16x32_bf16 v[16:19], v[220:223], v[188:191], v[16:19]
	s_waitcnt lgkmcnt(0)
	v_mfma_f32_16x16x32_bf16 v[108:111], v[224:227], v[176:179], v[108:111]
	ds_read_b128 v[192:195], v173 offset:0
	v_mfma_f32_16x16x32_bf16 v[104:107], v[228:231], v[176:179], v[104:107]
	ds_read_b128 v[196:199], v173 offset:2048
	v_mfma_f32_16x16x32_bf16 v[100:103], v[232:235], v[176:179], v[100:103]
	ds_read_b128 v[200:203], v173 offset:4096
	v_mfma_f32_16x16x32_bf16 v[96:99], v[236:239], v[176:179], v[96:99]
	ds_read_b128 v[204:207], v173 offset:6144
	v_mfma_f32_16x16x32_bf16 v[76:79], v[224:227], v[180:183], v[76:79]
	ds_read_b128 v[208:211], v175 offset:0
	v_mfma_f32_16x16x32_bf16 v[72:75], v[228:231], v[180:183], v[72:75]
	ds_read_b128 v[212:215], v175 offset:2048
	v_mfma_f32_16x16x32_bf16 v[68:71], v[232:235], v[180:183], v[68:71]
	ds_read_b128 v[216:219], v175 offset:4096
	v_mfma_f32_16x16x32_bf16 v[64:67], v[236:239], v[180:183], v[64:67]
	ds_read_b128 v[220:223], v175 offset:6144
	v_mfma_f32_16x16x32_bf16 v[44:47], v[224:227], v[184:187], v[44:47]
	v_mfma_f32_16x16x32_bf16 v[40:43], v[228:231], v[184:187], v[40:43]
	v_mfma_f32_16x16x32_bf16 v[36:39], v[232:235], v[184:187], v[36:39]
	v_mfma_f32_16x16x32_bf16 v[32:35], v[236:239], v[184:187], v[32:35]
	v_mfma_f32_16x16x32_bf16 v[12:15], v[224:227], v[188:191], v[12:15]
	v_mfma_f32_16x16x32_bf16 v[8:11], v[228:231], v[188:191], v[8:11]
	v_mfma_f32_16x16x32_bf16 v[4:7], v[232:235], v[188:191], v[4:7]
	v_mfma_f32_16x16x32_bf16 v[0:3], v[236:239], v[188:191], v[0:3]
	s_waitcnt lgkmcnt(0)
	v_mfma_f32_16x16x32_bf16 v[124:127], v[208:211], v[192:195], v[124:127]
	ds_read_b128 v[224:227], v175 offset:8192
	v_mfma_f32_16x16x32_bf16 v[120:123], v[212:215], v[192:195], v[120:123]
	ds_read_b128 v[228:231], v175 offset:10240
	v_mfma_f32_16x16x32_bf16 v[116:119], v[216:219], v[192:195], v[116:119]
	ds_read_b128 v[232:235], v175 offset:12288
	v_mfma_f32_16x16x32_bf16 v[112:115], v[220:223], v[192:195], v[112:115]
	ds_read_b128 v[236:239], v175 offset:14336
	v_mfma_f32_16x16x32_bf16 v[92:95], v[208:211], v[196:199], v[92:95]
	v_mfma_f32_16x16x32_bf16 v[88:91], v[212:215], v[196:199], v[88:91]
	v_mfma_f32_16x16x32_bf16 v[84:87], v[216:219], v[196:199], v[84:87]
	v_mfma_f32_16x16x32_bf16 v[80:83], v[220:223], v[196:199], v[80:83]
	v_mfma_f32_16x16x32_bf16 v[60:63], v[208:211], v[200:203], v[60:63]
	v_mfma_f32_16x16x32_bf16 v[56:59], v[212:215], v[200:203], v[56:59]
	v_mfma_f32_16x16x32_bf16 v[52:55], v[216:219], v[200:203], v[52:55]
	v_mfma_f32_16x16x32_bf16 v[48:51], v[220:223], v[200:203], v[48:51]
	v_mfma_f32_16x16x32_bf16 v[28:31], v[208:211], v[204:207], v[28:31]
	v_mfma_f32_16x16x32_bf16 v[24:27], v[212:215], v[204:207], v[24:27]
	v_mfma_f32_16x16x32_bf16 v[20:23], v[216:219], v[204:207], v[20:23]
	v_mfma_f32_16x16x32_bf16 v[16:19], v[220:223], v[204:207], v[16:19]
	s_waitcnt lgkmcnt(0)
	s_waitcnt vmcnt(4)
	s_barrier
	s_mov_b32 s44, 10

	.amdhsa_kernel _Z14fwd_megakernel6Params
		.amdhsa_group_segment_fixed_size 32768
		.amdhsa_private_segment_fixed_size 0
		.amdhsa_kernarg_size 616
		.amdhsa_user_sgpr_count 2
		.amdhsa_user_sgpr_dispatch_ptr 0
		.amdhsa_user_sgpr_queue_ptr 0
		.amdhsa_user_sgpr_kernarg_segment_ptr 1
		.amdhsa_user_sgpr_dispatch_id 0
		.amdhsa_user_sgpr_kernarg_preload_length 0
		.amdhsa_user_sgpr_kernarg_preload_offset 0
		.amdhsa_user_sgpr_private_segment_size 0
		.amdhsa_uses_dynamic_stack 0
		.amdhsa_enable_private_segment 0
		.amdhsa_system_sgpr_workgroup_id_x 1
		.amdhsa_system_sgpr_workgroup_id_y 0
		.amdhsa_system_sgpr_workgroup_id_z 0
		.amdhsa_system_sgpr_workgroup_info 0
		.amdhsa_system_vgpr_workitem_id 2
		.amdhsa_next_free_vgpr 256
		.amdhsa_next_free_sgpr 102
		.amdhsa_accum_offset 256
		.amdhsa_reserve_vcc 1
		.amdhsa_float_round_mode_32 0
		.amdhsa_float_round_mode_16_64 0
		.amdhsa_float_denorm_mode_32 3
		.amdhsa_float_denorm_mode_16_64 3
		.amdhsa_dx10_clamp 1
		.amdhsa_ieee_mode 1
		.amdhsa_fp16_overflow 0
		.amdhsa_tg_split 0
		.amdhsa_exception_fp_ieee_invalid_op 0
		.amdhsa_exception_fp_denorm_src 0
		.amdhsa_exception_fp_ieee_div_zero 0
		.amdhsa_exception_fp_ieee_overflow 0
		.amdhsa_exception_fp_ieee_underflow 0
		.amdhsa_exception_fp_ieee_inexact 0
		.amdhsa_exception_int_div_zero 0
	.end_amdhsa_kernel

amdhsa.kernels:
  - .agpr_count:     0
    .args:
      - .offset:         0
        .size:           360
        .value_kind:     by_value
      - .offset:         360
        .size:           4
        .value_kind:     hidden_block_count_x
      - .offset:         364
        .size:           4
        .value_kind:     hidden_block_count_y
      - .offset:         368
        .size:           4
        .value_kind:     hidden_block_count_z
      - .offset:         372
        .size:           2
        .value_kind:     hidden_group_size_x
      - .offset:         374
        .size:           2
        .value_kind:     hidden_group_size_y
      - .offset:         376
        .size:           2
        .value_kind:     hidden_group_size_z
      - .offset:         378
        .size:           2
        .value_kind:     hidden_remainder_x
      - .offset:         380
        .size:           2
        .value_kind:     hidden_remainder_y
      - .offset:         382
        .size:           2
        .value_kind:     hidden_remainder_z
      - .offset:         400
        .size:           8
        .value_kind:     hidden_global_offset_x
      - .offset:         408
        .size:           8
        .value_kind:     hidden_global_offset_y
      - .offset:         416
        .size:           8
        .value_kind:     hidden_global_offset_z
      - .offset:         424
        .size:           2
        .value_kind:     hidden_grid_dims
      - .offset:         448
        .size:           8
        .value_kind:     hidden_multigrid_sync_arg
      - .offset:         480
        .size:           4
        .value_kind:     hidden_dynamic_lds_size
    .group_segment_fixed_size: 32768
    .kernarg_segment_align: 8
    .kernarg_segment_size: 616
    .language:       OpenCL C
    .language_version:
      - 2
      - 0
    .max_flat_workgroup_size: 512
    .name:           _Z14fwd_megakernel6Params
    .private_segment_fixed_size: 0
    .sgpr_count:     108
    .sgpr_spill_count: 95
    .symbol:         _Z14fwd_megakernel6Params.kd
    .uniform_work_group_size: 1
    .uses_dynamic_stack: false
    .vgpr_count:     256
    .vgpr_spill_count: 0
    .wavefront_size: 64
